# 7 GEMM mainloops: LDS-DMA (global_load_lds_dwordx4) staging into XOR-swizzled image, 16x16x32 bf16 MFMA, one barrier per K=64 stage
# speedup vs baseline: 1.0825x; 1.0573x over previous
; DI int otid() { int t = threadIdx.x; asm volatile("" : "+v"(t)); return t; }
; template <bool SWAP, bool HALF>
; DI void gemm_mainloop(const GemmDesc& d, int m0, int n0, bf16_t* smem, f32x16 (&acc)[2][2], int dry) {
;   const int t = otid(), lane = t & 63, w = t >> 6, wm = w >> 1, wn = w & 1, r = lane & 31, hh = lane >> 5;
;   const int lrow = t >> 3, lkc = t & 7;
;   const bf16_t* ap[4]; const bf16_t* bp[4];
; #pragma unroll
;   for (int i = 0; i < 4; ++i) {
;     int am = m0 + lrow + 32 * i; am = am < M ? am : M - 1;
;     ap[i] = d.A + (size_t)am * d.lda + lkc * 8 + (d.a_grp ? (n0 / d.a_grp) * d.a_grp : 0);
;     bp[i] = d.Bt + (size_t)(n0 + lrow + 32 * i) * d.ldb + lkc * 8;
;   }
; #pragma unroll
;   for (int a = 0; a < 2; ++a)
; #pragma unroll
;     for (int b = 0; b < 2; ++b)
; #pragma unroll
;       for (int i = 0; i < 16; ++i) acc[a][b][i] = 0.f;
;   u32x4 ra0[4], rb0[4], ra1[4], rb1[4];
;   const int nk = d.K >> 6;
;   const int lds_w = lrow * LST + lkc * 8;
;     ...
;   gl(ra0, rb0, 0);
;   gl(ra1, rb1, 1);
;   lw(ra0, rb0, 0);
;   gl(ra0, rb0, 2);
;   __syncthreads();
;   ldf(0, 0, 0);
.LBB0_190:
	s_or_b64 exec, exec, s[4:5]
	s_lshl_b32 s33, s7, 7
	s_and_b32 s4, s7, -8
	s_waitcnt vmcnt(0)
	v_ashrrev_i32_e32 v187, 7, v150
	v_bfe_u32 v188, v150, 6, 1
	v_and_b32_e32 v170, 31, v150
	v_bfe_u32 v189, v150, 5, 1
	s_cmp_lg_u32 s4, 16
	s_mov_b64 s[4:5], -1
	s_cbranch_scc0 .LBB0_260
	v_mov_b32_e32 v32, v172
	v_readlane_b32 s76, v228, 60
	v_ashrrev_i32_e32 v10, 3, v32
	v_lshlrev_b32_e32 v0, 3, v32
	v_and_b32_e32 v33, 56, v0
	v_add_u32_e32 v2, s33, v10
	v_lshlrev_b32_e32 v144, 1, v33
	v_readlane_b32 s90, v223, 10
	v_readlane_b32 s91, v223, 11
	v_ashrrev_i32_e32 v3, 31, v2
	v_add_u32_e32 v11, s25, v10
	v_lshl_add_u64 v[4:5], s[90:91], 0, v[144:145]
	v_lshlrev_b64 v[2:3], 11, v[2:3]
	v_lshl_add_u64 v[154:155], v[4:5], 0, v[2:3]
	v_min_i32_e32 v2, 0x801f, v11
	v_ashrrev_i32_e32 v3, 31, v2
	v_lshl_add_u64 v[0:1], s[56:57], 0, v[144:145]
	v_lshlrev_b64 v[2:3], 11, v[2:3]
	v_lshl_add_u64 v[8:9], v[0:1], 0, v[2:3]
	v_min_i32_e32 v2, 0x7fff, v11
	v_ashrrev_i32_e32 v3, 31, v2
	v_min_i32_e32 v6, 0x803f, v11
	v_lshlrev_b64 v[2:3], 11, v[2:3]
	v_ashrrev_i32_e32 v7, 31, v6
	v_lshl_add_u64 v[16:17], v[0:1], 0, v[2:3]
	v_min_i32_e32 v2, 0x7fdf, v11
	v_lshlrev_b64 v[6:7], 11, v[6:7]
	v_ashrrev_i32_e32 v3, 31, v2
	v_lshl_add_u64 v[152:153], v[0:1], 0, v[6:7]
	v_lshlrev_b64 v[2:3], 11, v[2:3]
	v_lshl_add_u64 v[24:25], v[0:1], 0, v[2:3]
	s_mov_b64 s[4:5], 0x10000
	v_lshl_add_u64 v[156:157], v[8:9], 0, s[4:5]
	v_lshl_add_u64 v[158:159], v[154:155], 0, s[4:5]
	s_mov_b64 s[4:5], 0x20000
	v_lshl_add_u64 v[160:161], v[16:17], 0, s[4:5]
	v_lshl_add_u64 v[162:163], v[154:155], 0, s[4:5]
	s_mov_b64 s[4:5], 0x30000
	v_lshl_add_u64 v[164:165], v[24:25], 0, s[4:5]
	v_lshl_add_u64 v[166:167], v[154:155], 0, s[4:5]
	s_movk_i32 s4, 0x48
	v_and_b32_e32 v34, 31, v32
	v_mul_lo_u32 v35, v10, s4
	v_readlane_b32 s77, v228, 61
	v_readlane_b32 s78, v228, 62
	v_readlane_b32 s79, v228, 63
	v_readlane_b32 s80, v223, 0
	v_readlane_b32 s81, v223, 1
	v_readlane_b32 s82, v223, 2
	v_readlane_b32 s83, v223, 3
	v_readlane_b32 s84, v223, 4
	v_readlane_b32 s85, v223, 5
	v_readlane_b32 s86, v223, 6
	v_readlane_b32 s87, v223, 7
	v_readlane_b32 s88, v223, 8
	v_readlane_b32 s89, v223, 9
	s_mov_b32 s4, 0x10000
	v_add_co_u32_e32 v8, vcc, s4, v8
	s_nop 1
	v_addc_co_u32_e32 v9, vcc, 0, v9, vcc
	s_waitcnt vmcnt(19)
	v_add_co_u32_e32 v12, vcc, s4, v154
	s_nop 1
	v_addc_co_u32_e32 v13, vcc, 0, v155, vcc
	s_mov_b32 s4, 0x20000
	v_add_co_u32_e32 v16, vcc, s4, v16
	s_nop 1
	v_addc_co_u32_e32 v17, vcc, 0, v17, vcc
	v_add_co_u32_e32 v20, vcc, s4, v154
	s_nop 1
	v_addc_co_u32_e32 v21, vcc, 0, v155, vcc
	s_mov_b32 s4, 0x30000
	v_add_co_u32_e32 v24, vcc, s4, v24
	s_nop 1
	v_addc_co_u32_e32 v25, vcc, 0, v25, vcc
	v_add_co_u32_e32 v28, vcc, s4, v154
	s_nop 1
	v_addc_co_u32_e32 v29, vcc, 0, v155, vcc
	s_nop 0
	v_add_lshl_u32 v144, v35, v33, 1
	s_waitcnt vmcnt(15)
	s_waitcnt vmcnt(14)
	s_waitcnt vmcnt(13)
	s_waitcnt vmcnt(12)
	s_waitcnt vmcnt(11)
	s_waitcnt vmcnt(10)
	s_waitcnt vmcnt(9)
	s_waitcnt vmcnt(8)
	v_lshrrev_b32_e32 v0, 1, v32
	v_and_or_b32 v1, v0, s72, v34
	v_and_b32_e32 v0, 16, v0
	s_movk_i32 s4, 0x90
	v_mad_u64_u32 v[168:169], s[4:5], v1, s4, v[0:1]
	v_and_b32_e32 v1, 0x5f, v32
	v_mul_u32_u24_e32 v1, 0x48, v1
	v_lshl_add_u32 v169, v1, 1, v0
	v_bfe_u32 v204, v172, 4, 3
	v_lshlrev_b32_e32 v204, 4, v204
	v_xor_b32_e32 v152, v152, v204
	v_xor_b32_e32 v154, v154, v204
	v_xor_b32_e32 v156, v156, v204
	v_xor_b32_e32 v158, v158, v204
	v_xor_b32_e32 v160, v160, v204
	v_xor_b32_e32 v162, v162, v204
	v_xor_b32_e32 v164, v164, v204
	v_xor_b32_e32 v166, v166, v204
	v_lshrrev_b32_e32 v205, 6, v172
	s_nop 1
	v_readfirstlane_b32 s101, v205
	s_lshl_b32 s101, s101, 10
	s_add_u32 m0, s101, 0x0
	s_nop 0
	global_load_lds_dwordx4 v[152:153], off
	s_add_u32 m0, s101, 0x4000
	s_nop 0
	global_load_lds_dwordx4 v[154:155], off
	s_add_u32 m0, s101, 0x1000
	s_nop 0
	global_load_lds_dwordx4 v[156:157], off
	s_add_u32 m0, s101, 0x5000
	s_nop 0
	global_load_lds_dwordx4 v[158:159], off
	s_add_u32 m0, s101, 0x2000
	s_nop 0
	global_load_lds_dwordx4 v[160:161], off
	s_add_u32 m0, s101, 0x6000
	s_nop 0
	global_load_lds_dwordx4 v[162:163], off
	s_add_u32 m0, s101, 0x3000
	s_nop 0
	global_load_lds_dwordx4 v[164:165], off
	s_add_u32 m0, s101, 0x7000
	s_nop 0
	global_load_lds_dwordx4 v[166:167], off
	v_and_b32_e32 v204, 15, v172
	v_bfe_u32 v205, v172, 4, 2
	v_lshrrev_b32_e32 v206, 1, v204
	v_xor_b32_e32 v205, v205, v206
	v_lshlrev_b32_e32 v205, 4, v205
	v_lshl_or_b32 v204, v204, 7, v205
	v_lshrrev_b32_e32 v206, 7, v172
	v_lshl_add_u32 v168, v206, 13, v204
	v_bfe_u32 v206, v172, 6, 1
	v_lshl_add_u32 v169, v206, 13, v204
	v_add_u32_e32 v169, 0x4000, v169
	v_xor_b32_e32 v220, 64, v168
	v_xor_b32_e32 v221, 64, v169
	s_waitcnt vmcnt(0)
	s_waitcnt lgkmcnt(0)
	s_barrier
	v_mov_b32_e32 v0, 0
	v_add_u32_e32 v190, 0x9000, v144
	s_mov_b32 s4, -2
	v_mov_b32_e32 v1, v0
	v_mov_b32_e32 v2, v0
	v_mov_b32_e32 v3, v0
	v_mov_b32_e32 v4, v0
	v_mov_b32_e32 v5, v0
	v_mov_b32_e32 v6, v0
	v_mov_b32_e32 v7, v0
	v_mov_b32_e32 v8, v0
	v_mov_b32_e32 v9, v0
	v_mov_b32_e32 v10, v0
	v_mov_b32_e32 v11, v0
	v_mov_b32_e32 v12, v0
	v_mov_b32_e32 v13, v0
	v_mov_b32_e32 v14, v0
	v_mov_b32_e32 v15, v0
	v_mov_b32_e32 v16, v0
	v_mov_b32_e32 v17, v0
	v_mov_b32_e32 v18, v0
	v_mov_b32_e32 v19, v0
	v_mov_b32_e32 v20, v0
	v_mov_b32_e32 v21, v0
	v_mov_b32_e32 v22, v0
	v_mov_b32_e32 v23, v0
	v_mov_b32_e32 v24, v0
	v_mov_b32_e32 v25, v0
	v_mov_b32_e32 v26, v0
	v_mov_b32_e32 v27, v0
	v_mov_b32_e32 v28, v0
	v_mov_b32_e32 v29, v0
	v_mov_b32_e32 v30, v0
	v_mov_b32_e32 v31, v0
	v_mov_b32_e32 v32, v0
	v_mov_b32_e32 v33, v0
	v_mov_b32_e32 v34, v0
	v_mov_b32_e32 v35, v0
	v_mov_b32_e32 v36, v0
	v_mov_b32_e32 v37, v0
	v_mov_b32_e32 v38, v0
	v_mov_b32_e32 v39, v0
	v_mov_b32_e32 v40, v0
	v_mov_b32_e32 v41, v0
	v_mov_b32_e32 v42, v0
	v_mov_b32_e32 v43, v0
	v_mov_b32_e32 v44, v0
	v_mov_b32_e32 v45, v0
	v_mov_b32_e32 v46, v0
	v_mov_b32_e32 v47, v0
	v_mov_b32_e32 v48, v0
	v_mov_b32_e32 v49, v0
	v_mov_b32_e32 v50, v0
	v_mov_b32_e32 v51, v0
	v_mov_b32_e32 v52, v0
	v_mov_b32_e32 v53, v0
	v_mov_b32_e32 v54, v0
	v_mov_b32_e32 v55, v0
	v_mov_b32_e32 v56, v0
	v_mov_b32_e32 v57, v0
	v_mov_b32_e32 v58, v0
	v_mov_b32_e32 v59, v0
	v_mov_b32_e32 v60, v0
	v_mov_b32_e32 v61, v0
	v_mov_b32_e32 v62, v0
	v_mov_b32_e32 v63, v0
; #define MFMA32(a, b, c) __builtin_amdgcn_mfma_f32_32x32x16_bf16((a), (b), (c), 0, 0, 0)
; #define SB_ __builtin_amdgcn_sched_barrier(0)
; template <bool SWAP, bool HALF>
; DI void gemm_mainloop(const GemmDesc& d, int m0, int n0, bf16_t* smem, f32x16 (&acc)[2][2], int dry) {
;     ...
;   auto lw = [&](const u32x4 (&ra)[4], const u32x4 (&rb)[4], int buf) {
;     bf16_t* An = smem + buf * 2 * TILE_EL + lds_w; bf16_t* Bn = An + TILE_EL;
; #pragma unroll
;     for (int i = 0; i < 4; ++i) {
;       *(u32x4*)(An + 32 * i * LST) = ra[i];
;       *(u32x4*)(Bn + 32 * i * LST) = rb[i];
;     }
;   };
;   bf16x8 fa[2][2], fb[2][2];
;   auto ldf = [&](int buf, int kk, int set) {
;     const bf16_t* Ab = smem + buf * 2 * TILE_EL + ((HALF ? 0 : wm * 64) + r) * LST + 8 * hh + kk * 16;
;     const bf16_t* Bb = smem + buf * 2 * TILE_EL + TILE_EL + ((HALF ? w * 32 : wn * 64) + r) * LST + 8 * hh + kk * 16;
; #pragma unroll
;     for (int i = 0; i < 2; ++i) { fa[set][i] = *(const bf16x8*)(Ab + i * 32 * LST); if (!HALF || i == 0) fb[set][i] = *(const bf16x8*)(Bb + i * 32 * LST); }
;   };
;   auto mma = [&](int set) {
; #pragma unroll
;     for (int a = 0; a < 2; ++a)
; #pragma unroll
;       for (int b = 0; b < (HALF ? 1 : 2); ++b) {
;         if (SWAP) acc[a][b] = MFMA32(fb[set][b], fa[set][a], acc[a][b]);
;         else      acc[a][b] = MFMA32(fa[set][a], fb[set][b], acc[a][b]);
;       }
;   };
;     ...
;   auto stage = [&](int cur, u32x4 (&ran)[4], u32x4 (&rbn)[4], int ks) {
;     ldf(cur, 1, 1); SB_;
;     mma(0); SB_;
;     ldf(cur, 2, 0); SB_;
;     lw(ran, rbn, cur ^ 1);
;     gl(ran, rbn, (ks + 3 < nk) ? ks + 3 : nk - 1);
;     SB_;
;     mma(1); SB_;
;     __syncthreads();
;     ldf(cur, 3, 1); SB_;
;     mma(0); SB_;
;     ldf(cur ^ 1, 0, 0);
;     SB_;
;     mma(1); SB_;
;     __syncthreads();
;   };
.LBB0_192:
	ds_read_b128 v[64:67], v168 offset:0
	ds_read_b128 v[68:71], v168 offset:2048
	ds_read_b128 v[72:75], v168 offset:4096
	ds_read_b128 v[76:79], v168 offset:6144
	ds_read_b128 v[80:83], v169 offset:0
	ds_read_b128 v[84:87], v169 offset:2048
	ds_read_b128 v[88:91], v169 offset:4096
	ds_read_b128 v[92:95], v169 offset:6144
	ds_read_b128 v[96:99], v220 offset:0
	ds_read_b128 v[100:103], v220 offset:2048
	ds_read_b128 v[104:107], v220 offset:4096
	ds_read_b128 v[108:111], v220 offset:6144
	ds_read_b128 v[112:115], v221 offset:0
	ds_read_b128 v[116:119], v221 offset:2048
	ds_read_b128 v[120:123], v221 offset:4096
	ds_read_b128 v[124:127], v221 offset:6144
	s_add_i32 s4, s4, 2
	s_add_i32 s5, s4, 1
	s_min_u32 s5, s5, 15
	s_lshl_b32 s18, s5, 7
	s_add_u32 m0, s101, 0x8000
	v_lshl_add_u64 v[128:129], v[152:153], 0, s[18:19]
	global_load_lds_dwordx4 v[128:129], off
	s_add_u32 m0, s101, 0xc000
	v_lshl_add_u64 v[128:129], v[154:155], 0, s[18:19]
	global_load_lds_dwordx4 v[128:129], off
	s_add_u32 m0, s101, 0x9000
	v_lshl_add_u64 v[128:129], v[156:157], 0, s[18:19]
	global_load_lds_dwordx4 v[128:129], off
	s_add_u32 m0, s101, 0xd000
	v_lshl_add_u64 v[128:129], v[158:159], 0, s[18:19]
	global_load_lds_dwordx4 v[128:129], off
	s_add_u32 m0, s101, 0xa000
	v_lshl_add_u64 v[128:129], v[160:161], 0, s[18:19]
	global_load_lds_dwordx4 v[128:129], off
	s_add_u32 m0, s101, 0xe000
	v_lshl_add_u64 v[128:129], v[162:163], 0, s[18:19]
	global_load_lds_dwordx4 v[128:129], off
	s_add_u32 m0, s101, 0xb000
	v_lshl_add_u64 v[128:129], v[164:165], 0, s[18:19]
	global_load_lds_dwordx4 v[128:129], off
	s_add_u32 m0, s101, 0xf000
	v_lshl_add_u64 v[128:129], v[166:167], 0, s[18:19]
	global_load_lds_dwordx4 v[128:129], off
	s_waitcnt lgkmcnt(8)
	v_mfma_f32_16x16x32_bf16 v[0:3], v[80:83], v[64:67], v[0:3]
	v_mfma_f32_16x16x32_bf16 v[4:7], v[84:87], v[64:67], v[4:7]
	v_mfma_f32_16x16x32_bf16 v[8:11], v[88:91], v[64:67], v[8:11]
	v_mfma_f32_16x16x32_bf16 v[12:15], v[92:95], v[64:67], v[12:15]
	v_mfma_f32_16x16x32_bf16 v[16:19], v[80:83], v[68:71], v[16:19]
	v_mfma_f32_16x16x32_bf16 v[20:23], v[84:87], v[68:71], v[20:23]
	v_mfma_f32_16x16x32_bf16 v[24:27], v[88:91], v[68:71], v[24:27]
	v_mfma_f32_16x16x32_bf16 v[28:31], v[92:95], v[68:71], v[28:31]
	v_mfma_f32_16x16x32_bf16 v[32:35], v[80:83], v[72:75], v[32:35]
	v_mfma_f32_16x16x32_bf16 v[36:39], v[84:87], v[72:75], v[36:39]
	v_mfma_f32_16x16x32_bf16 v[40:43], v[88:91], v[72:75], v[40:43]
	v_mfma_f32_16x16x32_bf16 v[44:47], v[92:95], v[72:75], v[44:47]
	v_mfma_f32_16x16x32_bf16 v[48:51], v[80:83], v[76:79], v[48:51]
	v_mfma_f32_16x16x32_bf16 v[52:55], v[84:87], v[76:79], v[52:55]
	v_mfma_f32_16x16x32_bf16 v[56:59], v[88:91], v[76:79], v[56:59]
	v_mfma_f32_16x16x32_bf16 v[60:63], v[92:95], v[76:79], v[60:63]
	s_waitcnt lgkmcnt(0)
	v_mfma_f32_16x16x32_bf16 v[0:3], v[112:115], v[96:99], v[0:3]
	v_mfma_f32_16x16x32_bf16 v[4:7], v[116:119], v[96:99], v[4:7]
	v_mfma_f32_16x16x32_bf16 v[8:11], v[120:123], v[96:99], v[8:11]
	v_mfma_f32_16x16x32_bf16 v[12:15], v[124:127], v[96:99], v[12:15]
	v_mfma_f32_16x16x32_bf16 v[16:19], v[112:115], v[100:103], v[16:19]
	v_mfma_f32_16x16x32_bf16 v[20:23], v[116:119], v[100:103], v[20:23]
	v_mfma_f32_16x16x32_bf16 v[24:27], v[120:123], v[100:103], v[24:27]
	v_mfma_f32_16x16x32_bf16 v[28:31], v[124:127], v[100:103], v[28:31]
	v_mfma_f32_16x16x32_bf16 v[32:35], v[112:115], v[104:107], v[32:35]
	v_mfma_f32_16x16x32_bf16 v[36:39], v[116:119], v[104:107], v[36:39]
	v_mfma_f32_16x16x32_bf16 v[40:43], v[120:123], v[104:107], v[40:43]
	v_mfma_f32_16x16x32_bf16 v[44:47], v[124:127], v[104:107], v[44:47]
	v_mfma_f32_16x16x32_bf16 v[48:51], v[112:115], v[108:111], v[48:51]
	v_mfma_f32_16x16x32_bf16 v[52:55], v[116:119], v[108:111], v[52:55]
	v_mfma_f32_16x16x32_bf16 v[56:59], v[120:123], v[108:111], v[56:59]
	v_mfma_f32_16x16x32_bf16 v[60:63], v[124:127], v[108:111], v[60:63]
	s_waitcnt vmcnt(0)
	s_barrier
	ds_read_b128 v[64:67], v168 offset:32768
	ds_read_b128 v[68:71], v168 offset:34816
	ds_read_b128 v[72:75], v168 offset:36864
	ds_read_b128 v[76:79], v168 offset:38912
	ds_read_b128 v[80:83], v169 offset:32768
	ds_read_b128 v[84:87], v169 offset:34816
	ds_read_b128 v[88:91], v169 offset:36864
	ds_read_b128 v[92:95], v169 offset:38912
	ds_read_b128 v[96:99], v220 offset:32768
	ds_read_b128 v[100:103], v220 offset:34816
	ds_read_b128 v[104:107], v220 offset:36864
	ds_read_b128 v[108:111], v220 offset:38912
	ds_read_b128 v[112:115], v221 offset:32768
	ds_read_b128 v[116:119], v221 offset:34816
	ds_read_b128 v[120:123], v221 offset:36864
	ds_read_b128 v[124:127], v221 offset:38912
	s_add_i32 s5, s4, 2
	s_min_u32 s5, s5, 15
	s_lshl_b32 s18, s5, 7
	s_add_u32 m0, s101, 0x0
	v_lshl_add_u64 v[128:129], v[152:153], 0, s[18:19]
	global_load_lds_dwordx4 v[128:129], off
	s_add_u32 m0, s101, 0x4000
	v_lshl_add_u64 v[128:129], v[154:155], 0, s[18:19]
	global_load_lds_dwordx4 v[128:129], off
	s_add_u32 m0, s101, 0x1000
	v_lshl_add_u64 v[128:129], v[156:157], 0, s[18:19]
	global_load_lds_dwordx4 v[128:129], off
	s_add_u32 m0, s101, 0x5000
	v_lshl_add_u64 v[128:129], v[158:159], 0, s[18:19]
	global_load_lds_dwordx4 v[128:129], off
	s_add_u32 m0, s101, 0x2000
	v_lshl_add_u64 v[128:129], v[160:161], 0, s[18:19]
	global_load_lds_dwordx4 v[128:129], off
	s_add_u32 m0, s101, 0x6000
	v_lshl_add_u64 v[128:129], v[162:163], 0, s[18:19]
	global_load_lds_dwordx4 v[128:129], off
	s_add_u32 m0, s101, 0x3000
	v_lshl_add_u64 v[128:129], v[164:165], 0, s[18:19]
	global_load_lds_dwordx4 v[128:129], off
	s_add_u32 m0, s101, 0x7000
	v_lshl_add_u64 v[128:129], v[166:167], 0, s[18:19]
	global_load_lds_dwordx4 v[128:129], off
	s_waitcnt lgkmcnt(8)
; DI float ssq_f(u64 v) { return (float)v * (1.f / 1048576.f); }
; #define SB_ __builtin_amdgcn_sched_barrier(0)
; template <bool SWAP, bool HALF>
; DI void gemm_mainloop(const GemmDesc& d, int m0, int n0, bf16_t* smem, f32x16 (&acc)[2][2], int dry) {
;     ...
;   auto stage = [&](int cur, u32x4 (&ran)[4], u32x4 (&rbn)[4], int ks) {
;     ldf(cur, 1, 1); SB_;
;     mma(0); SB_;
;     ldf(cur, 2, 0); SB_;
;     lw(ran, rbn, cur ^ 1);
;     gl(ran, rbn, (ks + 3 < nk) ? ks + 3 : nk - 1);
;     SB_;
;     mma(1); SB_;
;     __syncthreads();
;     ldf(cur, 3, 1); SB_;
;     mma(0); SB_;
;     ldf(cur ^ 1, 0, 0);
;     SB_;
;     mma(1); SB_;
;     __syncthreads();
;   };
;   gl(ra0, rb0, 0);
;   gl(ra1, rb1, 1);
;   lw(ra0, rb0, 0);
;   gl(ra0, rb0, 2);
;   __syncthreads();
;   ldf(0, 0, 0);
; #pragma unroll 1
;   for (int ks = 0; ks < nk; ks += 2) {
;     stage(0, ra1, rb1, ks);
;     stage(1, ra0, rb0, ks + 1);
;   }
; DI void gemm_tile(const GemmDesc& d, int m0, int n0, bf16_t* smem, int dry) {
;     ...
;   } else if (t < 128) {
;     rs_s[t] = rsqrtf(ssq_f(myss) * d.inv_dim + EPS);
;   }
;   if (half) {
; #pragma unroll
;     for (int a = 0; a < 2; ++a)
; #pragma unroll
;       for (int g = 0; g < 4; ++g) {
;         f32x4 o;
; #pragma unroll
;         for (int j = 0; j < 4; ++j) o[j] = acc[a][0][4 * g + j];
;         *(f32x4*)(Ct + (a * 32 + r) * CS + w * 32 + 8 * g + 4 * hh) = o;
;       }
;   } else {
; #pragma unroll
;     for (int a = 0; a < 2; ++a)
; #pragma unroll
;       for (int b = 0; b < 2; ++b)
; #pragma unroll
;         for (int g = 0; g < 4; ++g) {
;           f32x4 o;
; #pragma unroll
;           for (int j = 0; j < 4; ++j) o[j] = acc[a][b][4 * g + j];
;           *(f32x4*)(Ct + (wm * 64 + a * 32 + r) * CS + wn * 64 + b * 32 + 8 * g + 4 * hh) = o;
;         }
;   }
;   __syncthreads();
	v_mfma_f32_16x16x32_bf16 v[0:3], v[80:83], v[64:67], v[0:3]
	v_mfma_f32_16x16x32_bf16 v[4:7], v[84:87], v[64:67], v[4:7]
	v_mfma_f32_16x16x32_bf16 v[8:11], v[88:91], v[64:67], v[8:11]
	v_mfma_f32_16x16x32_bf16 v[12:15], v[92:95], v[64:67], v[12:15]
	v_mfma_f32_16x16x32_bf16 v[16:19], v[80:83], v[68:71], v[16:19]
	v_mfma_f32_16x16x32_bf16 v[20:23], v[84:87], v[68:71], v[20:23]
	v_mfma_f32_16x16x32_bf16 v[24:27], v[88:91], v[68:71], v[24:27]
	v_mfma_f32_16x16x32_bf16 v[28:31], v[92:95], v[68:71], v[28:31]
	v_mfma_f32_16x16x32_bf16 v[32:35], v[80:83], v[72:75], v[32:35]
	v_mfma_f32_16x16x32_bf16 v[36:39], v[84:87], v[72:75], v[36:39]
	v_mfma_f32_16x16x32_bf16 v[40:43], v[88:91], v[72:75], v[40:43]
	v_mfma_f32_16x16x32_bf16 v[44:47], v[92:95], v[72:75], v[44:47]
	v_mfma_f32_16x16x32_bf16 v[48:51], v[80:83], v[76:79], v[48:51]
	v_mfma_f32_16x16x32_bf16 v[52:55], v[84:87], v[76:79], v[52:55]
	v_mfma_f32_16x16x32_bf16 v[56:59], v[88:91], v[76:79], v[56:59]
	v_mfma_f32_16x16x32_bf16 v[60:63], v[92:95], v[76:79], v[60:63]
	s_waitcnt lgkmcnt(0)
	v_mfma_f32_16x16x32_bf16 v[0:3], v[112:115], v[96:99], v[0:3]
	v_mfma_f32_16x16x32_bf16 v[4:7], v[116:119], v[96:99], v[4:7]
	v_mfma_f32_16x16x32_bf16 v[8:11], v[120:123], v[96:99], v[8:11]
	v_mfma_f32_16x16x32_bf16 v[12:15], v[124:127], v[96:99], v[12:15]
	v_mfma_f32_16x16x32_bf16 v[16:19], v[112:115], v[100:103], v[16:19]
	v_mfma_f32_16x16x32_bf16 v[20:23], v[116:119], v[100:103], v[20:23]
	v_mfma_f32_16x16x32_bf16 v[24:27], v[120:123], v[100:103], v[24:27]
	v_mfma_f32_16x16x32_bf16 v[28:31], v[124:127], v[100:103], v[28:31]
	v_mfma_f32_16x16x32_bf16 v[32:35], v[112:115], v[104:107], v[32:35]
	v_mfma_f32_16x16x32_bf16 v[36:39], v[116:119], v[104:107], v[36:39]
	v_mfma_f32_16x16x32_bf16 v[40:43], v[120:123], v[104:107], v[40:43]
	v_mfma_f32_16x16x32_bf16 v[44:47], v[124:127], v[104:107], v[44:47]
	v_mfma_f32_16x16x32_bf16 v[48:51], v[112:115], v[108:111], v[48:51]
	v_mfma_f32_16x16x32_bf16 v[52:55], v[116:119], v[108:111], v[52:55]
	v_mfma_f32_16x16x32_bf16 v[56:59], v[120:123], v[108:111], v[56:59]
	v_mfma_f32_16x16x32_bf16 v[60:63], v[124:127], v[108:111], v[60:63]
	s_cmp_lt_u32 s4, 14
	s_waitcnt vmcnt(0)
	s_barrier
	s_cbranch_scc1 .LBB0_192
	s_and_saveexec_b64 s[4:5], s[42:43]
	s_cbranch_execz .LBB0_195
	s_mov_b32 s8, 0x800000
	s_waitcnt vmcnt(15)
	v_mul_f32_e32 v64, 0x4b800000, v171
	v_cmp_gt_f32_e32 vcc, s8, v171
	v_lshl_add_u32 v65, v150, 2, v181
	s_nop 0
	v_cndmask_b32_e32 v64, v171, v64, vcc
	v_rsq_f32_e32 v64, v64
	s_nop 0
	v_mul_f32_e32 v66, 0x45800000, v64
	v_cndmask_b32_e32 v64, v64, v66, vcc
	ds_write_b32 v65, v64
.LBB0_195:
	s_or_b64 exec, exec, s[4:5]
	s_waitcnt vmcnt(15)
	v_lshlrev_b32_e32 v64, 4, v189
	v_lshl_or_b32 v65, v187, 6, v170
	v_lshl_or_b32 v64, v188, 8, v64
	v_mad_u64_u32 v[64:65], s[4:5], v65, s22, v[64:65]
	s_cmp_lt_i32 s7, 16
	s_mov_b64 s[4:5], -1
	v_and_b32_e32 v204, 15, v172
	v_lshrrev_b32_e32 v205, 1, v172
	v_and_or_b32 v204, v205, s72, v204
	v_lshlrev_b32_e32 v205, 2, v172
	v_and_b32_e32 v206, 0x30, v172
	v_and_b32_e32 v205, 0x100, v205
	v_or_b32_e32 v205, v205, v206
	v_mad_u32_u24 v64, v204, s22, v205
	ds_write_b128 v64, v[0:3]
	ds_write_b128 v64, v[4:7] offset:64
	ds_write_b128 v64, v[8:11] offset:128
	ds_write_b128 v64, v[12:15] offset:192
	ds_write_b128 v64, v[16:19] offset:8448
	ds_write_b128 v64, v[20:23] offset:8512
	ds_write_b128 v64, v[24:27] offset:8576
	ds_write_b128 v64, v[28:31] offset:8640
	ds_write_b128 v64, v[32:35] offset:16896
	ds_write_b128 v64, v[36:39] offset:16960
	ds_write_b128 v64, v[40:43] offset:17024
	ds_write_b128 v64, v[44:47] offset:17088
	ds_write_b128 v64, v[48:51] offset:25344
	ds_write_b128 v64, v[52:55] offset:25408
	ds_write_b128 v64, v[56:59] offset:25472
	ds_write_b128 v64, v[60:63] offset:25536
	s_waitcnt lgkmcnt(0)
	s_barrier
	s_cbranch_scc0 .LBB0_253
	s_lshl_b32 s16, s6, 13
	s_cmp_gt_i32 s7, 7
	s_cselect_b64 s[8:9], -1, 0
	s_and_b64 s[4:5], s[8:9], exec
	v_readlane_b32 s6, v228, 29
	s_cselect_b32 s4, 0xfffffc00, 0
	s_cselect_b32 s7, s6, 0
	v_readlane_b32 s6, v228, 30
	s_cselect_b32 s5, 0x4020000, 0
	s_cselect_b32 s10, s6, 0
	s_add_i32 s6, s4, s33
	s_add_u32 s17, s68, s5
	s_addc_u32 s39, s69, 0
	s_min_i32 s4, s25, 0x7fc0
	s_addk_i32 s4, 0x7f
	s_mul_hi_i32 s5, s25, 0x7fc01ff1
	s_mul_hi_i32 s4, s4, 0x7fc01ff1
	v_mov_b32_e32 v2, s7
	s_lshr_b32 s7, s5, 31
	s_ashr_i32 s37, s5, 12
	s_lshr_b32 s5, s4, 31
	s_ashr_i32 s4, s4, 12
	s_add_i32 s37, s37, s7
	s_add_i32 s4, s4, s5
	s_cmp_eq_u32 s37, s4
	v_mov_b32_e32 v3, s10
	s_cselect_b64 s[10:11], -1, 0
	s_cmp_lg_u32 s37, s4
	s_cselect_b64 s[12:13], -1, 0
	s_ashr_i32 s7, s6, 31
	v_and_b32_e32 v4, 15, v150
	s_lshl_b64 s[4:5], s[6:7], 1
	v_cmp_eq_u32_e64 s[44:45], 0, v4
	v_lshl_or_b32 v4, v170, 2, s6
	s_add_u32 s4, s17, s4
	v_ashrrev_i32_e32 v4, 6, v4
	v_ashrrev_i32_e32 v6, 5, v150
	s_addc_u32 s5, s39, s5
	v_lshlrev_b32_e32 v144, 3, v170
	v_ashrrev_i32_e32 v5, 31, v4
	v_lshl_add_u64 v[0:1], s[4:5], 0, v[144:145]
	v_lshl_add_u64 v[2:3], v[4:5], 2, v[2:3]
	v_mul_lo_u32 v4, v6, s22
	s_add_i32 s4, s1, s14
	s_lshl_b32 s1, s1, 10
	v_lshl_add_u32 v9, v170, 4, v4
	v_add_u32_e32 v4, s29, v6
	s_sub_i32 s4, s4, s15
	s_add_i32 s1, s1, s16
	v_lshl_add_u32 v11, s4, 10, v4
	v_add_u32_e32 v4, s1, v4
	s_lshl_b32 s1, s15, 10
	s_mov_b32 s18, 0
	v_readlane_b32 s39, v223, 29
	v_lshlrev_b32_e32 v10, 2, v6
	v_subrev_u32_e32 v12, s1, v4
	v_mov_b32_e32 v8, 0
	s_branch .LBB0_198

; DI int otid() { int t = threadIdx.x; asm volatile("" : "+v"(t)); return t; }
; template <bool SWAP, bool HALF>
; DI void gemm_mainloop(const GemmDesc& d, int m0, int n0, bf16_t* smem, f32x16 (&acc)[2][2], int dry) {
;   const int t = otid(), lane = t & 63, w = t >> 6, wm = w >> 1, wn = w & 1, r = lane & 31, hh = lane >> 5;
;   const int lrow = t >> 3, lkc = t & 7;
;   const bf16_t* ap[4]; const bf16_t* bp[4];
; #pragma unroll
;   for (int i = 0; i < 4; ++i) {
;     int am = m0 + lrow + 32 * i; am = am < M ? am : M - 1;
;     ap[i] = d.A + (size_t)am * d.lda + lkc * 8 + (d.a_grp ? (n0 / d.a_grp) * d.a_grp : 0);
;     bp[i] = d.Bt + (size_t)(n0 + lrow + 32 * i) * d.ldb + lkc * 8;
;   }
; #pragma unroll
;   for (int a = 0; a < 2; ++a)
; #pragma unroll
;     for (int b = 0; b < 2; ++b)
; #pragma unroll
;       for (int i = 0; i < 16; ++i) acc[a][b][i] = 0.f;
;   u32x4 ra0[4], rb0[4], ra1[4], rb1[4];
;   const int nk = d.K >> 6;
;   const int lds_w = lrow * LST + lkc * 8;
;     ...
;   gl(ra0, rb0, 0);
;   gl(ra1, rb1, 1);
;   lw(ra0, rb0, 0);
;   gl(ra0, rb0, 2);
;   __syncthreads();
;   ldf(0, 0, 0);
.LBB0_500:
	s_lshr_b32 s1, s8, 3
	s_and_b32 s1, s1, 0xffffff8
	v_readlane_b32 s5, v228, 38
	s_sub_i32 s5, s5, s1
	s_min_i32 s5, s5, 8
	s_abs_i32 s9, s5
	v_cvt_f32_u32_e32 v0, s9
	s_sub_i32 s10, 0, s9
	s_lshl_b32 s4, s1, 3
	s_sub_i32 s4, s8, s4
	v_rcp_iflag_f32_e32 v0, v0
	s_abs_i32 s7, s4
	s_xor_b32 s6, s4, s5
	s_ashr_i32 s6, s6, 31
	v_mul_f32_e32 v0, 0x4f7ffffe, v0
	v_cvt_u32_f32_e32 v0, v0
	v_mov_b32_e32 v150, v172
	v_mov_b32_e32 v32, v172
	v_readfirstlane_b32 s11, v0
	s_mul_i32 s10, s10, s11
	s_mul_hi_u32 s10, s11, s10
	s_add_i32 s11, s11, s10
	s_mul_hi_u32 s10, s7, s11
	s_mul_i32 s11, s10, s9
	s_sub_i32 s7, s7, s11
	s_add_i32 s11, s10, 1
	s_sub_i32 s12, s7, s9
	s_cmp_ge_u32 s7, s9
	s_cselect_b32 s10, s11, s10
	s_cselect_b32 s7, s12, s7
	s_add_i32 s11, s10, 1
	s_cmp_ge_u32 s7, s9
	s_cselect_b32 s7, s11, s10
	s_xor_b32 s7, s7, s6
	s_sub_i32 s6, s7, s6
	s_mul_i32 s5, s6, s5
	s_sub_i32 s4, s4, s5
	s_add_i32 s1, s1, s4
	s_lshl_b32 s4, s6, 7
	s_lshl_b32 s1, s1, 10
	v_ashrrev_i32_e32 v10, 3, v32
	v_lshlrev_b32_e32 v0, 3, v32
	v_and_b32_e32 v33, 56, v0
	v_add_u32_e32 v2, s4, v10
	v_readlane_b32 s44, v228, 56
	s_or_b32 s9, s1, s29
	v_lshlrev_b32_e32 v144, 1, v33
	v_readlane_b32 s45, v228, 57
	v_ashrrev_i32_e32 v3, 31, v2
	v_add_u32_e32 v11, s9, v10
	v_lshl_add_u64 v[4:5], s[44:45], 0, v[144:145]
	v_lshlrev_b64 v[2:3], 11, v[2:3]
	v_lshl_add_u64 v[154:155], v[4:5], 0, v[2:3]
	v_min_i32_e32 v2, 0x801f, v11
	v_ashrrev_i32_e32 v3, 31, v2
	v_lshl_add_u64 v[0:1], s[68:69], 0, v[144:145]
	v_lshlrev_b64 v[2:3], 11, v[2:3]
	v_lshl_add_u64 v[8:9], v[0:1], 0, v[2:3]
	v_min_i32_e32 v2, 0x7fff, v11
	v_ashrrev_i32_e32 v3, 31, v2
	v_min_i32_e32 v6, 0x803f, v11
	v_lshlrev_b64 v[2:3], 11, v[2:3]
	v_ashrrev_i32_e32 v7, 31, v6
	v_lshl_add_u64 v[16:17], v[0:1], 0, v[2:3]
	v_min_i32_e32 v2, 0x7fdf, v11
	v_lshlrev_b64 v[6:7], 11, v[6:7]
	v_ashrrev_i32_e32 v3, 31, v2
	v_lshl_add_u64 v[152:153], v[0:1], 0, v[6:7]
	v_lshlrev_b64 v[2:3], 11, v[2:3]
	v_lshl_add_u64 v[24:25], v[0:1], 0, v[2:3]
	s_mov_b64 s[6:7], 0x10000
	v_lshl_add_u64 v[156:157], v[8:9], 0, s[6:7]
	v_lshl_add_u64 v[158:159], v[154:155], 0, s[6:7]
	s_mov_b64 s[6:7], 0x20000
	v_lshl_add_u64 v[160:161], v[16:17], 0, s[6:7]
	v_lshl_add_u64 v[162:163], v[154:155], 0, s[6:7]
	s_mov_b64 s[6:7], 0x30000
	s_movk_i32 s1, 0x48
	v_lshl_add_u64 v[164:165], v[24:25], 0, s[6:7]
	v_lshl_add_u64 v[166:167], v[154:155], 0, s[6:7]
	v_and_b32_e32 v34, 31, v32
	v_mul_lo_u32 v35, v10, s1
	v_readlane_b32 s46, v228, 58
	v_readlane_b32 s47, v228, 59
	s_mov_b32 s1, 0x10000
	v_add_co_u32_e32 v8, vcc, s1, v8
	s_nop 1
	v_addc_co_u32_e32 v9, vcc, 0, v9, vcc
	s_waitcnt vmcnt(19)
	v_add_co_u32_e32 v12, vcc, s1, v154
	s_nop 1
	v_addc_co_u32_e32 v13, vcc, 0, v155, vcc
	s_mov_b32 s1, 0x20000
	v_add_co_u32_e32 v16, vcc, s1, v16
	s_nop 1
	v_addc_co_u32_e32 v17, vcc, 0, v17, vcc
	v_add_co_u32_e32 v20, vcc, s1, v154
	s_nop 1
	v_addc_co_u32_e32 v21, vcc, 0, v155, vcc
	s_mov_b32 s1, 0x30000
	v_add_co_u32_e32 v24, vcc, s1, v24
	s_nop 1
	v_addc_co_u32_e32 v25, vcc, 0, v25, vcc
	v_add_co_u32_e32 v28, vcc, s1, v154
	s_nop 1
	v_addc_co_u32_e32 v29, vcc, 0, v155, vcc
	s_nop 0
	v_add_lshl_u32 v144, v35, v33, 1
	s_waitcnt vmcnt(15)
	s_waitcnt vmcnt(14)
	s_waitcnt vmcnt(13)
	s_waitcnt vmcnt(12)
	s_waitcnt vmcnt(11)
	s_waitcnt vmcnt(10)
	s_waitcnt vmcnt(9)
	s_waitcnt vmcnt(8)
	v_lshrrev_b32_e32 v0, 1, v32
	v_and_or_b32 v1, v0, s72, v34
	v_and_b32_e32 v0, 16, v0
	s_movk_i32 s1, 0x90
	v_mad_u64_u32 v[168:169], s[6:7], v1, s1, v[0:1]
	v_and_b32_e32 v1, 0x5f, v32
	v_mul_u32_u24_e32 v1, 0x48, v1
	v_lshl_add_u32 v169, v1, 1, v0
	v_bfe_u32 v204, v172, 4, 3
	v_lshlrev_b32_e32 v204, 4, v204
	v_xor_b32_e32 v152, v152, v204
	v_xor_b32_e32 v154, v154, v204
	v_xor_b32_e32 v156, v156, v204
	v_xor_b32_e32 v158, v158, v204
	v_xor_b32_e32 v160, v160, v204
	v_xor_b32_e32 v162, v162, v204
	v_xor_b32_e32 v164, v164, v204
	v_xor_b32_e32 v166, v166, v204
	v_lshrrev_b32_e32 v205, 6, v172
	s_nop 1
	v_readfirstlane_b32 s101, v205
	s_lshl_b32 s101, s101, 10
	s_add_u32 m0, s101, 0x0
	s_nop 0
	global_load_lds_dwordx4 v[152:153], off
	s_add_u32 m0, s101, 0x4000
	s_nop 0
	global_load_lds_dwordx4 v[154:155], off
	s_add_u32 m0, s101, 0x1000
	s_nop 0
	global_load_lds_dwordx4 v[156:157], off
	s_add_u32 m0, s101, 0x5000
	s_nop 0
	global_load_lds_dwordx4 v[158:159], off
	s_add_u32 m0, s101, 0x2000
	s_nop 0
	global_load_lds_dwordx4 v[160:161], off
	s_add_u32 m0, s101, 0x6000
	s_nop 0
	global_load_lds_dwordx4 v[162:163], off
	s_add_u32 m0, s101, 0x3000
	s_nop 0
	global_load_lds_dwordx4 v[164:165], off
	s_add_u32 m0, s101, 0x7000
	s_nop 0
	global_load_lds_dwordx4 v[166:167], off
	v_and_b32_e32 v204, 15, v172
	v_bfe_u32 v205, v172, 4, 2
	v_lshrrev_b32_e32 v206, 1, v204
	v_xor_b32_e32 v205, v205, v206
	v_lshlrev_b32_e32 v205, 4, v205
	v_lshl_or_b32 v204, v204, 7, v205
	v_lshrrev_b32_e32 v206, 7, v172
	v_lshl_add_u32 v168, v206, 13, v204
	v_bfe_u32 v206, v172, 6, 1
	v_lshl_add_u32 v169, v206, 13, v204
	v_add_u32_e32 v169, 0x4000, v169
	v_xor_b32_e32 v220, 64, v168
	v_xor_b32_e32 v221, 64, v169
	s_waitcnt vmcnt(0)
	s_waitcnt lgkmcnt(0)
	s_barrier
	v_mov_b32_e32 v0, 0
	v_add_u32_e32 v170, 0x9000, v144
	s_mov_b32 s1, -2
	v_mov_b32_e32 v1, v0
	v_mov_b32_e32 v2, v0
	v_mov_b32_e32 v3, v0
	v_mov_b32_e32 v4, v0
	v_mov_b32_e32 v5, v0
	v_mov_b32_e32 v6, v0
	v_mov_b32_e32 v7, v0
	v_mov_b32_e32 v8, v0
	v_mov_b32_e32 v9, v0
	v_mov_b32_e32 v10, v0
	v_mov_b32_e32 v11, v0
	v_mov_b32_e32 v12, v0
	v_mov_b32_e32 v13, v0
	v_mov_b32_e32 v14, v0
	v_mov_b32_e32 v15, v0
	v_mov_b32_e32 v16, v0
	v_mov_b32_e32 v17, v0
	v_mov_b32_e32 v18, v0
	v_mov_b32_e32 v19, v0
	v_mov_b32_e32 v20, v0
	v_mov_b32_e32 v21, v0
	v_mov_b32_e32 v22, v0
	v_mov_b32_e32 v23, v0
	v_mov_b32_e32 v24, v0
	v_mov_b32_e32 v25, v0
	v_mov_b32_e32 v26, v0
	v_mov_b32_e32 v27, v0
	v_mov_b32_e32 v28, v0
	v_mov_b32_e32 v29, v0
	v_mov_b32_e32 v30, v0
	v_mov_b32_e32 v31, v0
	v_mov_b32_e32 v32, v0
	v_mov_b32_e32 v33, v0
	v_mov_b32_e32 v34, v0
	v_mov_b32_e32 v35, v0
	v_mov_b32_e32 v36, v0
	v_mov_b32_e32 v37, v0
	v_mov_b32_e32 v38, v0
	v_mov_b32_e32 v39, v0
	v_mov_b32_e32 v40, v0
	v_mov_b32_e32 v41, v0
	v_mov_b32_e32 v42, v0
	v_mov_b32_e32 v43, v0
	v_mov_b32_e32 v44, v0
	v_mov_b32_e32 v45, v0
	v_mov_b32_e32 v46, v0
	v_mov_b32_e32 v47, v0
	v_mov_b32_e32 v48, v0
	v_mov_b32_e32 v49, v0
	v_mov_b32_e32 v50, v0
	v_mov_b32_e32 v51, v0
	v_mov_b32_e32 v52, v0
	v_mov_b32_e32 v53, v0
	v_mov_b32_e32 v54, v0
	v_mov_b32_e32 v55, v0
	v_mov_b32_e32 v56, v0
	v_mov_b32_e32 v57, v0
	v_mov_b32_e32 v58, v0
	v_mov_b32_e32 v59, v0
	v_mov_b32_e32 v60, v0
	v_mov_b32_e32 v61, v0
	v_mov_b32_e32 v62, v0
	v_mov_b32_e32 v63, v0
; #define MFMA32(a, b, c) __builtin_amdgcn_mfma_f32_32x32x16_bf16((a), (b), (c), 0, 0, 0)
; #define SB_ __builtin_amdgcn_sched_barrier(0)
; template <bool SWAP, bool HALF>
; DI void gemm_mainloop(const GemmDesc& d, int m0, int n0, bf16_t* smem, f32x16 (&acc)[2][2], int dry) {
;     ...
;   auto lw = [&](const u32x4 (&ra)[4], const u32x4 (&rb)[4], int buf) {
;     bf16_t* An = smem + buf * 2 * TILE_EL + lds_w; bf16_t* Bn = An + TILE_EL;
; #pragma unroll
;     for (int i = 0; i < 4; ++i) {
;       *(u32x4*)(An + 32 * i * LST) = ra[i];
;       *(u32x4*)(Bn + 32 * i * LST) = rb[i];
;     }
;   };
;   bf16x8 fa[2][2], fb[2][2];
;   auto ldf = [&](int buf, int kk, int set) {
;     const bf16_t* Ab = smem + buf * 2 * TILE_EL + ((HALF ? 0 : wm * 64) + r) * LST + 8 * hh + kk * 16;
;     const bf16_t* Bb = smem + buf * 2 * TILE_EL + TILE_EL + ((HALF ? w * 32 : wn * 64) + r) * LST + 8 * hh + kk * 16;
; #pragma unroll
;     for (int i = 0; i < 2; ++i) { fa[set][i] = *(const bf16x8*)(Ab + i * 32 * LST); if (!HALF || i == 0) fb[set][i] = *(const bf16x8*)(Bb + i * 32 * LST); }
;   };
;   auto mma = [&](int set) {
; #pragma unroll
;     for (int a = 0; a < 2; ++a)
; #pragma unroll
;       for (int b = 0; b < (HALF ? 1 : 2); ++b) {
;         if (SWAP) acc[a][b] = MFMA32(fb[set][b], fa[set][a], acc[a][b]);
;         else      acc[a][b] = MFMA32(fa[set][a], fb[set][b], acc[a][b]);
;       }
;   };
;     ...
;   auto stage = [&](int cur, u32x4 (&ran)[4], u32x4 (&rbn)[4], int ks) {
;     ldf(cur, 1, 1); SB_;
;     mma(0); SB_;
;     ldf(cur, 2, 0); SB_;
;     lw(ran, rbn, cur ^ 1);
;     gl(ran, rbn, (ks + 3 < nk) ? ks + 3 : nk - 1);
;     SB_;
;     mma(1); SB_;
;     __syncthreads();
;     ldf(cur, 3, 1); SB_;
;     mma(0); SB_;
;     ldf(cur ^ 1, 0, 0);
;     SB_;
;     mma(1); SB_;
;     __syncthreads();
;   };
.LBB0_501:
	ds_read_b128 v[64:67], v168 offset:0
	ds_read_b128 v[68:71], v168 offset:2048
	ds_read_b128 v[72:75], v168 offset:4096
	ds_read_b128 v[76:79], v168 offset:6144
	ds_read_b128 v[80:83], v169 offset:0
	ds_read_b128 v[84:87], v169 offset:2048
	ds_read_b128 v[88:91], v169 offset:4096
	ds_read_b128 v[92:95], v169 offset:6144
	ds_read_b128 v[96:99], v220 offset:0
	ds_read_b128 v[100:103], v220 offset:2048
	ds_read_b128 v[104:107], v220 offset:4096
	ds_read_b128 v[108:111], v220 offset:6144
	ds_read_b128 v[112:115], v221 offset:0
	ds_read_b128 v[116:119], v221 offset:2048
	ds_read_b128 v[120:123], v221 offset:4096
	ds_read_b128 v[124:127], v221 offset:6144
	s_add_i32 s1, s1, 2
	s_add_i32 s5, s1, 1
	s_min_u32 s5, s5, 15
	s_lshl_b32 s18, s5, 7
	s_add_u32 m0, s101, 0x8000
	v_lshl_add_u64 v[128:129], v[152:153], 0, s[18:19]
	global_load_lds_dwordx4 v[128:129], off
	s_add_u32 m0, s101, 0xc000
	v_lshl_add_u64 v[128:129], v[154:155], 0, s[18:19]
	global_load_lds_dwordx4 v[128:129], off
	s_add_u32 m0, s101, 0x9000
	v_lshl_add_u64 v[128:129], v[156:157], 0, s[18:19]
	global_load_lds_dwordx4 v[128:129], off
	s_add_u32 m0, s101, 0xd000
	v_lshl_add_u64 v[128:129], v[158:159], 0, s[18:19]
	global_load_lds_dwordx4 v[128:129], off
	s_add_u32 m0, s101, 0xa000
	v_lshl_add_u64 v[128:129], v[160:161], 0, s[18:19]
	global_load_lds_dwordx4 v[128:129], off
	s_add_u32 m0, s101, 0xe000
	v_lshl_add_u64 v[128:129], v[162:163], 0, s[18:19]
	global_load_lds_dwordx4 v[128:129], off
	s_add_u32 m0, s101, 0xb000
	v_lshl_add_u64 v[128:129], v[164:165], 0, s[18:19]
	global_load_lds_dwordx4 v[128:129], off
	s_add_u32 m0, s101, 0xf000
	v_lshl_add_u64 v[128:129], v[166:167], 0, s[18:19]
	global_load_lds_dwordx4 v[128:129], off
	s_waitcnt lgkmcnt(8)
	v_mfma_f32_16x16x32_bf16 v[0:3], v[80:83], v[64:67], v[0:3]
	v_mfma_f32_16x16x32_bf16 v[4:7], v[84:87], v[64:67], v[4:7]
	v_mfma_f32_16x16x32_bf16 v[8:11], v[88:91], v[64:67], v[8:11]
	v_mfma_f32_16x16x32_bf16 v[12:15], v[92:95], v[64:67], v[12:15]
	v_mfma_f32_16x16x32_bf16 v[16:19], v[80:83], v[68:71], v[16:19]
	v_mfma_f32_16x16x32_bf16 v[20:23], v[84:87], v[68:71], v[20:23]
	v_mfma_f32_16x16x32_bf16 v[24:27], v[88:91], v[68:71], v[24:27]
	v_mfma_f32_16x16x32_bf16 v[28:31], v[92:95], v[68:71], v[28:31]
	v_mfma_f32_16x16x32_bf16 v[32:35], v[80:83], v[72:75], v[32:35]
	v_mfma_f32_16x16x32_bf16 v[36:39], v[84:87], v[72:75], v[36:39]
	v_mfma_f32_16x16x32_bf16 v[40:43], v[88:91], v[72:75], v[40:43]
	v_mfma_f32_16x16x32_bf16 v[44:47], v[92:95], v[72:75], v[44:47]
	v_mfma_f32_16x16x32_bf16 v[48:51], v[80:83], v[76:79], v[48:51]
	v_mfma_f32_16x16x32_bf16 v[52:55], v[84:87], v[76:79], v[52:55]
	v_mfma_f32_16x16x32_bf16 v[56:59], v[88:91], v[76:79], v[56:59]
	v_mfma_f32_16x16x32_bf16 v[60:63], v[92:95], v[76:79], v[60:63]
	s_waitcnt lgkmcnt(0)
	v_mfma_f32_16x16x32_bf16 v[0:3], v[112:115], v[96:99], v[0:3]
	v_mfma_f32_16x16x32_bf16 v[4:7], v[116:119], v[96:99], v[4:7]
	v_mfma_f32_16x16x32_bf16 v[8:11], v[120:123], v[96:99], v[8:11]
	v_mfma_f32_16x16x32_bf16 v[12:15], v[124:127], v[96:99], v[12:15]
	v_mfma_f32_16x16x32_bf16 v[16:19], v[112:115], v[100:103], v[16:19]
	v_mfma_f32_16x16x32_bf16 v[20:23], v[116:119], v[100:103], v[20:23]
	v_mfma_f32_16x16x32_bf16 v[24:27], v[120:123], v[100:103], v[24:27]
	v_mfma_f32_16x16x32_bf16 v[28:31], v[124:127], v[100:103], v[28:31]
	v_mfma_f32_16x16x32_bf16 v[32:35], v[112:115], v[104:107], v[32:35]
	v_mfma_f32_16x16x32_bf16 v[36:39], v[116:119], v[104:107], v[36:39]
	v_mfma_f32_16x16x32_bf16 v[40:43], v[120:123], v[104:107], v[40:43]
	v_mfma_f32_16x16x32_bf16 v[44:47], v[124:127], v[104:107], v[44:47]
	v_mfma_f32_16x16x32_bf16 v[48:51], v[112:115], v[108:111], v[48:51]
	v_mfma_f32_16x16x32_bf16 v[52:55], v[116:119], v[108:111], v[52:55]
	v_mfma_f32_16x16x32_bf16 v[56:59], v[120:123], v[108:111], v[56:59]
	v_mfma_f32_16x16x32_bf16 v[60:63], v[124:127], v[108:111], v[60:63]
	s_waitcnt vmcnt(0)
	s_barrier
	ds_read_b128 v[64:67], v168 offset:32768
	ds_read_b128 v[68:71], v168 offset:34816
	ds_read_b128 v[72:75], v168 offset:36864
	ds_read_b128 v[76:79], v168 offset:38912
	ds_read_b128 v[80:83], v169 offset:32768
	ds_read_b128 v[84:87], v169 offset:34816
	ds_read_b128 v[88:91], v169 offset:36864
	ds_read_b128 v[92:95], v169 offset:38912
	ds_read_b128 v[96:99], v220 offset:32768
	ds_read_b128 v[100:103], v220 offset:34816
	ds_read_b128 v[104:107], v220 offset:36864
	ds_read_b128 v[108:111], v220 offset:38912
	ds_read_b128 v[112:115], v221 offset:32768
	ds_read_b128 v[116:119], v221 offset:34816
	ds_read_b128 v[120:123], v221 offset:36864
	ds_read_b128 v[124:127], v221 offset:38912
	s_add_i32 s5, s1, 2
	s_min_u32 s5, s5, 15
	s_lshl_b32 s18, s5, 7
	s_add_u32 m0, s101, 0x0
	v_lshl_add_u64 v[128:129], v[152:153], 0, s[18:19]
	global_load_lds_dwordx4 v[128:129], off
	s_add_u32 m0, s101, 0x4000
	v_lshl_add_u64 v[128:129], v[154:155], 0, s[18:19]
	global_load_lds_dwordx4 v[128:129], off
	s_add_u32 m0, s101, 0x1000
	v_lshl_add_u64 v[128:129], v[156:157], 0, s[18:19]
	global_load_lds_dwordx4 v[128:129], off
	s_add_u32 m0, s101, 0x5000
	v_lshl_add_u64 v[128:129], v[158:159], 0, s[18:19]
	global_load_lds_dwordx4 v[128:129], off
	s_add_u32 m0, s101, 0x2000
	v_lshl_add_u64 v[128:129], v[160:161], 0, s[18:19]
	global_load_lds_dwordx4 v[128:129], off
	s_add_u32 m0, s101, 0x6000
	v_lshl_add_u64 v[128:129], v[162:163], 0, s[18:19]
	global_load_lds_dwordx4 v[128:129], off
	s_add_u32 m0, s101, 0x3000
	v_lshl_add_u64 v[128:129], v[164:165], 0, s[18:19]
	global_load_lds_dwordx4 v[128:129], off
	s_add_u32 m0, s101, 0x7000
	v_lshl_add_u64 v[128:129], v[166:167], 0, s[18:19]
	global_load_lds_dwordx4 v[128:129], off
	s_waitcnt lgkmcnt(8)
; #define SB_ __builtin_amdgcn_sched_barrier(0)
; template <bool SWAP, bool HALF>
; DI void gemm_mainloop(const GemmDesc& d, int m0, int n0, bf16_t* smem, f32x16 (&acc)[2][2], int dry) {
;     ...
;   auto stage = [&](int cur, u32x4 (&ran)[4], u32x4 (&rbn)[4], int ks) {
;     ldf(cur, 1, 1); SB_;
;     mma(0); SB_;
;     ldf(cur, 2, 0); SB_;
;     lw(ran, rbn, cur ^ 1);
;     gl(ran, rbn, (ks + 3 < nk) ? ks + 3 : nk - 1);
;     SB_;
;     mma(1); SB_;
;     __syncthreads();
;     ldf(cur, 3, 1); SB_;
;     mma(0); SB_;
;     ldf(cur ^ 1, 0, 0);
;     SB_;
;     mma(1); SB_;
;     __syncthreads();
;   };
;   gl(ra0, rb0, 0);
;   gl(ra1, rb1, 1);
;   lw(ra0, rb0, 0);
;   gl(ra0, rb0, 2);
;   __syncthreads();
;   ldf(0, 0, 0);
; #pragma unroll 1
;   for (int ks = 0; ks < nk; ks += 2) {
;     stage(0, ra1, rb1, ks);
;     stage(1, ra0, rb0, ks + 1);
;   }
	v_mfma_f32_16x16x32_bf16 v[0:3], v[80:83], v[64:67], v[0:3]
	v_mfma_f32_16x16x32_bf16 v[4:7], v[84:87], v[64:67], v[4:7]
	v_mfma_f32_16x16x32_bf16 v[8:11], v[88:91], v[64:67], v[8:11]
	v_mfma_f32_16x16x32_bf16 v[12:15], v[92:95], v[64:67], v[12:15]
	v_mfma_f32_16x16x32_bf16 v[16:19], v[80:83], v[68:71], v[16:19]
	v_mfma_f32_16x16x32_bf16 v[20:23], v[84:87], v[68:71], v[20:23]
	v_mfma_f32_16x16x32_bf16 v[24:27], v[88:91], v[68:71], v[24:27]
	v_mfma_f32_16x16x32_bf16 v[28:31], v[92:95], v[68:71], v[28:31]
	v_mfma_f32_16x16x32_bf16 v[32:35], v[80:83], v[72:75], v[32:35]
	v_mfma_f32_16x16x32_bf16 v[36:39], v[84:87], v[72:75], v[36:39]
	v_mfma_f32_16x16x32_bf16 v[40:43], v[88:91], v[72:75], v[40:43]
	v_mfma_f32_16x16x32_bf16 v[44:47], v[92:95], v[72:75], v[44:47]
	v_mfma_f32_16x16x32_bf16 v[48:51], v[80:83], v[76:79], v[48:51]
	v_mfma_f32_16x16x32_bf16 v[52:55], v[84:87], v[76:79], v[52:55]
	v_mfma_f32_16x16x32_bf16 v[56:59], v[88:91], v[76:79], v[56:59]
	v_mfma_f32_16x16x32_bf16 v[60:63], v[92:95], v[76:79], v[60:63]
	s_waitcnt lgkmcnt(0)
	v_mfma_f32_16x16x32_bf16 v[0:3], v[112:115], v[96:99], v[0:3]
	v_mfma_f32_16x16x32_bf16 v[4:7], v[116:119], v[96:99], v[4:7]
	v_mfma_f32_16x16x32_bf16 v[8:11], v[120:123], v[96:99], v[8:11]
	v_mfma_f32_16x16x32_bf16 v[12:15], v[124:127], v[96:99], v[12:15]
	v_mfma_f32_16x16x32_bf16 v[16:19], v[112:115], v[100:103], v[16:19]
	v_mfma_f32_16x16x32_bf16 v[20:23], v[116:119], v[100:103], v[20:23]
	v_mfma_f32_16x16x32_bf16 v[24:27], v[120:123], v[100:103], v[24:27]
	v_mfma_f32_16x16x32_bf16 v[28:31], v[124:127], v[100:103], v[28:31]
	v_mfma_f32_16x16x32_bf16 v[32:35], v[112:115], v[104:107], v[32:35]
	v_mfma_f32_16x16x32_bf16 v[36:39], v[116:119], v[104:107], v[36:39]
	v_mfma_f32_16x16x32_bf16 v[40:43], v[120:123], v[104:107], v[40:43]
	v_mfma_f32_16x16x32_bf16 v[44:47], v[124:127], v[104:107], v[44:47]
	v_mfma_f32_16x16x32_bf16 v[48:51], v[112:115], v[108:111], v[48:51]
	v_mfma_f32_16x16x32_bf16 v[52:55], v[116:119], v[108:111], v[52:55]
	v_mfma_f32_16x16x32_bf16 v[56:59], v[120:123], v[108:111], v[56:59]
	v_mfma_f32_16x16x32_bf16 v[60:63], v[124:127], v[108:111], v[60:63]
	s_cmp_lt_u32 s1, 14
	s_waitcnt vmcnt(0)
	s_barrier
	s_cbranch_scc1 .LBB0_501
; DI float ssq_f(u64 v) { return (float)v * (1.f / 1048576.f); }
; DI void gemm_tile(const GemmDesc& d, int m0, int n0, bf16_t* smem, int dry) {
;     ...
;   if (d.epi == EPI_RESID) {
; #pragma unroll
;     for (int pass = 0; pass < 16; ++pass) {
;       int m = m0 + pass * 8 + (t >> 5); m = m < M ? m : M - 1;
;       hpre[pass] = *(const u32x2*)(d.hb + (size_t)m * D + d.c_off + n0 + (t & 31) * 4);
;     }
;   } else if (t < 128) {
;     rs_s[t] = rsqrtf(ssq_f(myss) * d.inv_dim + EPS);
;   }
;   if (half) {
; #pragma unroll
;     for (int a = 0; a < 2; ++a)
; #pragma unroll
;       for (int g = 0; g < 4; ++g) {
;         f32x4 o;
; #pragma unroll
;         for (int j = 0; j < 4; ++j) o[j] = acc[a][0][4 * g + j];
;         *(f32x4*)(Ct + (a * 32 + r) * CS + w * 32 + 8 * g + 4 * hh) = o;
;       }
;   } else {
; #pragma unroll
;     for (int a = 0; a < 2; ++a)
; #pragma unroll
;       for (int b = 0; b < 2; ++b)
; #pragma unroll
;         for (int g = 0; g < 4; ++g) {
;           f32x4 o;
; #pragma unroll
;           for (int j = 0; j < 4; ++j) o[j] = acc[a][b][4 * g + j];
;           *(f32x4*)(Ct + (wm * 64 + a * 32 + r) * CS + wn * 64 + b * 32 + 8 * g + 4 * hh) = o;
;         }
;   }
;   __syncthreads();
;   if (d.epi == EPI_RESID) {
; #pragma unroll
;     for (int pass = 0; pass < 16; ++pass) {
;       const int row = pass * 8 + (t >> 5), c4 = t & 31, m = m0 + row;
;       float part = 0.f;
;       if (m < M) {
;         const f32x4 v = *(const f32x4*)(Ct + row * CS + c4 * 4);
;         const int n = d.c_off + n0 + c4 * 4;
;         f32x4 hv;
;         hv[0] = __uint_as_float(hpre[pass][0] << 16); hv[1] = __uint_as_float(hpre[pass][0] & 0xffff0000u);
;         hv[2] = __uint_as_float(hpre[pass][1] << 16); hv[3] = __uint_as_float(hpre[pass][1] & 0xffff0000u);
; #pragma unroll
;         for (int j = 0; j < 4; ++j) { hv[j] += v[j]; part += hv[j] * hv[j]; }
;         u32x2 o; o[0] = pk_bf16(hv[0], hv[1]); o[1] = pk_bf16(hv[2], hv[3]);
;         *(u32x2*)(d.hb + (size_t)m * D + n) = o;
;       }
	s_waitcnt vmcnt(7)
	v_ashrrev_i32_e32 v98, 5, v150
	v_add_u32_e32 v92, s9, v98
	s_ashr_i32 s5, s4, 31
	s_lshl_b64 s[6:7], s[4:5], 1
	v_add_u32_e32 v70, 16, v92
	v_add_u32_e32 v72, 24, v92
	s_add_u32 s6, s56, s6
	v_lshlrev_b32_e32 v64, 3, v150
	v_min_i32_e32 v66, 0x803f, v92
	v_add_u32_e32 v68, 8, v92
	v_min_i32_e32 v70, 0x803f, v70
	v_min_i32_e32 v72, 0x803f, v72
	s_addc_u32 s7, s57, s7
	v_and_b32_e32 v144, 0xf8, v64
	v_ashrrev_i32_e32 v67, 31, v66
	v_min_i32_e32 v68, 0x803f, v68
	v_ashrrev_i32_e32 v71, 31, v70
	v_ashrrev_i32_e32 v73, 31, v72
	v_lshl_add_u64 v[64:65], s[6:7], 0, v[144:145]
	v_lshlrev_b64 v[66:67], 11, v[66:67]
	v_ashrrev_i32_e32 v69, 31, v68
	v_lshlrev_b64 v[70:71], 11, v[70:71]
	v_lshlrev_b64 v[72:73], 11, v[72:73]
	v_lshl_add_u64 v[66:67], v[64:65], 0, v[66:67]
	v_lshlrev_b64 v[68:69], 11, v[68:69]
	v_lshl_add_u64 v[70:71], v[64:65], 0, v[70:71]
	v_lshl_add_u64 v[72:73], v[64:65], 0, v[72:73]
	v_lshl_add_u64 v[68:69], v[64:65], 0, v[68:69]
	global_load_dwordx2 v[96:97], v[66:67], off
	global_load_dwordx2 v[94:95], v[68:69], off
	global_load_dwordx2 v[90:91], v[70:71], off
	global_load_dwordx2 v[88:89], v[72:73], off
	v_add_u32_e32 v66, 32, v92
	v_add_u32_e32 v70, 48, v92
	v_add_u32_e32 v72, 56, v92
	v_min_i32_e32 v66, 0x803f, v66
	v_add_u32_e32 v68, 40, v92
	v_min_i32_e32 v70, 0x803f, v70
	v_min_i32_e32 v72, 0x803f, v72
	v_ashrrev_i32_e32 v67, 31, v66
	v_min_i32_e32 v68, 0x803f, v68
	v_ashrrev_i32_e32 v71, 31, v70
	v_ashrrev_i32_e32 v73, 31, v72
	v_lshlrev_b64 v[66:67], 11, v[66:67]
	v_ashrrev_i32_e32 v69, 31, v68
	v_lshlrev_b64 v[70:71], 11, v[70:71]
	v_lshlrev_b64 v[72:73], 11, v[72:73]
	v_lshl_add_u64 v[66:67], v[64:65], 0, v[66:67]
	v_lshlrev_b64 v[68:69], 11, v[68:69]
	v_lshl_add_u64 v[70:71], v[64:65], 0, v[70:71]
	v_lshl_add_u64 v[72:73], v[64:65], 0, v[72:73]
	v_lshl_add_u64 v[68:69], v[64:65], 0, v[68:69]
	global_load_dwordx2 v[86:87], v[66:67], off
	global_load_dwordx2 v[84:85], v[68:69], off
	global_load_dwordx2 v[82:83], v[70:71], off
	global_load_dwordx2 v[80:81], v[72:73], off
	v_add_u32_e32 v66, 64, v92
	v_add_u32_e32 v70, 0x50, v92
	v_add_u32_e32 v72, 0x58, v92
	v_min_i32_e32 v66, 0x803f, v66
	v_add_u32_e32 v68, 0x48, v92
	v_min_i32_e32 v70, 0x803f, v70
	v_min_i32_e32 v72, 0x803f, v72
	v_ashrrev_i32_e32 v67, 31, v66
	v_min_i32_e32 v68, 0x803f, v68
	v_ashrrev_i32_e32 v71, 31, v70
	v_ashrrev_i32_e32 v73, 31, v72
	v_lshlrev_b64 v[66:67], 11, v[66:67]
	v_ashrrev_i32_e32 v69, 31, v68
	v_lshlrev_b64 v[70:71], 11, v[70:71]
	v_lshlrev_b64 v[72:73], 11, v[72:73]
	v_lshl_add_u64 v[66:67], v[64:65], 0, v[66:67]
	v_lshlrev_b64 v[68:69], 11, v[68:69]
	v_lshl_add_u64 v[70:71], v[64:65], 0, v[70:71]
	v_lshl_add_u64 v[72:73], v[64:65], 0, v[72:73]
	v_lshl_add_u64 v[68:69], v[64:65], 0, v[68:69]
	global_load_dwordx2 v[78:79], v[66:67], off
	global_load_dwordx2 v[76:77], v[68:69], off
	global_load_dwordx2 v[74:75], v[70:71], off
	s_nop 0
	global_load_dwordx2 v[72:73], v[72:73], off
	v_add_u32_e32 v70, 0x70, v92
	v_min_i32_e32 v70, 0x803f, v70
	v_ashrrev_i32_e32 v71, 31, v70
	v_lshlrev_b64 v[70:71], 11, v[70:71]
	v_add_u32_e32 v66, 0x60, v92
	v_add_u32_e32 v68, 0x68, v92
	s_waitcnt vmcnt(18)
	v_lshl_add_u64 v[100:101], v[64:65], 0, v[70:71]
	v_add_u32_e32 v70, 0x78, v92
	v_min_i32_e32 v66, 0x803f, v66
	v_min_i32_e32 v68, 0x803f, v68
	v_min_i32_e32 v70, 0x803f, v70
	v_ashrrev_i32_e32 v67, 31, v66
	v_ashrrev_i32_e32 v69, 31, v68
	v_ashrrev_i32_e32 v71, 31, v70
	v_lshlrev_b64 v[66:67], 11, v[66:67]
	v_lshlrev_b64 v[68:69], 11, v[68:69]
	v_lshlrev_b64 v[70:71], 11, v[70:71]
	v_lshl_add_u64 v[66:67], v[64:65], 0, v[66:67]
	v_lshl_add_u64 v[68:69], v[64:65], 0, v[68:69]
	v_lshl_add_u64 v[64:65], v[64:65], 0, v[70:71]
	global_load_dwordx2 v[70:71], v[66:67], off
	s_nop 0
	global_load_dwordx2 v[68:69], v[68:69], off
	s_nop 0
	global_load_dwordx2 v[66:67], v[100:101], off
	s_nop 0
	global_load_dwordx2 v[64:65], v[64:65], off
	v_and_b32_e32 v99, 31, v150
	v_lshrrev_b32_e32 v100, 1, v150
	v_lshlrev_b32_e32 v93, 2, v150
	v_and_or_b32 v101, v100, s72, v99
	v_and_b32_e32 v100, 16, v100
	s_movk_i32 s1, 0x100
	v_and_or_b32 v100, v93, s1, v100
	v_mad_u64_u32 v[100:101], s[6:7], v101, s22, v[100:101]
	v_and_b32_e32 v204, 15, v172
	v_lshrrev_b32_e32 v205, 1, v172
	v_and_or_b32 v204, v205, s72, v204
	v_lshlrev_b32_e32 v205, 2, v172
	v_and_b32_e32 v206, 0x30, v172
	v_and_b32_e32 v205, 0x100, v205
	v_or_b32_e32 v205, v205, v206
	v_mad_u32_u24 v100, v204, s22, v205
	ds_write_b128 v100, v[0:3]
	ds_write_b128 v100, v[4:7] offset:64
	ds_write_b128 v100, v[8:11] offset:128
	ds_write_b128 v100, v[12:15] offset:192
	ds_write_b128 v100, v[16:19] offset:8448
	ds_write_b128 v100, v[20:23] offset:8512
	ds_write_b128 v100, v[24:27] offset:8576
	ds_write_b128 v100, v[28:31] offset:8640
	ds_write_b128 v100, v[32:35] offset:16896
	ds_write_b128 v100, v[36:39] offset:16960
	ds_write_b128 v100, v[40:43] offset:17024
	ds_write_b128 v100, v[44:47] offset:17088
	ds_write_b128 v100, v[48:51] offset:25344
	ds_write_b128 v100, v[52:55] offset:25408
	ds_write_b128 v100, v[56:59] offset:25472
	ds_write_b128 v100, v[60:63] offset:25536
	v_lshl_or_b32 v0, v99, 2, s4
	v_lshlrev_b32_e32 v2, 4, v99
	v_cmp_gt_i32_e64 s[4:5], s23, v92
	v_mov_b32_e32 v4, 0
	v_ashrrev_i32_e32 v93, 31, v92
	v_ashrrev_i32_e32 v1, 31, v0
	s_waitcnt lgkmcnt(0)
	s_barrier
	s_and_saveexec_b64 s[6:7], s[4:5]
	s_cbranch_execz .LBB0_504
	v_mad_u64_u32 v[4:5], s[10:11], v98, s22, v[2:3]
	ds_read_b128 v[4:7], v4
	s_waitcnt vmcnt(15)
	v_lshlrev_b32_e32 v8, 16, v96
	v_and_b32_e32 v9, 0xffff0000, v96
	v_and_b32_e32 v11, 0xffff0000, v97
	v_lshlrev_b32_e32 v10, 16, v97
	s_waitcnt lgkmcnt(0)
	v_pk_add_f32 v[8:9], v[4:5], v[8:9]
	v_pk_add_f32 v[6:7], v[6:7], v[10:11]
	v_pk_mul_f32 v[4:5], v[8:9], v[8:9]
	v_pk_mul_f32 v[10:11], v[6:7], v[6:7]
	v_add_f32_e32 v3, v4, v5
	v_cvt_pk_bf16_f32 v8, v8, v9
	v_cvt_pk_bf16_f32 v9, v6, v7
	v_lshlrev_b64 v[6:7], 11, v[92:93]
	v_add_f32_e32 v3, v10, v3
	v_lshl_add_u64 v[6:7], s[56:57], 0, v[6:7]
	v_add_f32_e32 v4, v11, v3
	v_lshl_add_u64 v[6:7], v[0:1], 1, v[6:7]
	global_store_dwordx2 v[6:7], v[8:9], off

; DI int otid() { int t = threadIdx.x; asm volatile("" : "+v"(t)); return t; }
; template <bool SWAP, bool HALF>
; DI void gemm_mainloop(const GemmDesc& d, int m0, int n0, bf16_t* smem, f32x16 (&acc)[2][2], int dry) {
;   const int t = otid(), lane = t & 63, w = t >> 6, wm = w >> 1, wn = w & 1, r = lane & 31, hh = lane >> 5;
;   const int lrow = t >> 3, lkc = t & 7;
;   const bf16_t* ap[4]; const bf16_t* bp[4];
; #pragma unroll
;   for (int i = 0; i < 4; ++i) {
;     int am = m0 + lrow + 32 * i; am = am < M ? am : M - 1;
;     ap[i] = d.A + (size_t)am * d.lda + lkc * 8 + (d.a_grp ? (n0 / d.a_grp) * d.a_grp : 0);
;     bp[i] = d.Bt + (size_t)(n0 + lrow + 32 * i) * d.ldb + lkc * 8;
;   }
; #pragma unroll
;   for (int a = 0; a < 2; ++a)
; #pragma unroll
;     for (int b = 0; b < 2; ++b)
; #pragma unroll
;       for (int i = 0; i < 16; ++i) acc[a][b][i] = 0.f;
;   u32x4 ra0[4], rb0[4], ra1[4], rb1[4];
;   const int nk = d.K >> 6;
;   const int lds_w = lrow * LST + lkc * 8;
;     ...
;   gl(ra0, rb0, 0);
;   gl(ra1, rb1, 1);
;   lw(ra0, rb0, 0);
;   gl(ra0, rb0, 2);
;   __syncthreads();
;   ldf(0, 0, 0);
.LBB0_626:
	s_or_b64 exec, exec, s[4:5]
	v_mov_b32_e32 v32, v172
	v_readlane_b32 s76, v228, 60
	v_ashrrev_i32_e32 v10, 3, v32
	v_add_u32_e32 v11, s6, v10
	v_lshlrev_b32_e32 v0, 3, v32
	v_and_b32_e32 v33, 56, v0
	v_min_i32_e32 v0, 0x803f, v11
	v_lshlrev_b32_e32 v144, 1, v33
	v_ashrrev_i32_e32 v1, 31, v0
	v_lshl_add_u64 v[4:5], s[56:57], 0, v[144:145]
	v_lshlrev_b64 v[0:1], 11, v[0:1]
	v_lshl_add_u64 v[152:153], v[4:5], 0, v[0:1]
	s_lshl_b32 s6, s10, 7
	v_add_u32_e32 v6, s6, v10
	v_readlane_b32 s82, v223, 2
	v_readlane_b32 s83, v223, 3
	v_ashrrev_i32_e32 v7, 31, v6
	v_lshlrev_b64 v[6:7], 11, v[6:7]
	v_lshl_add_u64 v[8:9], s[82:83], 0, v[144:145]
	v_lshl_add_u64 v[154:155], v[8:9], 0, v[6:7]
	v_min_i32_e32 v6, 0x801f, v11
	v_ashrrev_i32_e32 v7, 31, v6
	v_lshlrev_b64 v[6:7], 11, v[6:7]
	v_lshl_add_u64 v[8:9], v[4:5], 0, v[6:7]
	v_min_i32_e32 v6, 0x7fff, v11
	v_ashrrev_i32_e32 v7, 31, v6
	v_lshlrev_b64 v[6:7], 11, v[6:7]
	v_lshl_add_u64 v[16:17], v[4:5], 0, v[6:7]
	v_min_i32_e32 v6, 0x7fdf, v11
	s_mov_b64 s[4:5], 0x10000
	v_ashrrev_i32_e32 v7, 31, v6
	v_lshl_add_u64 v[156:157], v[8:9], 0, s[4:5]
	v_lshl_add_u64 v[158:159], v[154:155], 0, s[4:5]
	s_mov_b64 s[4:5], 0x20000
	v_lshlrev_b64 v[6:7], 11, v[6:7]
	v_lshl_add_u64 v[160:161], v[16:17], 0, s[4:5]
	v_lshl_add_u64 v[162:163], v[154:155], 0, s[4:5]
	v_lshl_add_u64 v[24:25], v[4:5], 0, v[6:7]
	s_mov_b64 s[4:5], 0x30000
	v_lshl_add_u64 v[164:165], v[24:25], 0, s[4:5]
	v_lshl_add_u64 v[166:167], v[154:155], 0, s[4:5]
	s_movk_i32 s4, 0x48
	v_and_b32_e32 v34, 31, v32
	v_mul_lo_u32 v35, v10, s4
	v_readlane_b32 s77, v228, 61
	v_readlane_b32 s78, v228, 62
	v_readlane_b32 s79, v228, 63
	v_readlane_b32 s80, v223, 0
	v_readlane_b32 s81, v223, 1
	v_readlane_b32 s84, v223, 4
	v_readlane_b32 s85, v223, 5
	v_readlane_b32 s86, v223, 6
	v_readlane_b32 s87, v223, 7
	v_readlane_b32 s88, v223, 8
	v_readlane_b32 s89, v223, 9
	v_readlane_b32 s90, v223, 10
	v_readlane_b32 s91, v223, 11
	s_mov_b32 s8, 0x10000
	v_add_co_u32_e64 v8, s[4:5], s8, v8
	s_nop 1
	v_addc_co_u32_e64 v9, s[4:5], 0, v9, s[4:5]
	s_waitcnt vmcnt(19)
	v_add_co_u32_e64 v12, s[4:5], s8, v154
	s_nop 1
	v_addc_co_u32_e64 v13, s[4:5], 0, v155, s[4:5]
	s_mov_b32 s8, 0x20000
	v_add_co_u32_e64 v16, s[4:5], s8, v16
	s_nop 1
	v_addc_co_u32_e64 v17, s[4:5], 0, v17, s[4:5]
	v_add_co_u32_e64 v20, s[4:5], s8, v154
	s_nop 1
	v_addc_co_u32_e64 v21, s[4:5], 0, v155, s[4:5]
	s_mov_b32 s8, 0x30000
	v_add_co_u32_e64 v24, s[4:5], s8, v24
	s_nop 1
	v_addc_co_u32_e64 v25, s[4:5], 0, v25, s[4:5]
	v_add_co_u32_e64 v28, s[4:5], s8, v154
	s_nop 1
	v_addc_co_u32_e64 v29, s[4:5], 0, v155, s[4:5]
	s_nop 0
	v_add_lshl_u32 v144, v35, v33, 1
	s_waitcnt vmcnt(15)
	s_waitcnt vmcnt(14)
	s_waitcnt vmcnt(13)
	s_waitcnt vmcnt(12)
	s_waitcnt vmcnt(11)
	s_waitcnt vmcnt(10)
	s_waitcnt vmcnt(9)
	s_waitcnt vmcnt(8)
	v_lshrrev_b32_e32 v0, 1, v32
	v_and_or_b32 v1, v0, s72, v34
	v_and_b32_e32 v0, 16, v0
	s_movk_i32 s4, 0x90
	v_mad_u64_u32 v[168:169], s[4:5], v1, s4, v[0:1]
	v_and_b32_e32 v1, 0x5f, v32
	v_mul_u32_u24_e32 v1, 0x48, v1
	v_lshl_add_u32 v169, v1, 1, v0
	v_bfe_u32 v204, v172, 4, 3
	v_lshlrev_b32_e32 v204, 4, v204
	v_xor_b32_e32 v152, v152, v204
	v_xor_b32_e32 v154, v154, v204
	v_xor_b32_e32 v156, v156, v204
	v_xor_b32_e32 v158, v158, v204
	v_xor_b32_e32 v160, v160, v204
	v_xor_b32_e32 v162, v162, v204
	v_xor_b32_e32 v164, v164, v204
	v_xor_b32_e32 v166, v166, v204
	v_lshrrev_b32_e32 v205, 6, v172
	s_nop 1
	v_readfirstlane_b32 s101, v205
	s_lshl_b32 s101, s101, 10
	s_add_u32 m0, s101, 0x0
	s_nop 0
	global_load_lds_dwordx4 v[152:153], off
	s_add_u32 m0, s101, 0x4000
	s_nop 0
	global_load_lds_dwordx4 v[154:155], off
	s_add_u32 m0, s101, 0x1000
	s_nop 0
	global_load_lds_dwordx4 v[156:157], off
	s_add_u32 m0, s101, 0x5000
	s_nop 0
	global_load_lds_dwordx4 v[158:159], off
	s_add_u32 m0, s101, 0x2000
	s_nop 0
	global_load_lds_dwordx4 v[160:161], off
	s_add_u32 m0, s101, 0x6000
	s_nop 0
	global_load_lds_dwordx4 v[162:163], off
	s_add_u32 m0, s101, 0x3000
	s_nop 0
	global_load_lds_dwordx4 v[164:165], off
	s_add_u32 m0, s101, 0x7000
	s_nop 0
	global_load_lds_dwordx4 v[166:167], off
	v_and_b32_e32 v204, 15, v172
	v_bfe_u32 v205, v172, 4, 2
	v_lshrrev_b32_e32 v206, 1, v204
	v_xor_b32_e32 v205, v205, v206
	v_lshlrev_b32_e32 v205, 4, v205
	v_lshl_or_b32 v204, v204, 7, v205
	v_lshrrev_b32_e32 v206, 7, v172
	v_lshl_add_u32 v168, v206, 13, v204
	v_bfe_u32 v206, v172, 6, 1
	v_lshl_add_u32 v169, v206, 13, v204
	v_add_u32_e32 v169, 0x4000, v169
	v_xor_b32_e32 v220, 64, v168
	v_xor_b32_e32 v221, 64, v169
	s_waitcnt vmcnt(0)
	s_waitcnt lgkmcnt(0)
	s_barrier
	v_mov_b32_e32 v0, 0
	v_add_u32_e32 v171, 0x9000, v144
	s_mov_b32 s4, -2
	v_mov_b32_e32 v1, v0
	v_mov_b32_e32 v2, v0
	v_mov_b32_e32 v3, v0
	v_mov_b32_e32 v4, v0
	v_mov_b32_e32 v5, v0
	v_mov_b32_e32 v6, v0
	v_mov_b32_e32 v7, v0
	v_mov_b32_e32 v8, v0
	v_mov_b32_e32 v9, v0
	v_mov_b32_e32 v10, v0
	v_mov_b32_e32 v11, v0
	v_mov_b32_e32 v12, v0
	v_mov_b32_e32 v13, v0
	v_mov_b32_e32 v14, v0
	v_mov_b32_e32 v15, v0
	v_mov_b32_e32 v16, v0
	v_mov_b32_e32 v17, v0
	v_mov_b32_e32 v18, v0
	v_mov_b32_e32 v19, v0
	v_mov_b32_e32 v20, v0
	v_mov_b32_e32 v21, v0
	v_mov_b32_e32 v22, v0
	v_mov_b32_e32 v23, v0
	v_mov_b32_e32 v24, v0
	v_mov_b32_e32 v25, v0
	v_mov_b32_e32 v26, v0
	v_mov_b32_e32 v27, v0
	v_mov_b32_e32 v28, v0
	v_mov_b32_e32 v29, v0
	v_mov_b32_e32 v30, v0
	v_mov_b32_e32 v31, v0
	v_mov_b32_e32 v32, v0
	v_mov_b32_e32 v33, v0
	v_mov_b32_e32 v34, v0
	v_mov_b32_e32 v35, v0
	v_mov_b32_e32 v36, v0
	v_mov_b32_e32 v37, v0
	v_mov_b32_e32 v38, v0
	v_mov_b32_e32 v39, v0
	v_mov_b32_e32 v40, v0
	v_mov_b32_e32 v41, v0
	v_mov_b32_e32 v42, v0
	v_mov_b32_e32 v43, v0
	v_mov_b32_e32 v44, v0
	v_mov_b32_e32 v45, v0
	v_mov_b32_e32 v46, v0
	v_mov_b32_e32 v47, v0
	v_mov_b32_e32 v48, v0
	v_mov_b32_e32 v49, v0
	v_mov_b32_e32 v50, v0
	v_mov_b32_e32 v51, v0
	v_mov_b32_e32 v52, v0
	v_mov_b32_e32 v53, v0
	v_mov_b32_e32 v54, v0
	v_mov_b32_e32 v55, v0
	v_mov_b32_e32 v56, v0
	v_mov_b32_e32 v57, v0
	v_mov_b32_e32 v58, v0
	v_mov_b32_e32 v59, v0
	v_mov_b32_e32 v60, v0
	v_mov_b32_e32 v61, v0
	v_mov_b32_e32 v62, v0
	v_mov_b32_e32 v63, v0
; #define MFMA32(a, b, c) __builtin_amdgcn_mfma_f32_32x32x16_bf16((a), (b), (c), 0, 0, 0)
; #define SB_ __builtin_amdgcn_sched_barrier(0)
; template <bool SWAP, bool HALF>
; DI void gemm_mainloop(const GemmDesc& d, int m0, int n0, bf16_t* smem, f32x16 (&acc)[2][2], int dry) {
;     ...
;   auto lw = [&](const u32x4 (&ra)[4], const u32x4 (&rb)[4], int buf) {
;     bf16_t* An = smem + buf * 2 * TILE_EL + lds_w; bf16_t* Bn = An + TILE_EL;
; #pragma unroll
;     for (int i = 0; i < 4; ++i) {
;       *(u32x4*)(An + 32 * i * LST) = ra[i];
;       *(u32x4*)(Bn + 32 * i * LST) = rb[i];
;     }
;   };
;   bf16x8 fa[2][2], fb[2][2];
;   auto ldf = [&](int buf, int kk, int set) {
;     const bf16_t* Ab = smem + buf * 2 * TILE_EL + ((HALF ? 0 : wm * 64) + r) * LST + 8 * hh + kk * 16;
;     const bf16_t* Bb = smem + buf * 2 * TILE_EL + TILE_EL + ((HALF ? w * 32 : wn * 64) + r) * LST + 8 * hh + kk * 16;
; #pragma unroll
;     for (int i = 0; i < 2; ++i) { fa[set][i] = *(const bf16x8*)(Ab + i * 32 * LST); if (!HALF || i == 0) fb[set][i] = *(const bf16x8*)(Bb + i * 32 * LST); }
;   };
;   auto mma = [&](int set) {
; #pragma unroll
;     for (int a = 0; a < 2; ++a)
; #pragma unroll
;       for (int b = 0; b < (HALF ? 1 : 2); ++b) {
;         if (SWAP) acc[a][b] = MFMA32(fb[set][b], fa[set][a], acc[a][b]);
;         else      acc[a][b] = MFMA32(fa[set][a], fb[set][b], acc[a][b]);
;       }
;   };
;     ...
;   auto stage = [&](int cur, u32x4 (&ran)[4], u32x4 (&rbn)[4], int ks) {
;     ldf(cur, 1, 1); SB_;
;     mma(0); SB_;
;     ldf(cur, 2, 0); SB_;
;     lw(ran, rbn, cur ^ 1);
;     gl(ran, rbn, (ks + 3 < nk) ? ks + 3 : nk - 1);
;     SB_;
;     mma(1); SB_;
;     __syncthreads();
;     ldf(cur, 3, 1); SB_;
;     mma(0); SB_;
;     ldf(cur ^ 1, 0, 0);
;     SB_;
;     mma(1); SB_;
;     __syncthreads();
;   };
.LBB0_627:
	ds_read_b128 v[64:67], v168 offset:0
	ds_read_b128 v[68:71], v168 offset:2048
	ds_read_b128 v[72:75], v168 offset:4096
	ds_read_b128 v[76:79], v168 offset:6144
	ds_read_b128 v[80:83], v169 offset:0
	ds_read_b128 v[84:87], v169 offset:2048
	ds_read_b128 v[88:91], v169 offset:4096
	ds_read_b128 v[92:95], v169 offset:6144
	ds_read_b128 v[96:99], v220 offset:0
	ds_read_b128 v[100:103], v220 offset:2048
	ds_read_b128 v[104:107], v220 offset:4096
	ds_read_b128 v[108:111], v220 offset:6144
	ds_read_b128 v[112:115], v221 offset:0
	ds_read_b128 v[116:119], v221 offset:2048
	ds_read_b128 v[120:123], v221 offset:4096
	ds_read_b128 v[124:127], v221 offset:6144
	s_add_i32 s4, s4, 2
	s_add_i32 s5, s4, 1
	s_min_u32 s5, s5, 15
	s_lshl_b32 s18, s5, 7
	s_add_u32 m0, s101, 0x8000
	v_lshl_add_u64 v[128:129], v[152:153], 0, s[18:19]
	global_load_lds_dwordx4 v[128:129], off
	s_add_u32 m0, s101, 0xc000
	v_lshl_add_u64 v[128:129], v[154:155], 0, s[18:19]
	global_load_lds_dwordx4 v[128:129], off
	s_add_u32 m0, s101, 0x9000
	v_lshl_add_u64 v[128:129], v[156:157], 0, s[18:19]
	global_load_lds_dwordx4 v[128:129], off
	s_add_u32 m0, s101, 0xd000
	v_lshl_add_u64 v[128:129], v[158:159], 0, s[18:19]
	global_load_lds_dwordx4 v[128:129], off
	s_add_u32 m0, s101, 0xa000
	v_lshl_add_u64 v[128:129], v[160:161], 0, s[18:19]
	global_load_lds_dwordx4 v[128:129], off
	s_add_u32 m0, s101, 0xe000
	v_lshl_add_u64 v[128:129], v[162:163], 0, s[18:19]
	global_load_lds_dwordx4 v[128:129], off
	s_add_u32 m0, s101, 0xb000
	v_lshl_add_u64 v[128:129], v[164:165], 0, s[18:19]
	global_load_lds_dwordx4 v[128:129], off
	s_add_u32 m0, s101, 0xf000
	v_lshl_add_u64 v[128:129], v[166:167], 0, s[18:19]
	global_load_lds_dwordx4 v[128:129], off
	s_waitcnt lgkmcnt(8)
	v_mfma_f32_16x16x32_bf16 v[0:3], v[80:83], v[64:67], v[0:3]
	v_mfma_f32_16x16x32_bf16 v[4:7], v[84:87], v[64:67], v[4:7]
	v_mfma_f32_16x16x32_bf16 v[8:11], v[88:91], v[64:67], v[8:11]
	v_mfma_f32_16x16x32_bf16 v[12:15], v[92:95], v[64:67], v[12:15]
	v_mfma_f32_16x16x32_bf16 v[16:19], v[80:83], v[68:71], v[16:19]
	v_mfma_f32_16x16x32_bf16 v[20:23], v[84:87], v[68:71], v[20:23]
	v_mfma_f32_16x16x32_bf16 v[24:27], v[88:91], v[68:71], v[24:27]
	v_mfma_f32_16x16x32_bf16 v[28:31], v[92:95], v[68:71], v[28:31]
	v_mfma_f32_16x16x32_bf16 v[32:35], v[80:83], v[72:75], v[32:35]
	v_mfma_f32_16x16x32_bf16 v[36:39], v[84:87], v[72:75], v[36:39]
	v_mfma_f32_16x16x32_bf16 v[40:43], v[88:91], v[72:75], v[40:43]
	v_mfma_f32_16x16x32_bf16 v[44:47], v[92:95], v[72:75], v[44:47]
	v_mfma_f32_16x16x32_bf16 v[48:51], v[80:83], v[76:79], v[48:51]
	v_mfma_f32_16x16x32_bf16 v[52:55], v[84:87], v[76:79], v[52:55]
	v_mfma_f32_16x16x32_bf16 v[56:59], v[88:91], v[76:79], v[56:59]
	v_mfma_f32_16x16x32_bf16 v[60:63], v[92:95], v[76:79], v[60:63]
	s_waitcnt lgkmcnt(0)
	v_mfma_f32_16x16x32_bf16 v[0:3], v[112:115], v[96:99], v[0:3]
	v_mfma_f32_16x16x32_bf16 v[4:7], v[116:119], v[96:99], v[4:7]
	v_mfma_f32_16x16x32_bf16 v[8:11], v[120:123], v[96:99], v[8:11]
	v_mfma_f32_16x16x32_bf16 v[12:15], v[124:127], v[96:99], v[12:15]
	v_mfma_f32_16x16x32_bf16 v[16:19], v[112:115], v[100:103], v[16:19]
	v_mfma_f32_16x16x32_bf16 v[20:23], v[116:119], v[100:103], v[20:23]
	v_mfma_f32_16x16x32_bf16 v[24:27], v[120:123], v[100:103], v[24:27]
	v_mfma_f32_16x16x32_bf16 v[28:31], v[124:127], v[100:103], v[28:31]
	v_mfma_f32_16x16x32_bf16 v[32:35], v[112:115], v[104:107], v[32:35]
	v_mfma_f32_16x16x32_bf16 v[36:39], v[116:119], v[104:107], v[36:39]
	v_mfma_f32_16x16x32_bf16 v[40:43], v[120:123], v[104:107], v[40:43]
	v_mfma_f32_16x16x32_bf16 v[44:47], v[124:127], v[104:107], v[44:47]
	v_mfma_f32_16x16x32_bf16 v[48:51], v[112:115], v[108:111], v[48:51]
	v_mfma_f32_16x16x32_bf16 v[52:55], v[116:119], v[108:111], v[52:55]
	v_mfma_f32_16x16x32_bf16 v[56:59], v[120:123], v[108:111], v[56:59]
	v_mfma_f32_16x16x32_bf16 v[60:63], v[124:127], v[108:111], v[60:63]
	s_waitcnt vmcnt(0)
	s_barrier
; #define SB_ __builtin_amdgcn_sched_barrier(0)
; template <bool SWAP, bool HALF>
; DI void gemm_mainloop(const GemmDesc& d, int m0, int n0, bf16_t* smem, f32x16 (&acc)[2][2], int dry) {
;     ...
;   auto stage = [&](int cur, u32x4 (&ran)[4], u32x4 (&rbn)[4], int ks) {
;     ldf(cur, 1, 1); SB_;
;     mma(0); SB_;
;     ldf(cur, 2, 0); SB_;
;     lw(ran, rbn, cur ^ 1);
;     gl(ran, rbn, (ks + 3 < nk) ? ks + 3 : nk - 1);
;     SB_;
;     mma(1); SB_;
;     __syncthreads();
;     ldf(cur, 3, 1); SB_;
;     mma(0); SB_;
;     ldf(cur ^ 1, 0, 0);
;     SB_;
;     mma(1); SB_;
;     __syncthreads();
;   };
; DI void gemm_tile(const GemmDesc& d, int m0, int n0, bf16_t* smem, int dry) {
;     ...
; #pragma unroll
;     for (int a = 0; a < 2; ++a)
; #pragma unroll
;       for (int b = 0; b < 2; ++b)
; #pragma unroll
;         for (int g = 0; g < 4; ++g) {
;           f32x4 o;
; #pragma unroll
;           for (int j = 0; j < 4; ++j) o[j] = acc[a][b][4 * g + j];
;           *(f32x4*)(Ct + (wm * 64 + a * 32 + r) * CS + wn * 64 + b * 32 + 8 * g + 4 * hh) = o;
;         }
	ds_read_b128 v[64:67], v168 offset:32768
	ds_read_b128 v[68:71], v168 offset:34816
	ds_read_b128 v[72:75], v168 offset:36864
	ds_read_b128 v[76:79], v168 offset:38912
	ds_read_b128 v[80:83], v169 offset:32768
	ds_read_b128 v[84:87], v169 offset:34816
	ds_read_b128 v[88:91], v169 offset:36864
	ds_read_b128 v[92:95], v169 offset:38912
	ds_read_b128 v[96:99], v220 offset:32768
	ds_read_b128 v[100:103], v220 offset:34816
	ds_read_b128 v[104:107], v220 offset:36864
	ds_read_b128 v[108:111], v220 offset:38912
	ds_read_b128 v[112:115], v221 offset:32768
	ds_read_b128 v[116:119], v221 offset:34816
	ds_read_b128 v[120:123], v221 offset:36864
	ds_read_b128 v[124:127], v221 offset:38912
	s_add_i32 s5, s4, 2
	s_min_u32 s5, s5, 15
	s_lshl_b32 s18, s5, 7
	s_add_u32 m0, s101, 0x0
	v_lshl_add_u64 v[128:129], v[152:153], 0, s[18:19]
	global_load_lds_dwordx4 v[128:129], off
	s_add_u32 m0, s101, 0x4000
	v_lshl_add_u64 v[128:129], v[154:155], 0, s[18:19]
	global_load_lds_dwordx4 v[128:129], off
	s_add_u32 m0, s101, 0x1000
	v_lshl_add_u64 v[128:129], v[156:157], 0, s[18:19]
	global_load_lds_dwordx4 v[128:129], off
	s_add_u32 m0, s101, 0x5000
	v_lshl_add_u64 v[128:129], v[158:159], 0, s[18:19]
	global_load_lds_dwordx4 v[128:129], off
	s_add_u32 m0, s101, 0x2000
	v_lshl_add_u64 v[128:129], v[160:161], 0, s[18:19]
	global_load_lds_dwordx4 v[128:129], off
	s_add_u32 m0, s101, 0x6000
	v_lshl_add_u64 v[128:129], v[162:163], 0, s[18:19]
	global_load_lds_dwordx4 v[128:129], off
	s_add_u32 m0, s101, 0x3000
	v_lshl_add_u64 v[128:129], v[164:165], 0, s[18:19]
	global_load_lds_dwordx4 v[128:129], off
	s_add_u32 m0, s101, 0x7000
	v_lshl_add_u64 v[128:129], v[166:167], 0, s[18:19]
	global_load_lds_dwordx4 v[128:129], off
	s_waitcnt lgkmcnt(8)
	v_mfma_f32_16x16x32_bf16 v[0:3], v[80:83], v[64:67], v[0:3]
	v_mfma_f32_16x16x32_bf16 v[4:7], v[84:87], v[64:67], v[4:7]
	v_mfma_f32_16x16x32_bf16 v[8:11], v[88:91], v[64:67], v[8:11]
	v_mfma_f32_16x16x32_bf16 v[12:15], v[92:95], v[64:67], v[12:15]
	v_mfma_f32_16x16x32_bf16 v[16:19], v[80:83], v[68:71], v[16:19]
	v_mfma_f32_16x16x32_bf16 v[20:23], v[84:87], v[68:71], v[20:23]
	v_mfma_f32_16x16x32_bf16 v[24:27], v[88:91], v[68:71], v[24:27]
	v_mfma_f32_16x16x32_bf16 v[28:31], v[92:95], v[68:71], v[28:31]
	v_mfma_f32_16x16x32_bf16 v[32:35], v[80:83], v[72:75], v[32:35]
	v_mfma_f32_16x16x32_bf16 v[36:39], v[84:87], v[72:75], v[36:39]
	v_mfma_f32_16x16x32_bf16 v[40:43], v[88:91], v[72:75], v[40:43]
	v_mfma_f32_16x16x32_bf16 v[44:47], v[92:95], v[72:75], v[44:47]
	v_mfma_f32_16x16x32_bf16 v[48:51], v[80:83], v[76:79], v[48:51]
	v_mfma_f32_16x16x32_bf16 v[52:55], v[84:87], v[76:79], v[52:55]
	v_mfma_f32_16x16x32_bf16 v[56:59], v[88:91], v[76:79], v[56:59]
	v_mfma_f32_16x16x32_bf16 v[60:63], v[92:95], v[76:79], v[60:63]
	s_waitcnt lgkmcnt(0)
	v_mfma_f32_16x16x32_bf16 v[0:3], v[112:115], v[96:99], v[0:3]
	v_mfma_f32_16x16x32_bf16 v[4:7], v[116:119], v[96:99], v[4:7]
	v_mfma_f32_16x16x32_bf16 v[8:11], v[120:123], v[96:99], v[8:11]
	v_mfma_f32_16x16x32_bf16 v[12:15], v[124:127], v[96:99], v[12:15]
	v_mfma_f32_16x16x32_bf16 v[16:19], v[112:115], v[100:103], v[16:19]
	v_mfma_f32_16x16x32_bf16 v[20:23], v[116:119], v[100:103], v[20:23]
	v_mfma_f32_16x16x32_bf16 v[24:27], v[120:123], v[100:103], v[24:27]
	v_mfma_f32_16x16x32_bf16 v[28:31], v[124:127], v[100:103], v[28:31]
	v_mfma_f32_16x16x32_bf16 v[32:35], v[112:115], v[104:107], v[32:35]
	v_mfma_f32_16x16x32_bf16 v[36:39], v[116:119], v[104:107], v[36:39]
	v_mfma_f32_16x16x32_bf16 v[40:43], v[120:123], v[104:107], v[40:43]
	v_mfma_f32_16x16x32_bf16 v[44:47], v[124:127], v[104:107], v[44:47]
	v_mfma_f32_16x16x32_bf16 v[48:51], v[112:115], v[108:111], v[48:51]
	v_mfma_f32_16x16x32_bf16 v[52:55], v[116:119], v[108:111], v[52:55]
	v_mfma_f32_16x16x32_bf16 v[56:59], v[120:123], v[108:111], v[56:59]
	v_mfma_f32_16x16x32_bf16 v[60:63], v[124:127], v[108:111], v[60:63]
	s_cmp_lt_u32 s4, 14
	s_waitcnt vmcnt(0)
	s_barrier
	s_cbranch_scc1 .LBB0_627
	s_and_saveexec_b64 s[4:5], vcc
	s_cbranch_execz .LBB0_630
	s_mov_b32 s8, 0x800000
	s_waitcnt vmcnt(15)
	v_mul_f32_e32 v64, 0x4b800000, v170
	v_cmp_gt_f32_e32 vcc, s8, v170
	v_lshl_add_u32 v65, v150, 2, v181
	s_nop 0
	v_cndmask_b32_e32 v64, v170, v64, vcc
	v_rsq_f32_e32 v64, v64
	s_nop 0
	v_mul_f32_e32 v66, 0x45800000, v64
	v_cndmask_b32_e32 v64, v64, v66, vcc
	ds_write_b32 v65, v64
.LBB0_630:
	s_or_b64 exec, exec, s[4:5]
	s_waitcnt vmcnt(15)
	v_and_b32_e32 v64, 31, v150
	v_lshrrev_b32_e32 v65, 1, v150
	v_and_or_b32 v67, v65, s72, v64
	v_lshlrev_b32_e32 v66, 2, v150
	v_and_b32_e32 v65, 16, v65
	s_movk_i32 s4, 0x100
	v_and_or_b32 v66, v66, s4, v65
	s_cmp_gt_i32 s10, 5
	v_mad_u64_u32 v[66:67], s[4:5], v67, s22, v[66:67]
	v_and_b32_e32 v204, 15, v172
	v_lshrrev_b32_e32 v205, 1, v172
	v_and_or_b32 v204, v205, s72, v204
	v_lshlrev_b32_e32 v205, 2, v172
	v_and_b32_e32 v206, 0x30, v172
	v_and_b32_e32 v205, 0x100, v205
	v_or_b32_e32 v205, v205, v206
	v_mad_u32_u24 v66, v204, s22, v205
	ds_write_b128 v66, v[0:3]
	ds_write_b128 v66, v[4:7] offset:64
	ds_write_b128 v66, v[8:11] offset:128
	ds_write_b128 v66, v[12:15] offset:192
	ds_write_b128 v66, v[16:19] offset:8448
	ds_write_b128 v66, v[20:23] offset:8512
	ds_write_b128 v66, v[24:27] offset:8576
	ds_write_b128 v66, v[28:31] offset:8640
	ds_write_b128 v66, v[32:35] offset:16896
	ds_write_b128 v66, v[36:39] offset:16960
	ds_write_b128 v66, v[40:43] offset:17024
	ds_write_b128 v66, v[44:47] offset:17088
	ds_write_b128 v66, v[48:51] offset:25344
	ds_write_b128 v66, v[52:55] offset:25408
	ds_write_b128 v66, v[56:59] offset:25472
	ds_write_b128 v66, v[60:63] offset:25536
	s_waitcnt lgkmcnt(0)
	s_barrier
	s_cbranch_scc1 .LBB0_623
	s_lshl_b32 s16, s7, 13
	s_cmp_lg_u32 s10, 5
	v_readlane_b32 s4, v229, 10
	s_cselect_b64 s[8:9], -1, 0
	s_cmp_eq_u32 s10, 5
	v_readlane_b32 s5, v229, 11
	s_cselect_b32 s4, 0, s4
	s_cselect_b32 s5, 0, s5
	s_cmp_gt_i32 s10, 2
	s_cselect_b32 s11, s5, s25
	s_cselect_b32 s10, s4, s24
	s_ashr_i32 s7, s6, 31
	s_lshl_b64 s[4:5], s[6:7], 1
	s_add_u32 s4, s66, s4
	s_addc_u32 s5, s67, s5
	v_lshlrev_b32_e32 v144, 3, v64
	v_ashrrev_i32_e32 v2, 5, v150
	v_lshl_add_u64 v[0:1], s[4:5], 0, v[144:145]
	s_add_i32 s4, s12, s13
	v_mul_lo_u32 v4, v2, s22
	s_sub_i32 s4, s4, s14
	v_lshl_add_u32 v6, v64, 4, v4
	v_add_u32_e32 v4, s29, v2
	s_lshl_b32 s4, s4, 10
	v_add_u32_e32 v8, s4, v4
	s_or_b32 s4, s29, s4
	v_ashrrev_i32_e32 v3, 31, v2
	s_ashr_i32 s5, s4, 31
	v_lshlrev_b32_e32 v7, 2, v2
	v_lshl_add_u64 v[2:3], v[2:3], 0, s[4:5]
	v_lshl_add_u64 v[2:3], v[2:3], 3, s[10:11]
	s_mov_b64 s[4:5], 0x80
	v_lshl_add_u64 v[2:3], v[2:3], 0, s[4:5]
	s_lshl_b32 s4, s12, 10
	s_add_i32 s4, s4, s16
	v_add_u32_e32 v4, s4, v4
	s_lshl_b32 s4, s14, 10
	s_mov_b32 s15, 0
	v_cmp_eq_u32_e64 s[42:43], 0, v64
	v_subrev_u32_e32 v9, s4, v4
	s_branch .LBB0_634

; DI int otid() { int t = threadIdx.x; asm volatile("" : "+v"(t)); return t; }
; template <bool SWAP, bool HALF>
; DI void gemm_mainloop(const GemmDesc& d, int m0, int n0, bf16_t* smem, f32x16 (&acc)[2][2], int dry) {
;   const int t = otid(), lane = t & 63, w = t >> 6, wm = w >> 1, wn = w & 1, r = lane & 31, hh = lane >> 5;
;   const int lrow = t >> 3, lkc = t & 7;
;   const bf16_t* ap[4]; const bf16_t* bp[4];
; #pragma unroll
;   for (int i = 0; i < 4; ++i) {
;     int am = m0 + lrow + 32 * i; am = am < M ? am : M - 1;
;     ap[i] = d.A + (size_t)am * d.lda + lkc * 8 + (d.a_grp ? (n0 / d.a_grp) * d.a_grp : 0);
;     bp[i] = d.Bt + (size_t)(n0 + lrow + 32 * i) * d.ldb + lkc * 8;
;   }
; #pragma unroll
;   for (int a = 0; a < 2; ++a)
; #pragma unroll
;     for (int b = 0; b < 2; ++b)
; #pragma unroll
;       for (int i = 0; i < 16; ++i) acc[a][b][i] = 0.f;
;   u32x4 ra0[4], rb0[4], ra1[4], rb1[4];
;   const int nk = d.K >> 6;
;   const int lds_w = lrow * LST + lkc * 8;
;     ...
;   gl(ra0, rb0, 0);
;   gl(ra1, rb1, 1);
;   lw(ra0, rb0, 0);
;   gl(ra0, rb0, 2);
;   __syncthreads();
;   ldf(0, 0, 0);
.LBB0_1002:
	s_or_b64 exec, exec, s[4:5]
	s_lshl_b32 s1, s14, 7
	s_and_b32 s4, s14, -8
	s_waitcnt vmcnt(0)
	v_ashrrev_i32_e32 v187, 7, v150
	v_bfe_u32 v188, v150, 6, 1
	v_and_b32_e32 v170, 31, v150
	v_bfe_u32 v189, v150, 5, 1
	s_cmp_lg_u32 s4, 16
	s_mov_b64 s[4:5], -1
	s_cbranch_scc0 .LBB0_1018
	v_mov_b32_e32 v32, v172
	v_readlane_b32 s76, v228, 60
	v_ashrrev_i32_e32 v10, 3, v32
	v_lshlrev_b32_e32 v0, 3, v32
	v_and_b32_e32 v33, 56, v0
	v_add_u32_e32 v2, s1, v10
	v_lshlrev_b32_e32 v144, 1, v33
	v_readlane_b32 s78, v228, 62
	v_readlane_b32 s79, v228, 63
	v_ashrrev_i32_e32 v3, 31, v2
	v_add_u32_e32 v11, s9, v10
	v_lshl_add_u64 v[4:5], s[78:79], 0, v[144:145]
	v_lshlrev_b64 v[2:3], 11, v[2:3]
	v_lshl_add_u64 v[154:155], v[4:5], 0, v[2:3]
	v_min_i32_e32 v2, 0x801f, v11
	v_ashrrev_i32_e32 v3, 31, v2
	v_lshl_add_u64 v[0:1], s[56:57], 0, v[144:145]
	v_lshlrev_b64 v[2:3], 11, v[2:3]
	v_lshl_add_u64 v[8:9], v[0:1], 0, v[2:3]
	v_min_i32_e32 v2, 0x7fff, v11
	v_ashrrev_i32_e32 v3, 31, v2
	v_min_i32_e32 v6, 0x803f, v11
	v_lshlrev_b64 v[2:3], 11, v[2:3]
	v_ashrrev_i32_e32 v7, 31, v6
	v_lshl_add_u64 v[16:17], v[0:1], 0, v[2:3]
	v_min_i32_e32 v2, 0x7fdf, v11
	v_lshlrev_b64 v[6:7], 11, v[6:7]
	v_ashrrev_i32_e32 v3, 31, v2
	v_lshl_add_u64 v[152:153], v[0:1], 0, v[6:7]
	v_lshlrev_b64 v[2:3], 11, v[2:3]
	v_lshl_add_u64 v[24:25], v[0:1], 0, v[2:3]
	s_mov_b64 s[4:5], 0x10000
	v_lshl_add_u64 v[156:157], v[8:9], 0, s[4:5]
	v_lshl_add_u64 v[158:159], v[154:155], 0, s[4:5]
	s_mov_b64 s[4:5], 0x20000
	v_lshl_add_u64 v[160:161], v[16:17], 0, s[4:5]
	v_lshl_add_u64 v[162:163], v[154:155], 0, s[4:5]
	s_mov_b64 s[4:5], 0x30000
	v_lshl_add_u64 v[164:165], v[24:25], 0, s[4:5]
	v_lshl_add_u64 v[166:167], v[154:155], 0, s[4:5]
	s_movk_i32 s4, 0x48
	v_and_b32_e32 v34, 31, v32
	v_mul_lo_u32 v35, v10, s4
	v_readlane_b32 s77, v228, 61
	v_readlane_b32 s80, v223, 0
	v_readlane_b32 s81, v223, 1
	v_readlane_b32 s82, v223, 2
	v_readlane_b32 s83, v223, 3
	v_readlane_b32 s84, v223, 4
	v_readlane_b32 s85, v223, 5
	v_readlane_b32 s86, v223, 6
	v_readlane_b32 s87, v223, 7
	v_readlane_b32 s88, v223, 8
	v_readlane_b32 s89, v223, 9
	v_readlane_b32 s90, v223, 10
	v_readlane_b32 s91, v223, 11
	s_mov_b32 s4, 0x10000
	v_add_co_u32_e32 v8, vcc, s4, v8
	s_nop 1
	v_addc_co_u32_e32 v9, vcc, 0, v9, vcc
	v_add_co_u32_e32 v12, vcc, s4, v154
	s_nop 1
	v_addc_co_u32_e32 v13, vcc, 0, v155, vcc
	s_mov_b32 s4, 0x20000
	v_add_co_u32_e32 v16, vcc, s4, v16
	s_nop 1
	v_addc_co_u32_e32 v17, vcc, 0, v17, vcc
	v_add_co_u32_e32 v20, vcc, s4, v154
	s_nop 1
	v_addc_co_u32_e32 v21, vcc, 0, v155, vcc
	s_mov_b32 s4, 0x30000
	v_add_co_u32_e32 v24, vcc, s4, v24
	s_nop 1
	v_addc_co_u32_e32 v25, vcc, 0, v25, vcc
	v_add_co_u32_e32 v28, vcc, s4, v154
	s_nop 1
	v_addc_co_u32_e32 v29, vcc, 0, v155, vcc
	s_nop 0
	v_add_lshl_u32 v144, v35, v33, 1
	s_waitcnt vmcnt(15)
	s_waitcnt vmcnt(14)
	s_waitcnt vmcnt(13)
	s_waitcnt vmcnt(12)
	s_waitcnt vmcnt(11)
	s_waitcnt vmcnt(10)
	s_waitcnt vmcnt(9)
	s_waitcnt vmcnt(8)
	v_lshrrev_b32_e32 v0, 1, v32
	v_and_or_b32 v1, v0, s72, v34
	v_and_b32_e32 v0, 16, v0
	s_movk_i32 s4, 0x90
	v_mad_u64_u32 v[168:169], s[4:5], v1, s4, v[0:1]
	v_and_b32_e32 v1, 0x5f, v32
	v_mul_u32_u24_e32 v1, 0x48, v1
	v_lshl_add_u32 v169, v1, 1, v0
	v_bfe_u32 v204, v172, 4, 3
	v_lshlrev_b32_e32 v204, 4, v204
	v_xor_b32_e32 v152, v152, v204
	v_xor_b32_e32 v154, v154, v204
	v_xor_b32_e32 v156, v156, v204
	v_xor_b32_e32 v158, v158, v204
	v_xor_b32_e32 v160, v160, v204
	v_xor_b32_e32 v162, v162, v204
	v_xor_b32_e32 v164, v164, v204
	v_xor_b32_e32 v166, v166, v204
	v_lshrrev_b32_e32 v205, 6, v172
	s_nop 1
	v_readfirstlane_b32 s101, v205
	s_lshl_b32 s101, s101, 10
	s_add_u32 m0, s101, 0x0
	s_nop 0
	global_load_lds_dwordx4 v[152:153], off
	s_add_u32 m0, s101, 0x4000
	s_nop 0
	global_load_lds_dwordx4 v[154:155], off
	s_add_u32 m0, s101, 0x1000
	s_nop 0
	global_load_lds_dwordx4 v[156:157], off
	s_add_u32 m0, s101, 0x5000
	s_nop 0
	global_load_lds_dwordx4 v[158:159], off
	s_add_u32 m0, s101, 0x2000
	s_nop 0
	global_load_lds_dwordx4 v[160:161], off
	s_add_u32 m0, s101, 0x6000
	s_nop 0
	global_load_lds_dwordx4 v[162:163], off
	s_add_u32 m0, s101, 0x3000
	s_nop 0
	global_load_lds_dwordx4 v[164:165], off
	s_add_u32 m0, s101, 0x7000
	s_nop 0
	global_load_lds_dwordx4 v[166:167], off
	v_and_b32_e32 v204, 15, v172
	v_bfe_u32 v205, v172, 4, 2
	v_lshrrev_b32_e32 v206, 1, v204
	v_xor_b32_e32 v205, v205, v206
	v_lshlrev_b32_e32 v205, 4, v205
	v_lshl_or_b32 v204, v204, 7, v205
	v_lshrrev_b32_e32 v206, 7, v172
	v_lshl_add_u32 v168, v206, 13, v204
	v_bfe_u32 v206, v172, 6, 1
	v_lshl_add_u32 v169, v206, 13, v204
	v_add_u32_e32 v169, 0x4000, v169
	v_xor_b32_e32 v220, 64, v168
	v_xor_b32_e32 v221, 64, v169
	s_waitcnt vmcnt(0)
	s_waitcnt lgkmcnt(0)
	s_barrier
	v_mov_b32_e32 v0, 0
	v_add_u32_e32 v190, 0x9000, v144
	s_mov_b32 s4, -2
	v_mov_b32_e32 v1, v0
	v_mov_b32_e32 v2, v0
	v_mov_b32_e32 v3, v0
	v_mov_b32_e32 v4, v0
	v_mov_b32_e32 v5, v0
	v_mov_b32_e32 v6, v0
	v_mov_b32_e32 v7, v0
	v_mov_b32_e32 v8, v0
	v_mov_b32_e32 v9, v0
	v_mov_b32_e32 v10, v0
	v_mov_b32_e32 v11, v0
	v_mov_b32_e32 v12, v0
	v_mov_b32_e32 v13, v0
	v_mov_b32_e32 v14, v0
	v_mov_b32_e32 v15, v0
	v_mov_b32_e32 v16, v0
	v_mov_b32_e32 v17, v0
	v_mov_b32_e32 v18, v0
	v_mov_b32_e32 v19, v0
	v_mov_b32_e32 v20, v0
	v_mov_b32_e32 v21, v0
	v_mov_b32_e32 v22, v0
	v_mov_b32_e32 v23, v0
	v_mov_b32_e32 v24, v0
	v_mov_b32_e32 v25, v0
	v_mov_b32_e32 v26, v0
	v_mov_b32_e32 v27, v0
	v_mov_b32_e32 v28, v0
	v_mov_b32_e32 v29, v0
	v_mov_b32_e32 v30, v0
	v_mov_b32_e32 v31, v0
	v_mov_b32_e32 v32, v0
	v_mov_b32_e32 v33, v0
	v_mov_b32_e32 v34, v0
	v_mov_b32_e32 v35, v0
	v_mov_b32_e32 v36, v0
	v_mov_b32_e32 v37, v0
	v_mov_b32_e32 v38, v0
	v_mov_b32_e32 v39, v0
	v_mov_b32_e32 v40, v0
	v_mov_b32_e32 v41, v0
	v_mov_b32_e32 v42, v0
	v_mov_b32_e32 v43, v0
	v_mov_b32_e32 v44, v0
	v_mov_b32_e32 v45, v0
	v_mov_b32_e32 v46, v0
	v_mov_b32_e32 v47, v0
	v_mov_b32_e32 v48, v0
	v_mov_b32_e32 v49, v0
	v_mov_b32_e32 v50, v0
	v_mov_b32_e32 v51, v0
	v_mov_b32_e32 v52, v0
	v_mov_b32_e32 v53, v0
	v_mov_b32_e32 v54, v0
	v_mov_b32_e32 v55, v0
	v_mov_b32_e32 v56, v0
	v_mov_b32_e32 v57, v0
	v_mov_b32_e32 v58, v0
	v_mov_b32_e32 v59, v0
	v_mov_b32_e32 v60, v0
	v_mov_b32_e32 v61, v0
	v_mov_b32_e32 v62, v0
	v_mov_b32_e32 v63, v0
; #define MFMA32(a, b, c) __builtin_amdgcn_mfma_f32_32x32x16_bf16((a), (b), (c), 0, 0, 0)
; #define SB_ __builtin_amdgcn_sched_barrier(0)
; template <bool SWAP, bool HALF>
; DI void gemm_mainloop(const GemmDesc& d, int m0, int n0, bf16_t* smem, f32x16 (&acc)[2][2], int dry) {
;     ...
;   auto ldf = [&](int buf, int kk, int set) {
;     const bf16_t* Ab = smem + buf * 2 * TILE_EL + ((HALF ? 0 : wm * 64) + r) * LST + 8 * hh + kk * 16;
;     const bf16_t* Bb = smem + buf * 2 * TILE_EL + TILE_EL + ((HALF ? w * 32 : wn * 64) + r) * LST + 8 * hh + kk * 16;
; #pragma unroll
;     for (int i = 0; i < 2; ++i) { fa[set][i] = *(const bf16x8*)(Ab + i * 32 * LST); if (!HALF || i == 0) fb[set][i] = *(const bf16x8*)(Bb + i * 32 * LST); }
;   };
;   auto mma = [&](int set) {
; #pragma unroll
;     for (int a = 0; a < 2; ++a)
; #pragma unroll
;       for (int b = 0; b < (HALF ? 1 : 2); ++b) {
;         if (SWAP) acc[a][b] = MFMA32(fb[set][b], fa[set][a], acc[a][b]);
;         else      acc[a][b] = MFMA32(fa[set][a], fb[set][b], acc[a][b]);
;       }
;   };
;     ...
;   auto stage = [&](int cur, u32x4 (&ran)[4], u32x4 (&rbn)[4], int ks) {
;     ldf(cur, 1, 1); SB_;
;     mma(0); SB_;
;     ldf(cur, 2, 0); SB_;
;     lw(ran, rbn, cur ^ 1);
;     gl(ran, rbn, (ks + 3 < nk) ? ks + 3 : nk - 1);
;     SB_;
;     mma(1); SB_;
;     __syncthreads();
;     ldf(cur, 3, 1); SB_;
;     mma(0); SB_;
;     ldf(cur ^ 1, 0, 0);
;     SB_;
;     mma(1); SB_;
;     __syncthreads();
;   };
.LBB0_1004:
	ds_read_b128 v[64:67], v168 offset:0
	ds_read_b128 v[68:71], v168 offset:2048
	ds_read_b128 v[72:75], v168 offset:4096
	ds_read_b128 v[76:79], v168 offset:6144
	ds_read_b128 v[80:83], v169 offset:0
	ds_read_b128 v[84:87], v169 offset:2048
	ds_read_b128 v[88:91], v169 offset:4096
	ds_read_b128 v[92:95], v169 offset:6144
	ds_read_b128 v[96:99], v220 offset:0
	ds_read_b128 v[100:103], v220 offset:2048
	ds_read_b128 v[104:107], v220 offset:4096
	ds_read_b128 v[108:111], v220 offset:6144
	ds_read_b128 v[112:115], v221 offset:0
	ds_read_b128 v[116:119], v221 offset:2048
	ds_read_b128 v[120:123], v221 offset:4096
	ds_read_b128 v[124:127], v221 offset:6144
	s_add_i32 s4, s4, 2
	s_add_i32 s5, s4, 1
	s_min_u32 s5, s5, 15
	s_lshl_b32 s18, s5, 7
	s_add_u32 m0, s101, 0x8000
	v_lshl_add_u64 v[128:129], v[152:153], 0, s[18:19]
	global_load_lds_dwordx4 v[128:129], off
	s_add_u32 m0, s101, 0xc000
	v_lshl_add_u64 v[128:129], v[154:155], 0, s[18:19]
	global_load_lds_dwordx4 v[128:129], off
	s_add_u32 m0, s101, 0x9000
	v_lshl_add_u64 v[128:129], v[156:157], 0, s[18:19]
	global_load_lds_dwordx4 v[128:129], off
	s_add_u32 m0, s101, 0xd000
	v_lshl_add_u64 v[128:129], v[158:159], 0, s[18:19]
	global_load_lds_dwordx4 v[128:129], off
	s_add_u32 m0, s101, 0xa000
	v_lshl_add_u64 v[128:129], v[160:161], 0, s[18:19]
	global_load_lds_dwordx4 v[128:129], off
	s_add_u32 m0, s101, 0xe000
	v_lshl_add_u64 v[128:129], v[162:163], 0, s[18:19]
	global_load_lds_dwordx4 v[128:129], off
	s_add_u32 m0, s101, 0xb000
	v_lshl_add_u64 v[128:129], v[164:165], 0, s[18:19]
	global_load_lds_dwordx4 v[128:129], off
	s_add_u32 m0, s101, 0xf000
	v_lshl_add_u64 v[128:129], v[166:167], 0, s[18:19]
	global_load_lds_dwordx4 v[128:129], off
	s_waitcnt lgkmcnt(8)
	v_mfma_f32_16x16x32_bf16 v[0:3], v[80:83], v[64:67], v[0:3]
	v_mfma_f32_16x16x32_bf16 v[4:7], v[84:87], v[64:67], v[4:7]
	v_mfma_f32_16x16x32_bf16 v[8:11], v[88:91], v[64:67], v[8:11]
	v_mfma_f32_16x16x32_bf16 v[12:15], v[92:95], v[64:67], v[12:15]
	v_mfma_f32_16x16x32_bf16 v[16:19], v[80:83], v[68:71], v[16:19]
	v_mfma_f32_16x16x32_bf16 v[20:23], v[84:87], v[68:71], v[20:23]
	v_mfma_f32_16x16x32_bf16 v[24:27], v[88:91], v[68:71], v[24:27]
	v_mfma_f32_16x16x32_bf16 v[28:31], v[92:95], v[68:71], v[28:31]
	v_mfma_f32_16x16x32_bf16 v[32:35], v[80:83], v[72:75], v[32:35]
	v_mfma_f32_16x16x32_bf16 v[36:39], v[84:87], v[72:75], v[36:39]
	v_mfma_f32_16x16x32_bf16 v[40:43], v[88:91], v[72:75], v[40:43]
	v_mfma_f32_16x16x32_bf16 v[44:47], v[92:95], v[72:75], v[44:47]
	v_mfma_f32_16x16x32_bf16 v[48:51], v[80:83], v[76:79], v[48:51]
	v_mfma_f32_16x16x32_bf16 v[52:55], v[84:87], v[76:79], v[52:55]
	v_mfma_f32_16x16x32_bf16 v[56:59], v[88:91], v[76:79], v[56:59]
	v_mfma_f32_16x16x32_bf16 v[60:63], v[92:95], v[76:79], v[60:63]
	s_waitcnt lgkmcnt(0)
	v_mfma_f32_16x16x32_bf16 v[0:3], v[112:115], v[96:99], v[0:3]
	v_mfma_f32_16x16x32_bf16 v[4:7], v[116:119], v[96:99], v[4:7]
	v_mfma_f32_16x16x32_bf16 v[8:11], v[120:123], v[96:99], v[8:11]
	v_mfma_f32_16x16x32_bf16 v[12:15], v[124:127], v[96:99], v[12:15]
	v_mfma_f32_16x16x32_bf16 v[16:19], v[112:115], v[100:103], v[16:19]
	v_mfma_f32_16x16x32_bf16 v[20:23], v[116:119], v[100:103], v[20:23]
	v_mfma_f32_16x16x32_bf16 v[24:27], v[120:123], v[100:103], v[24:27]
	v_mfma_f32_16x16x32_bf16 v[28:31], v[124:127], v[100:103], v[28:31]
	v_mfma_f32_16x16x32_bf16 v[32:35], v[112:115], v[104:107], v[32:35]
	v_mfma_f32_16x16x32_bf16 v[36:39], v[116:119], v[104:107], v[36:39]
	v_mfma_f32_16x16x32_bf16 v[40:43], v[120:123], v[104:107], v[40:43]
	v_mfma_f32_16x16x32_bf16 v[44:47], v[124:127], v[104:107], v[44:47]
	v_mfma_f32_16x16x32_bf16 v[48:51], v[112:115], v[108:111], v[48:51]
	v_mfma_f32_16x16x32_bf16 v[52:55], v[116:119], v[108:111], v[52:55]
	v_mfma_f32_16x16x32_bf16 v[56:59], v[120:123], v[108:111], v[56:59]
	v_mfma_f32_16x16x32_bf16 v[60:63], v[124:127], v[108:111], v[60:63]
	s_waitcnt vmcnt(0)
	s_barrier
; DI float ssq_f(u64 v) { return (float)v * (1.f / 1048576.f); }
; #define SB_ __builtin_amdgcn_sched_barrier(0)
; template <bool SWAP, bool HALF>
; DI void gemm_mainloop(const GemmDesc& d, int m0, int n0, bf16_t* smem, f32x16 (&acc)[2][2], int dry) {
;     ...
;   auto stage = [&](int cur, u32x4 (&ran)[4], u32x4 (&rbn)[4], int ks) {
;     ldf(cur, 1, 1); SB_;
;     mma(0); SB_;
;     ldf(cur, 2, 0); SB_;
;     lw(ran, rbn, cur ^ 1);
;     gl(ran, rbn, (ks + 3 < nk) ? ks + 3 : nk - 1);
;     SB_;
;     mma(1); SB_;
;     __syncthreads();
;     ldf(cur, 3, 1); SB_;
;     mma(0); SB_;
;     ldf(cur ^ 1, 0, 0);
;     SB_;
;     mma(1); SB_;
;     __syncthreads();
;   };
; DI void gemm_tile(const GemmDesc& d, int m0, int n0, bf16_t* smem, int dry) {
;     ...
;   u32x2 hpre[16];
;   if (d.epi == EPI_RESID) {
; #pragma unroll
;     for (int pass = 0; pass < 16; ++pass) {
;       int m = m0 + pass * 8 + (t >> 5); m = m < M ? m : M - 1;
;       hpre[pass] = *(const u32x2*)(d.hb + (size_t)m * D + d.c_off + n0 + (t & 31) * 4);
;     }
;   } else if (t < 128) {
;     rs_s[t] = rsqrtf(ssq_f(myss) * d.inv_dim + EPS);
;   }
;   if (half) {
; #pragma unroll
;     for (int a = 0; a < 2; ++a)
; #pragma unroll
;       for (int g = 0; g < 4; ++g) {
;         f32x4 o;
; #pragma unroll
;         for (int j = 0; j < 4; ++j) o[j] = acc[a][0][4 * g + j];
;         *(f32x4*)(Ct + (a * 32 + r) * CS + w * 32 + 8 * g + 4 * hh) = o;
;       }
;   } else {
; #pragma unroll
;     for (int a = 0; a < 2; ++a)
; #pragma unroll
;       for (int b = 0; b < 2; ++b)
; #pragma unroll
;         for (int g = 0; g < 4; ++g) {
;           f32x4 o;
; #pragma unroll
;           for (int j = 0; j < 4; ++j) o[j] = acc[a][b][4 * g + j];
;           *(f32x4*)(Ct + (wm * 64 + a * 32 + r) * CS + wn * 64 + b * 32 + 8 * g + 4 * hh) = o;
;         }
;   }
;   __syncthreads();
	ds_read_b128 v[64:67], v168 offset:32768
	ds_read_b128 v[68:71], v168 offset:34816
	ds_read_b128 v[72:75], v168 offset:36864
	ds_read_b128 v[76:79], v168 offset:38912
	ds_read_b128 v[80:83], v169 offset:32768
	ds_read_b128 v[84:87], v169 offset:34816
	ds_read_b128 v[88:91], v169 offset:36864
	ds_read_b128 v[92:95], v169 offset:38912
	ds_read_b128 v[96:99], v220 offset:32768
	ds_read_b128 v[100:103], v220 offset:34816
	ds_read_b128 v[104:107], v220 offset:36864
	ds_read_b128 v[108:111], v220 offset:38912
	ds_read_b128 v[112:115], v221 offset:32768
	ds_read_b128 v[116:119], v221 offset:34816
	ds_read_b128 v[120:123], v221 offset:36864
	ds_read_b128 v[124:127], v221 offset:38912
	s_add_i32 s5, s4, 2
	s_min_u32 s5, s5, 15
	s_lshl_b32 s18, s5, 7
	s_add_u32 m0, s101, 0x0
	v_lshl_add_u64 v[128:129], v[152:153], 0, s[18:19]
	global_load_lds_dwordx4 v[128:129], off
	s_add_u32 m0, s101, 0x4000
	v_lshl_add_u64 v[128:129], v[154:155], 0, s[18:19]
	global_load_lds_dwordx4 v[128:129], off
	s_add_u32 m0, s101, 0x1000
	v_lshl_add_u64 v[128:129], v[156:157], 0, s[18:19]
	global_load_lds_dwordx4 v[128:129], off
	s_add_u32 m0, s101, 0x5000
	v_lshl_add_u64 v[128:129], v[158:159], 0, s[18:19]
	global_load_lds_dwordx4 v[128:129], off
	s_add_u32 m0, s101, 0x2000
	v_lshl_add_u64 v[128:129], v[160:161], 0, s[18:19]
	global_load_lds_dwordx4 v[128:129], off
	s_add_u32 m0, s101, 0x6000
	v_lshl_add_u64 v[128:129], v[162:163], 0, s[18:19]
	global_load_lds_dwordx4 v[128:129], off
	s_add_u32 m0, s101, 0x3000
	v_lshl_add_u64 v[128:129], v[164:165], 0, s[18:19]
	global_load_lds_dwordx4 v[128:129], off
	s_add_u32 m0, s101, 0x7000
	v_lshl_add_u64 v[128:129], v[166:167], 0, s[18:19]
	global_load_lds_dwordx4 v[128:129], off
	s_waitcnt lgkmcnt(8)
	v_mfma_f32_16x16x32_bf16 v[0:3], v[80:83], v[64:67], v[0:3]
	v_mfma_f32_16x16x32_bf16 v[4:7], v[84:87], v[64:67], v[4:7]
	v_mfma_f32_16x16x32_bf16 v[8:11], v[88:91], v[64:67], v[8:11]
	v_mfma_f32_16x16x32_bf16 v[12:15], v[92:95], v[64:67], v[12:15]
	v_mfma_f32_16x16x32_bf16 v[16:19], v[80:83], v[68:71], v[16:19]
	v_mfma_f32_16x16x32_bf16 v[20:23], v[84:87], v[68:71], v[20:23]
	v_mfma_f32_16x16x32_bf16 v[24:27], v[88:91], v[68:71], v[24:27]
	v_mfma_f32_16x16x32_bf16 v[28:31], v[92:95], v[68:71], v[28:31]
	v_mfma_f32_16x16x32_bf16 v[32:35], v[80:83], v[72:75], v[32:35]
	v_mfma_f32_16x16x32_bf16 v[36:39], v[84:87], v[72:75], v[36:39]
	v_mfma_f32_16x16x32_bf16 v[40:43], v[88:91], v[72:75], v[40:43]
	v_mfma_f32_16x16x32_bf16 v[44:47], v[92:95], v[72:75], v[44:47]
	v_mfma_f32_16x16x32_bf16 v[48:51], v[80:83], v[76:79], v[48:51]
	v_mfma_f32_16x16x32_bf16 v[52:55], v[84:87], v[76:79], v[52:55]
	v_mfma_f32_16x16x32_bf16 v[56:59], v[88:91], v[76:79], v[56:59]
	v_mfma_f32_16x16x32_bf16 v[60:63], v[92:95], v[76:79], v[60:63]
	s_waitcnt lgkmcnt(0)
	v_mfma_f32_16x16x32_bf16 v[0:3], v[112:115], v[96:99], v[0:3]
	v_mfma_f32_16x16x32_bf16 v[4:7], v[116:119], v[96:99], v[4:7]
	v_mfma_f32_16x16x32_bf16 v[8:11], v[120:123], v[96:99], v[8:11]
	v_mfma_f32_16x16x32_bf16 v[12:15], v[124:127], v[96:99], v[12:15]
	v_mfma_f32_16x16x32_bf16 v[16:19], v[112:115], v[100:103], v[16:19]
	v_mfma_f32_16x16x32_bf16 v[20:23], v[116:119], v[100:103], v[20:23]
	v_mfma_f32_16x16x32_bf16 v[24:27], v[120:123], v[100:103], v[24:27]
	v_mfma_f32_16x16x32_bf16 v[28:31], v[124:127], v[100:103], v[28:31]
	v_mfma_f32_16x16x32_bf16 v[32:35], v[112:115], v[104:107], v[32:35]
	v_mfma_f32_16x16x32_bf16 v[36:39], v[116:119], v[104:107], v[36:39]
	v_mfma_f32_16x16x32_bf16 v[40:43], v[120:123], v[104:107], v[40:43]
	v_mfma_f32_16x16x32_bf16 v[44:47], v[124:127], v[104:107], v[44:47]
	v_mfma_f32_16x16x32_bf16 v[48:51], v[112:115], v[108:111], v[48:51]
	v_mfma_f32_16x16x32_bf16 v[52:55], v[116:119], v[108:111], v[52:55]
	v_mfma_f32_16x16x32_bf16 v[56:59], v[120:123], v[108:111], v[56:59]
	v_mfma_f32_16x16x32_bf16 v[60:63], v[124:127], v[108:111], v[60:63]
	s_cmp_lt_u32 s4, 14
	s_waitcnt vmcnt(0)
	s_barrier
	s_cbranch_scc1 .LBB0_1004
	s_and_saveexec_b64 s[4:5], s[42:43]
	s_cbranch_execz .LBB0_1007
	s_mov_b32 s15, 0x800000
	s_waitcnt vmcnt(15)
	v_mul_f32_e32 v64, 0x4b800000, v171
	v_cmp_gt_f32_e32 vcc, s15, v171
	v_lshl_add_u32 v65, v150, 2, v181
	s_nop 0
	v_cndmask_b32_e32 v64, v171, v64, vcc
	v_rsq_f32_e32 v64, v64
	s_nop 0
	v_mul_f32_e32 v66, 0x45800000, v64
	v_cndmask_b32_e32 v64, v64, v66, vcc
	ds_write_b32 v65, v64
.LBB0_1007:
	s_or_b64 exec, exec, s[4:5]
	s_waitcnt vmcnt(15)
	v_lshlrev_b32_e32 v64, 4, v189
	v_lshl_or_b32 v65, v187, 6, v170
	v_lshl_or_b32 v64, v188, 8, v64
	v_mad_u64_u32 v[64:65], s[4:5], v65, s22, v[64:65]
	s_cmp_lt_i32 s14, 16
	s_mov_b64 s[4:5], -1
	v_and_b32_e32 v204, 15, v172
	v_lshrrev_b32_e32 v205, 1, v172
	v_and_or_b32 v204, v205, s72, v204
	v_lshlrev_b32_e32 v205, 2, v172
	v_and_b32_e32 v206, 0x30, v172
	v_and_b32_e32 v205, 0x100, v205
	v_or_b32_e32 v205, v205, v206
	v_mad_u32_u24 v64, v204, s22, v205
	ds_write_b128 v64, v[0:3]
	ds_write_b128 v64, v[4:7] offset:64
	ds_write_b128 v64, v[8:11] offset:128
	ds_write_b128 v64, v[12:15] offset:192
	ds_write_b128 v64, v[16:19] offset:8448
	ds_write_b128 v64, v[20:23] offset:8512
	ds_write_b128 v64, v[24:27] offset:8576
	ds_write_b128 v64, v[28:31] offset:8640
	ds_write_b128 v64, v[32:35] offset:16896
	ds_write_b128 v64, v[36:39] offset:16960
	ds_write_b128 v64, v[40:43] offset:17024
	ds_write_b128 v64, v[44:47] offset:17088
	ds_write_b128 v64, v[48:51] offset:25344
	ds_write_b128 v64, v[52:55] offset:25408
	ds_write_b128 v64, v[56:59] offset:25472
	ds_write_b128 v64, v[60:63] offset:25536
	s_waitcnt lgkmcnt(0)
	s_barrier
	s_cbranch_scc0 .LBB0_1020
	s_lshl_b32 s15, s12, 13
	s_cmp_lt_i32 s14, 8
	s_cselect_b32 s4, 0, 0xfffffc00
	s_cselect_b32 s5, 0, 0x4020000
	s_add_i32 s4, s4, s1
	s_add_u32 s14, s68, s5
	s_addc_u32 s16, s69, 0
	s_ashr_i32 s5, s4, 31
	s_lshl_b64 s[4:5], s[4:5], 1
	s_add_u32 s4, s14, s4
	s_addc_u32 s5, s16, s5
	v_lshlrev_b32_e32 v144, 3, v170
	v_ashrrev_i32_e32 v2, 5, v150
	v_lshl_add_u64 v[0:1], s[4:5], 0, v[144:145]
	s_add_i32 s4, s10, s11
	v_mul_lo_u32 v3, v2, s22
	v_lshlrev_b32_e32 v5, 2, v2
	v_add_u32_e32 v2, s29, v2
	s_sub_i32 s4, s4, s13
	v_lshl_add_u32 v6, s4, 10, v2
	s_lshl_b32 s4, s10, 10
	s_add_i32 s4, s4, s15
	v_add_u32_e32 v2, s4, v2
	s_lshl_b32 s4, s13, 10
	s_mov_b32 s12, 0
	v_lshl_add_u32 v4, v170, 4, v3
	v_subrev_u32_e32 v7, s4, v2
	s_branch .LBB0_1010

; DI int otid() { int t = threadIdx.x; asm volatile("" : "+v"(t)); return t; }
; template <bool SWAP, bool HALF>
; DI void gemm_mainloop(const GemmDesc& d, int m0, int n0, bf16_t* smem, f32x16 (&acc)[2][2], int dry) {
;   const int t = otid(), lane = t & 63, w = t >> 6, wm = w >> 1, wn = w & 1, r = lane & 31, hh = lane >> 5;
;   const int lrow = t >> 3, lkc = t & 7;
;   const bf16_t* ap[4]; const bf16_t* bp[4];
; #pragma unroll
;   for (int i = 0; i < 4; ++i) {
;     int am = m0 + lrow + 32 * i; am = am < M ? am : M - 1;
;     ap[i] = d.A + (size_t)am * d.lda + lkc * 8 + (d.a_grp ? (n0 / d.a_grp) * d.a_grp : 0);
;     bp[i] = d.Bt + (size_t)(n0 + lrow + 32 * i) * d.ldb + lkc * 8;
;   }
; #pragma unroll
;   for (int a = 0; a < 2; ++a)
; #pragma unroll
;     for (int b = 0; b < 2; ++b)
; #pragma unroll
;       for (int i = 0; i < 16; ++i) acc[a][b][i] = 0.f;
;   u32x4 ra0[4], rb0[4], ra1[4], rb1[4];
;   const int nk = d.K >> 6;
;   const int lds_w = lrow * LST + lkc * 8;
;     ...
;     const int g = i / (8 * nN), j = i - g * 8 * nN;
;     const int gm = (cx - g * 8) < 8 ? (cx - g * 8) : 8;
;     const int mt = (g * 8 + j % gm) * 8 + x, nt = j / gm;
;     gemm_tile(d, mt * 128, nt * 128, smem, dry);
.LBB0_1218:
	s_lshr_b32 s1, s8, 3
	s_and_b32 s1, s1, 0xffffff8
	v_readlane_b32 s5, v228, 38
	s_sub_i32 s5, s5, s1
	s_min_i32 s5, s5, 8
	s_abs_i32 s9, s5
	v_cvt_f32_u32_e32 v0, s9
	s_sub_i32 s10, 0, s9
	s_lshl_b32 s4, s1, 3
	s_sub_i32 s4, s8, s4
	v_rcp_iflag_f32_e32 v0, v0
	s_abs_i32 s7, s4
	s_xor_b32 s6, s4, s5
	s_ashr_i32 s6, s6, 31
	v_mul_f32_e32 v0, 0x4f7ffffe, v0
	v_cvt_u32_f32_e32 v0, v0
	v_mov_b32_e32 v150, v172
	v_mov_b32_e32 v32, v172
	v_readfirstlane_b32 s11, v0
	s_mul_i32 s10, s10, s11
	s_mul_hi_u32 s10, s11, s10
	s_add_i32 s11, s11, s10
	s_mul_hi_u32 s10, s7, s11
	s_mul_i32 s11, s10, s9
	s_sub_i32 s7, s7, s11
	s_add_i32 s11, s10, 1
	s_sub_i32 s12, s7, s9
	s_cmp_ge_u32 s7, s9
	s_cselect_b32 s10, s11, s10
	s_cselect_b32 s7, s12, s7
	s_add_i32 s11, s10, 1
	s_cmp_ge_u32 s7, s9
	s_cselect_b32 s7, s11, s10
	s_xor_b32 s7, s7, s6
	s_sub_i32 s6, s7, s6
	s_mul_i32 s5, s6, s5
	s_sub_i32 s4, s4, s5
	s_add_i32 s1, s1, s4
	s_lshl_b32 s4, s6, 7
	s_lshl_b32 s1, s1, 10
	v_ashrrev_i32_e32 v10, 3, v32
	v_lshlrev_b32_e32 v0, 3, v32
	v_and_b32_e32 v33, 56, v0
	v_add_u32_e32 v2, s4, v10
	v_readlane_b32 s76, v228, 60
	s_or_b32 s9, s1, s29
	v_lshlrev_b32_e32 v144, 1, v33
	v_readlane_b32 s80, v223, 0
	v_readlane_b32 s81, v223, 1
	v_ashrrev_i32_e32 v3, 31, v2
	v_add_u32_e32 v11, s9, v10
	v_lshl_add_u64 v[4:5], s[80:81], 0, v[144:145]
	v_lshlrev_b64 v[2:3], 11, v[2:3]
	v_lshl_add_u64 v[154:155], v[4:5], 0, v[2:3]
	v_min_i32_e32 v2, 0x801f, v11
	v_ashrrev_i32_e32 v3, 31, v2
	v_lshl_add_u64 v[0:1], s[68:69], 0, v[144:145]
	v_lshlrev_b64 v[2:3], 11, v[2:3]
	v_lshl_add_u64 v[8:9], v[0:1], 0, v[2:3]
	v_min_i32_e32 v2, 0x7fff, v11
	v_ashrrev_i32_e32 v3, 31, v2
	v_min_i32_e32 v6, 0x803f, v11
	v_lshlrev_b64 v[2:3], 11, v[2:3]
	v_ashrrev_i32_e32 v7, 31, v6
	v_lshl_add_u64 v[16:17], v[0:1], 0, v[2:3]
	v_min_i32_e32 v2, 0x7fdf, v11
	v_lshlrev_b64 v[6:7], 11, v[6:7]
	v_ashrrev_i32_e32 v3, 31, v2
	v_lshl_add_u64 v[152:153], v[0:1], 0, v[6:7]
	v_lshlrev_b64 v[2:3], 11, v[2:3]
	v_lshl_add_u64 v[24:25], v[0:1], 0, v[2:3]
	s_mov_b64 s[6:7], 0x10000
	v_lshl_add_u64 v[156:157], v[8:9], 0, s[6:7]
	v_lshl_add_u64 v[158:159], v[154:155], 0, s[6:7]
	s_mov_b64 s[6:7], 0x20000
	v_lshl_add_u64 v[160:161], v[16:17], 0, s[6:7]
	v_lshl_add_u64 v[162:163], v[154:155], 0, s[6:7]
	s_mov_b64 s[6:7], 0x30000
	s_movk_i32 s1, 0x48
	v_lshl_add_u64 v[164:165], v[24:25], 0, s[6:7]
	v_lshl_add_u64 v[166:167], v[154:155], 0, s[6:7]
	v_and_b32_e32 v34, 31, v32
	v_mul_lo_u32 v35, v10, s1
	v_readlane_b32 s77, v228, 61
	v_readlane_b32 s78, v228, 62
	v_readlane_b32 s79, v228, 63
	v_readlane_b32 s82, v223, 2
	v_readlane_b32 s83, v223, 3
	v_readlane_b32 s84, v223, 4
	v_readlane_b32 s85, v223, 5
	v_readlane_b32 s86, v223, 6
	v_readlane_b32 s87, v223, 7
	v_readlane_b32 s88, v223, 8
	v_readlane_b32 s89, v223, 9
	v_readlane_b32 s90, v223, 10
	v_readlane_b32 s91, v223, 11
	s_mov_b32 s1, 0x10000
	v_add_co_u32_e32 v8, vcc, s1, v8
	s_nop 1
	v_addc_co_u32_e32 v9, vcc, 0, v9, vcc
	s_waitcnt vmcnt(19)
	v_add_co_u32_e32 v12, vcc, s1, v154
	s_nop 1
	v_addc_co_u32_e32 v13, vcc, 0, v155, vcc
	s_mov_b32 s1, 0x20000
	v_add_co_u32_e32 v16, vcc, s1, v16
	s_nop 1
	v_addc_co_u32_e32 v17, vcc, 0, v17, vcc
	v_add_co_u32_e32 v20, vcc, s1, v154
	s_nop 1
	v_addc_co_u32_e32 v21, vcc, 0, v155, vcc
	s_mov_b32 s1, 0x30000
	v_add_co_u32_e32 v24, vcc, s1, v24
	s_nop 1
	v_addc_co_u32_e32 v25, vcc, 0, v25, vcc
	v_add_co_u32_e32 v28, vcc, s1, v154
	s_nop 1
	v_addc_co_u32_e32 v29, vcc, 0, v155, vcc
	s_nop 0
	v_add_lshl_u32 v144, v35, v33, 1
	s_waitcnt vmcnt(15)
	s_waitcnt vmcnt(14)
	s_waitcnt vmcnt(13)
	s_waitcnt vmcnt(12)
	s_waitcnt vmcnt(11)
	s_waitcnt vmcnt(10)
	s_waitcnt vmcnt(9)
	s_waitcnt vmcnt(8)
	v_lshrrev_b32_e32 v0, 1, v32
	v_and_or_b32 v1, v0, s72, v34
	v_and_b32_e32 v0, 16, v0
	s_movk_i32 s1, 0x90
	v_mad_u64_u32 v[168:169], s[6:7], v1, s1, v[0:1]
	v_and_b32_e32 v1, 0x5f, v32
	v_mul_u32_u24_e32 v1, 0x48, v1
	v_lshl_add_u32 v169, v1, 1, v0
	v_bfe_u32 v204, v172, 4, 3
	v_lshlrev_b32_e32 v204, 4, v204
	v_xor_b32_e32 v152, v152, v204
	v_xor_b32_e32 v154, v154, v204
	v_xor_b32_e32 v156, v156, v204
	v_xor_b32_e32 v158, v158, v204
	v_xor_b32_e32 v160, v160, v204
	v_xor_b32_e32 v162, v162, v204
	v_xor_b32_e32 v164, v164, v204
	v_xor_b32_e32 v166, v166, v204
	v_lshrrev_b32_e32 v205, 6, v172
	s_nop 1
	v_readfirstlane_b32 s101, v205
	s_lshl_b32 s101, s101, 10
	s_add_u32 m0, s101, 0x0
	s_nop 0
	global_load_lds_dwordx4 v[152:153], off
	s_add_u32 m0, s101, 0x4000
	s_nop 0
	global_load_lds_dwordx4 v[154:155], off
	s_add_u32 m0, s101, 0x1000
	s_nop 0
	global_load_lds_dwordx4 v[156:157], off
	s_add_u32 m0, s101, 0x5000
	s_nop 0
	global_load_lds_dwordx4 v[158:159], off
	s_add_u32 m0, s101, 0x2000
	s_nop 0
	global_load_lds_dwordx4 v[160:161], off
	s_add_u32 m0, s101, 0x6000
	s_nop 0
	global_load_lds_dwordx4 v[162:163], off
	s_add_u32 m0, s101, 0x3000
	s_nop 0
	global_load_lds_dwordx4 v[164:165], off
	s_add_u32 m0, s101, 0x7000
	s_nop 0
	global_load_lds_dwordx4 v[166:167], off
	v_and_b32_e32 v204, 15, v172
	v_bfe_u32 v205, v172, 4, 2
	v_lshrrev_b32_e32 v206, 1, v204
	v_xor_b32_e32 v205, v205, v206
	v_lshlrev_b32_e32 v205, 4, v205
	v_lshl_or_b32 v204, v204, 7, v205
	v_lshrrev_b32_e32 v206, 7, v172
	v_lshl_add_u32 v168, v206, 13, v204
	v_bfe_u32 v206, v172, 6, 1
	v_lshl_add_u32 v169, v206, 13, v204
	v_add_u32_e32 v169, 0x4000, v169
	v_xor_b32_e32 v220, 64, v168
	v_xor_b32_e32 v221, 64, v169
	s_waitcnt vmcnt(0)
	s_waitcnt lgkmcnt(0)
	s_barrier
	v_mov_b32_e32 v0, 0
	v_add_u32_e32 v170, 0x9000, v144
	s_mov_b32 s1, -2
	v_mov_b32_e32 v1, v0
	v_mov_b32_e32 v2, v0
	v_mov_b32_e32 v3, v0
	v_mov_b32_e32 v4, v0
	v_mov_b32_e32 v5, v0
	v_mov_b32_e32 v6, v0
	v_mov_b32_e32 v7, v0
	v_mov_b32_e32 v8, v0
	v_mov_b32_e32 v9, v0
	v_mov_b32_e32 v10, v0
	v_mov_b32_e32 v11, v0
	v_mov_b32_e32 v12, v0
	v_mov_b32_e32 v13, v0
	v_mov_b32_e32 v14, v0
	v_mov_b32_e32 v15, v0
	v_mov_b32_e32 v16, v0
	v_mov_b32_e32 v17, v0
	v_mov_b32_e32 v18, v0
	v_mov_b32_e32 v19, v0
	v_mov_b32_e32 v20, v0
	v_mov_b32_e32 v21, v0
	v_mov_b32_e32 v22, v0
	v_mov_b32_e32 v23, v0
	v_mov_b32_e32 v24, v0
	v_mov_b32_e32 v25, v0
	v_mov_b32_e32 v26, v0
	v_mov_b32_e32 v27, v0
	v_mov_b32_e32 v28, v0
	v_mov_b32_e32 v29, v0
	v_mov_b32_e32 v30, v0
	v_mov_b32_e32 v31, v0
	v_mov_b32_e32 v32, v0
	v_mov_b32_e32 v33, v0
	v_mov_b32_e32 v34, v0
	v_mov_b32_e32 v35, v0
	v_mov_b32_e32 v36, v0
	v_mov_b32_e32 v37, v0
	v_mov_b32_e32 v38, v0
	v_mov_b32_e32 v39, v0
	v_mov_b32_e32 v40, v0
	v_mov_b32_e32 v41, v0
	v_mov_b32_e32 v42, v0
	v_mov_b32_e32 v43, v0
	v_mov_b32_e32 v44, v0
	v_mov_b32_e32 v45, v0
	v_mov_b32_e32 v46, v0
	v_mov_b32_e32 v47, v0
	v_mov_b32_e32 v48, v0
	v_mov_b32_e32 v49, v0
	v_mov_b32_e32 v50, v0
	v_mov_b32_e32 v51, v0
	v_mov_b32_e32 v52, v0
	v_mov_b32_e32 v53, v0
	v_mov_b32_e32 v54, v0
	v_mov_b32_e32 v55, v0
	v_mov_b32_e32 v56, v0
	v_mov_b32_e32 v57, v0
	v_mov_b32_e32 v58, v0
	v_mov_b32_e32 v59, v0
	v_mov_b32_e32 v60, v0
	v_mov_b32_e32 v61, v0
	v_mov_b32_e32 v62, v0
	v_mov_b32_e32 v63, v0

; DI int otid() { int t = threadIdx.x; asm volatile("" : "+v"(t)); return t; }
; template <bool SWAP, bool HALF>
; DI void gemm_mainloop(const GemmDesc& d, int m0, int n0, bf16_t* smem, f32x16 (&acc)[2][2], int dry) {
;   const int t = otid(), lane = t & 63, w = t >> 6, wm = w >> 1, wn = w & 1, r = lane & 31, hh = lane >> 5;
;   const int lrow = t >> 3, lkc = t & 7;
;   const bf16_t* ap[4]; const bf16_t* bp[4];
; #pragma unroll
;   for (int i = 0; i < 4; ++i) {
;     int am = m0 + lrow + 32 * i; am = am < M ? am : M - 1;
;     ap[i] = d.A + (size_t)am * d.lda + lkc * 8 + (d.a_grp ? (n0 / d.a_grp) * d.a_grp : 0);
;     bp[i] = d.Bt + (size_t)(n0 + lrow + 32 * i) * d.ldb + lkc * 8;
;   }
; #pragma unroll
;   for (int a = 0; a < 2; ++a)
; #pragma unroll
;     for (int b = 0; b < 2; ++b)
; #pragma unroll
;       for (int i = 0; i < 16; ++i) acc[a][b][i] = 0.f;
;   u32x4 ra0[4], rb0[4], ra1[4], rb1[4];
;   const int nk = d.K >> 6;
;   const int lds_w = lrow * LST + lkc * 8;
;     ...
;   gl(ra0, rb0, 0);
;   gl(ra1, rb1, 1);
;   lw(ra0, rb0, 0);
;   gl(ra0, rb0, 2);
;   __syncthreads();
;   ldf(0, 0, 0);
.LBB0_1461:
	s_or_b64 exec, exec, s[4:5]
	v_mov_b32_e32 v32, v172
	s_mov_b64 s[4:5], 0x10000
	v_ashrrev_i32_e32 v10, 3, v32
	v_lshlrev_b32_e32 v0, 3, v32
	v_and_b32_e32 v33, 56, v0
	v_lshl_add_u32 v2, s13, 7, v10
	v_lshlrev_b32_e32 v144, 1, v33
	v_ashrrev_i32_e32 v3, 31, v2
	v_add_u32_e32 v11, s14, v10
	v_lshl_add_u64 v[4:5], s[6:7], 0, v[144:145]
	v_lshlrev_b64 v[2:3], 11, v[2:3]
	v_lshl_add_u64 v[154:155], v[4:5], 0, v[2:3]
	v_min_i32_e32 v2, 0x801f, v11
	v_ashrrev_i32_e32 v3, 31, v2
	v_lshl_add_u64 v[0:1], s[56:57], 0, v[144:145]
	v_lshlrev_b64 v[2:3], 11, v[2:3]
	v_lshl_add_u64 v[8:9], v[0:1], 0, v[2:3]
	v_min_i32_e32 v2, 0x7fff, v11
	v_ashrrev_i32_e32 v3, 31, v2
	v_min_i32_e32 v6, 0x803f, v11
	v_lshlrev_b64 v[2:3], 11, v[2:3]
	v_ashrrev_i32_e32 v7, 31, v6
	v_lshl_add_u64 v[16:17], v[0:1], 0, v[2:3]
	v_min_i32_e32 v2, 0x7fdf, v11
	v_lshlrev_b64 v[6:7], 11, v[6:7]
	v_ashrrev_i32_e32 v3, 31, v2
	v_lshl_add_u64 v[152:153], v[0:1], 0, v[6:7]
	v_lshlrev_b64 v[2:3], 11, v[2:3]
	v_lshl_add_u64 v[24:25], v[0:1], 0, v[2:3]
	v_lshl_add_u64 v[156:157], v[8:9], 0, s[4:5]
	v_lshl_add_u64 v[158:159], v[154:155], 0, s[4:5]
	s_mov_b64 s[4:5], 0x20000
	v_lshl_add_u64 v[160:161], v[16:17], 0, s[4:5]
	v_lshl_add_u64 v[162:163], v[154:155], 0, s[4:5]
	s_mov_b64 s[4:5], 0x30000
	v_lshl_add_u64 v[164:165], v[24:25], 0, s[4:5]
	v_lshl_add_u64 v[166:167], v[154:155], 0, s[4:5]
	s_movk_i32 s4, 0x48
	v_and_b32_e32 v34, 31, v32
	v_mul_lo_u32 v35, v10, s4
	s_mov_b32 s15, 0x10000
	v_add_co_u32_e64 v8, s[4:5], s15, v8
	s_mov_b32 s14, 0
	s_nop 0
	v_addc_co_u32_e64 v9, s[4:5], 0, v9, s[4:5]
	s_waitcnt vmcnt(19)
	v_add_co_u32_e64 v12, s[4:5], s15, v154
	s_nop 1
	v_addc_co_u32_e64 v13, s[4:5], 0, v155, s[4:5]
	s_mov_b32 s15, 0x20000
	v_add_co_u32_e64 v16, s[4:5], s15, v16
	s_nop 1
	v_addc_co_u32_e64 v17, s[4:5], 0, v17, s[4:5]
	v_add_co_u32_e64 v20, s[4:5], s15, v154
	s_nop 1
	v_addc_co_u32_e64 v21, s[4:5], 0, v155, s[4:5]
	s_mov_b32 s15, 0x30000
	v_add_co_u32_e64 v24, s[4:5], s15, v24
	s_nop 1
	v_addc_co_u32_e64 v25, s[4:5], 0, v25, s[4:5]
	v_add_co_u32_e64 v28, s[4:5], s15, v154
	s_nop 1
	v_addc_co_u32_e64 v29, s[4:5], 0, v155, s[4:5]
	s_nop 0
	v_add_lshl_u32 v144, v35, v33, 1
	s_waitcnt vmcnt(15)
	s_waitcnt vmcnt(14)
	s_waitcnt vmcnt(13)
	s_waitcnt vmcnt(12)
	s_waitcnt vmcnt(11)
	s_waitcnt vmcnt(10)
	s_waitcnt vmcnt(9)
	s_waitcnt vmcnt(8)
	v_lshrrev_b32_e32 v0, 1, v32
	v_and_or_b32 v1, v0, s72, v34
	v_and_b32_e32 v0, 16, v0
	s_movk_i32 s4, 0x90
	v_mad_u64_u32 v[168:169], s[4:5], v1, s4, v[0:1]
	v_and_b32_e32 v1, 0x5f, v32
	v_mul_u32_u24_e32 v1, 0x48, v1
	v_lshl_add_u32 v169, v1, 1, v0
	v_bfe_u32 v204, v172, 4, 3
	v_lshlrev_b32_e32 v204, 4, v204
	v_xor_b32_e32 v152, v152, v204
	v_xor_b32_e32 v154, v154, v204
	v_xor_b32_e32 v156, v156, v204
	v_xor_b32_e32 v158, v158, v204
	v_xor_b32_e32 v160, v160, v204
	v_xor_b32_e32 v162, v162, v204
	v_xor_b32_e32 v164, v164, v204
	v_xor_b32_e32 v166, v166, v204
	v_lshrrev_b32_e32 v205, 6, v172
	s_nop 1
	v_readfirstlane_b32 s101, v205
	s_lshl_b32 s101, s101, 10
	s_add_u32 m0, s101, 0x0
	s_nop 0
	global_load_lds_dwordx4 v[152:153], off
	s_add_u32 m0, s101, 0x4000
	s_nop 0
	global_load_lds_dwordx4 v[154:155], off
	s_add_u32 m0, s101, 0x1000
	s_nop 0
	global_load_lds_dwordx4 v[156:157], off
	s_add_u32 m0, s101, 0x5000
	s_nop 0
	global_load_lds_dwordx4 v[158:159], off
	s_add_u32 m0, s101, 0x2000
	s_nop 0
	global_load_lds_dwordx4 v[160:161], off
	s_add_u32 m0, s101, 0x6000
	s_nop 0
	global_load_lds_dwordx4 v[162:163], off
	s_add_u32 m0, s101, 0x3000
	s_nop 0
	global_load_lds_dwordx4 v[164:165], off
	s_add_u32 m0, s101, 0x7000
	s_nop 0
	global_load_lds_dwordx4 v[166:167], off
	v_and_b32_e32 v204, 15, v172
	v_bfe_u32 v205, v172, 4, 2
	v_lshrrev_b32_e32 v206, 1, v204
	v_xor_b32_e32 v205, v205, v206
	v_lshlrev_b32_e32 v205, 4, v205
	v_lshl_or_b32 v204, v204, 7, v205
	v_lshrrev_b32_e32 v206, 7, v172
	v_lshl_add_u32 v168, v206, 13, v204
	v_bfe_u32 v206, v172, 6, 1
	v_lshl_add_u32 v169, v206, 13, v204
	v_add_u32_e32 v169, 0x4000, v169
	v_xor_b32_e32 v220, 64, v168
	v_xor_b32_e32 v221, 64, v169
	s_waitcnt vmcnt(0)
	s_waitcnt lgkmcnt(0)
	s_barrier
	v_mov_b32_e32 v0, 0
	v_add_u32_e32 v171, 0x9000, v144
	v_mov_b32_e32 v1, v0
	v_mov_b32_e32 v2, v0
	v_mov_b32_e32 v3, v0
	v_mov_b32_e32 v4, v0
	v_mov_b32_e32 v5, v0
	v_mov_b32_e32 v6, v0
	v_mov_b32_e32 v7, v0
	v_mov_b32_e32 v8, v0
	v_mov_b32_e32 v9, v0
	v_mov_b32_e32 v10, v0
	v_mov_b32_e32 v11, v0
	v_mov_b32_e32 v12, v0
	v_mov_b32_e32 v13, v0
	v_mov_b32_e32 v14, v0
	v_mov_b32_e32 v15, v0
	v_mov_b32_e32 v16, v0
	v_mov_b32_e32 v17, v0
	v_mov_b32_e32 v18, v0
	v_mov_b32_e32 v19, v0
	v_mov_b32_e32 v20, v0
	v_mov_b32_e32 v21, v0
	v_mov_b32_e32 v22, v0
	v_mov_b32_e32 v23, v0
	v_mov_b32_e32 v24, v0
	v_mov_b32_e32 v25, v0
	v_mov_b32_e32 v26, v0
	v_mov_b32_e32 v27, v0
	v_mov_b32_e32 v28, v0
	v_mov_b32_e32 v29, v0
	v_mov_b32_e32 v30, v0
	v_mov_b32_e32 v31, v0
	v_mov_b32_e32 v32, v0
	v_mov_b32_e32 v33, v0
	v_mov_b32_e32 v34, v0
	v_mov_b32_e32 v35, v0
	v_mov_b32_e32 v36, v0
	v_mov_b32_e32 v37, v0
	v_mov_b32_e32 v38, v0
	v_mov_b32_e32 v39, v0
	v_mov_b32_e32 v40, v0
	v_mov_b32_e32 v41, v0
	v_mov_b32_e32 v42, v0
	v_mov_b32_e32 v43, v0
	v_mov_b32_e32 v44, v0
	v_mov_b32_e32 v45, v0
	v_mov_b32_e32 v46, v0
	v_mov_b32_e32 v47, v0
	v_mov_b32_e32 v48, v0
	v_mov_b32_e32 v49, v0
	v_mov_b32_e32 v50, v0
	v_mov_b32_e32 v51, v0
	v_mov_b32_e32 v52, v0
	v_mov_b32_e32 v53, v0
	v_mov_b32_e32 v54, v0
	v_mov_b32_e32 v55, v0
	v_mov_b32_e32 v56, v0
	v_mov_b32_e32 v57, v0
	v_mov_b32_e32 v58, v0
	v_mov_b32_e32 v59, v0
	v_mov_b32_e32 v60, v0
	v_mov_b32_e32 v61, v0
	v_mov_b32_e32 v62, v0
	v_mov_b32_e32 v63, v0
; #define MFMA32(a, b, c) __builtin_amdgcn_mfma_f32_32x32x16_bf16((a), (b), (c), 0, 0, 0)
; #define SB_ __builtin_amdgcn_sched_barrier(0)
; template <bool SWAP, bool HALF>
; DI void gemm_mainloop(const GemmDesc& d, int m0, int n0, bf16_t* smem, f32x16 (&acc)[2][2], int dry) {
;     ...
;   auto ldf = [&](int buf, int kk, int set) {
;     const bf16_t* Ab = smem + buf * 2 * TILE_EL + ((HALF ? 0 : wm * 64) + r) * LST + 8 * hh + kk * 16;
;     const bf16_t* Bb = smem + buf * 2 * TILE_EL + TILE_EL + ((HALF ? w * 32 : wn * 64) + r) * LST + 8 * hh + kk * 16;
; #pragma unroll
;     for (int i = 0; i < 2; ++i) { fa[set][i] = *(const bf16x8*)(Ab + i * 32 * LST); if (!HALF || i == 0) fb[set][i] = *(const bf16x8*)(Bb + i * 32 * LST); }
;   };
;   auto mma = [&](int set) {
; #pragma unroll
;     for (int a = 0; a < 2; ++a)
; #pragma unroll
;       for (int b = 0; b < (HALF ? 1 : 2); ++b) {
;         if (SWAP) acc[a][b] = MFMA32(fb[set][b], fa[set][a], acc[a][b]);
;         else      acc[a][b] = MFMA32(fa[set][a], fb[set][b], acc[a][b]);
;       }
;   };
;     ...
;   auto stage = [&](int cur, u32x4 (&ran)[4], u32x4 (&rbn)[4], int ks) {
;     ldf(cur, 1, 1); SB_;
;     mma(0); SB_;
;     ldf(cur, 2, 0); SB_;
;     lw(ran, rbn, cur ^ 1);
;     gl(ran, rbn, (ks + 3 < nk) ? ks + 3 : nk - 1);
;     SB_;
;     mma(1); SB_;
;     __syncthreads();
;     ldf(cur, 3, 1); SB_;
;     mma(0); SB_;
;     ldf(cur ^ 1, 0, 0);
;     SB_;
;     mma(1); SB_;
;     __syncthreads();
;   };
.LBB0_1462:
	ds_read_b128 v[64:67], v168 offset:0
	ds_read_b128 v[68:71], v168 offset:2048
	ds_read_b128 v[72:75], v168 offset:4096
	ds_read_b128 v[76:79], v168 offset:6144
	ds_read_b128 v[80:83], v169 offset:0
	ds_read_b128 v[84:87], v169 offset:2048
	ds_read_b128 v[88:91], v169 offset:4096
	ds_read_b128 v[92:95], v169 offset:6144
	ds_read_b128 v[96:99], v220 offset:0
	ds_read_b128 v[100:103], v220 offset:2048
	ds_read_b128 v[104:107], v220 offset:4096
	ds_read_b128 v[108:111], v220 offset:6144
	ds_read_b128 v[112:115], v221 offset:0
	ds_read_b128 v[116:119], v221 offset:2048
	ds_read_b128 v[120:123], v221 offset:4096
	ds_read_b128 v[124:127], v221 offset:6144
	s_add_i32 s4, s14, 1
	s_min_u32 s4, s4, 15
	s_lshl_b32 s18, s4, 7
	s_add_u32 m0, s101, 0x8000
	v_lshl_add_u64 v[128:129], v[152:153], 0, s[18:19]
	global_load_lds_dwordx4 v[128:129], off
	s_add_u32 m0, s101, 0xc000
	v_lshl_add_u64 v[128:129], v[154:155], 0, s[18:19]
	global_load_lds_dwordx4 v[128:129], off
	s_add_u32 m0, s101, 0x9000
	v_lshl_add_u64 v[128:129], v[156:157], 0, s[18:19]
	global_load_lds_dwordx4 v[128:129], off
	s_add_u32 m0, s101, 0xd000
	v_lshl_add_u64 v[128:129], v[158:159], 0, s[18:19]
	global_load_lds_dwordx4 v[128:129], off
	s_add_u32 m0, s101, 0xa000
	v_lshl_add_u64 v[128:129], v[160:161], 0, s[18:19]
	global_load_lds_dwordx4 v[128:129], off
	s_add_u32 m0, s101, 0xe000
	v_lshl_add_u64 v[128:129], v[162:163], 0, s[18:19]
	global_load_lds_dwordx4 v[128:129], off
	s_add_u32 m0, s101, 0xb000
	v_lshl_add_u64 v[128:129], v[164:165], 0, s[18:19]
	global_load_lds_dwordx4 v[128:129], off
	s_add_u32 m0, s101, 0xf000
	v_lshl_add_u64 v[128:129], v[166:167], 0, s[18:19]
	global_load_lds_dwordx4 v[128:129], off
	s_waitcnt lgkmcnt(8)
	v_mfma_f32_16x16x32_bf16 v[0:3], v[80:83], v[64:67], v[0:3]
	v_mfma_f32_16x16x32_bf16 v[4:7], v[84:87], v[64:67], v[4:7]
	v_mfma_f32_16x16x32_bf16 v[8:11], v[88:91], v[64:67], v[8:11]
	v_mfma_f32_16x16x32_bf16 v[12:15], v[92:95], v[64:67], v[12:15]
	v_mfma_f32_16x16x32_bf16 v[16:19], v[80:83], v[68:71], v[16:19]
	v_mfma_f32_16x16x32_bf16 v[20:23], v[84:87], v[68:71], v[20:23]
	v_mfma_f32_16x16x32_bf16 v[24:27], v[88:91], v[68:71], v[24:27]
	v_mfma_f32_16x16x32_bf16 v[28:31], v[92:95], v[68:71], v[28:31]
	v_mfma_f32_16x16x32_bf16 v[32:35], v[80:83], v[72:75], v[32:35]
	v_mfma_f32_16x16x32_bf16 v[36:39], v[84:87], v[72:75], v[36:39]
	v_mfma_f32_16x16x32_bf16 v[40:43], v[88:91], v[72:75], v[40:43]
	v_mfma_f32_16x16x32_bf16 v[44:47], v[92:95], v[72:75], v[44:47]
	v_mfma_f32_16x16x32_bf16 v[48:51], v[80:83], v[76:79], v[48:51]
	v_mfma_f32_16x16x32_bf16 v[52:55], v[84:87], v[76:79], v[52:55]
	v_mfma_f32_16x16x32_bf16 v[56:59], v[88:91], v[76:79], v[56:59]
	v_mfma_f32_16x16x32_bf16 v[60:63], v[92:95], v[76:79], v[60:63]
	s_waitcnt lgkmcnt(0)
	v_mfma_f32_16x16x32_bf16 v[0:3], v[112:115], v[96:99], v[0:3]
	v_mfma_f32_16x16x32_bf16 v[4:7], v[116:119], v[96:99], v[4:7]
	v_mfma_f32_16x16x32_bf16 v[8:11], v[120:123], v[96:99], v[8:11]
	v_mfma_f32_16x16x32_bf16 v[12:15], v[124:127], v[96:99], v[12:15]
	v_mfma_f32_16x16x32_bf16 v[16:19], v[112:115], v[100:103], v[16:19]
	v_mfma_f32_16x16x32_bf16 v[20:23], v[116:119], v[100:103], v[20:23]
	v_mfma_f32_16x16x32_bf16 v[24:27], v[120:123], v[100:103], v[24:27]
	v_mfma_f32_16x16x32_bf16 v[28:31], v[124:127], v[100:103], v[28:31]
	v_mfma_f32_16x16x32_bf16 v[32:35], v[112:115], v[104:107], v[32:35]
	v_mfma_f32_16x16x32_bf16 v[36:39], v[116:119], v[104:107], v[36:39]
	v_mfma_f32_16x16x32_bf16 v[40:43], v[120:123], v[104:107], v[40:43]
	v_mfma_f32_16x16x32_bf16 v[44:47], v[124:127], v[104:107], v[44:47]
	v_mfma_f32_16x16x32_bf16 v[48:51], v[112:115], v[108:111], v[48:51]
	v_mfma_f32_16x16x32_bf16 v[52:55], v[116:119], v[108:111], v[52:55]
	v_mfma_f32_16x16x32_bf16 v[56:59], v[120:123], v[108:111], v[56:59]
	v_mfma_f32_16x16x32_bf16 v[60:63], v[124:127], v[108:111], v[60:63]
	s_waitcnt vmcnt(0)
	s_barrier
; #define SB_ __builtin_amdgcn_sched_barrier(0)
; template <bool SWAP, bool HALF>
; DI void gemm_mainloop(const GemmDesc& d, int m0, int n0, bf16_t* smem, f32x16 (&acc)[2][2], int dry) {
;     ...
;   auto stage = [&](int cur, u32x4 (&ran)[4], u32x4 (&rbn)[4], int ks) {
;     ldf(cur, 1, 1); SB_;
;     mma(0); SB_;
;     ldf(cur, 2, 0); SB_;
;     lw(ran, rbn, cur ^ 1);
;     gl(ran, rbn, (ks + 3 < nk) ? ks + 3 : nk - 1);
;     SB_;
;     mma(1); SB_;
;     __syncthreads();
;     ldf(cur, 3, 1); SB_;
;     mma(0); SB_;
;     ldf(cur ^ 1, 0, 0);
;     SB_;
;     mma(1); SB_;
;     __syncthreads();
;   };
; DI void gemm_tile(const GemmDesc& d, int m0, int n0, bf16_t* smem, int dry) {
;     ...
; #pragma unroll
;     for (int a = 0; a < 2; ++a)
; #pragma unroll
;       for (int b = 0; b < 2; ++b)
; #pragma unroll
;         for (int g = 0; g < 4; ++g) {
;           f32x4 o;
; #pragma unroll
;           for (int j = 0; j < 4; ++j) o[j] = acc[a][b][4 * g + j];
;           *(f32x4*)(Ct + (wm * 64 + a * 32 + r) * CS + wn * 64 + b * 32 + 8 * g + 4 * hh) = o;
;         }
;   }
;   __syncthreads();
	ds_read_b128 v[64:67], v168 offset:32768
	ds_read_b128 v[68:71], v168 offset:34816
	ds_read_b128 v[72:75], v168 offset:36864
	ds_read_b128 v[76:79], v168 offset:38912
	ds_read_b128 v[80:83], v169 offset:32768
	ds_read_b128 v[84:87], v169 offset:34816
	ds_read_b128 v[88:91], v169 offset:36864
	ds_read_b128 v[92:95], v169 offset:38912
	ds_read_b128 v[96:99], v220 offset:32768
	ds_read_b128 v[100:103], v220 offset:34816
	ds_read_b128 v[104:107], v220 offset:36864
	ds_read_b128 v[108:111], v220 offset:38912
	ds_read_b128 v[112:115], v221 offset:32768
	ds_read_b128 v[116:119], v221 offset:34816
	ds_read_b128 v[120:123], v221 offset:36864
	ds_read_b128 v[124:127], v221 offset:38912
	s_add_i32 s4, s14, 2
	s_min_u32 s4, s4, 15
	s_lshl_b32 s18, s4, 7
	s_add_u32 m0, s101, 0x0
	v_lshl_add_u64 v[128:129], v[152:153], 0, s[18:19]
	global_load_lds_dwordx4 v[128:129], off
	s_add_u32 m0, s101, 0x4000
	v_lshl_add_u64 v[128:129], v[154:155], 0, s[18:19]
	global_load_lds_dwordx4 v[128:129], off
	s_add_u32 m0, s101, 0x1000
	v_lshl_add_u64 v[128:129], v[156:157], 0, s[18:19]
	global_load_lds_dwordx4 v[128:129], off
	s_add_u32 m0, s101, 0x5000
	v_lshl_add_u64 v[128:129], v[158:159], 0, s[18:19]
	global_load_lds_dwordx4 v[128:129], off
	s_add_u32 m0, s101, 0x2000
	v_lshl_add_u64 v[128:129], v[160:161], 0, s[18:19]
	global_load_lds_dwordx4 v[128:129], off
	s_add_u32 m0, s101, 0x6000
	v_lshl_add_u64 v[128:129], v[162:163], 0, s[18:19]
	global_load_lds_dwordx4 v[128:129], off
	s_add_u32 m0, s101, 0x3000
	v_lshl_add_u64 v[128:129], v[164:165], 0, s[18:19]
	global_load_lds_dwordx4 v[128:129], off
	s_add_u32 m0, s101, 0x7000
	v_lshl_add_u64 v[128:129], v[166:167], 0, s[18:19]
	global_load_lds_dwordx4 v[128:129], off
	s_waitcnt lgkmcnt(8)
	v_mfma_f32_16x16x32_bf16 v[0:3], v[80:83], v[64:67], v[0:3]
	v_mfma_f32_16x16x32_bf16 v[4:7], v[84:87], v[64:67], v[4:7]
	v_mfma_f32_16x16x32_bf16 v[8:11], v[88:91], v[64:67], v[8:11]
	v_mfma_f32_16x16x32_bf16 v[12:15], v[92:95], v[64:67], v[12:15]
	v_mfma_f32_16x16x32_bf16 v[16:19], v[80:83], v[68:71], v[16:19]
	v_mfma_f32_16x16x32_bf16 v[20:23], v[84:87], v[68:71], v[20:23]
	v_mfma_f32_16x16x32_bf16 v[24:27], v[88:91], v[68:71], v[24:27]
	v_mfma_f32_16x16x32_bf16 v[28:31], v[92:95], v[68:71], v[28:31]
	v_mfma_f32_16x16x32_bf16 v[32:35], v[80:83], v[72:75], v[32:35]
	v_mfma_f32_16x16x32_bf16 v[36:39], v[84:87], v[72:75], v[36:39]
	v_mfma_f32_16x16x32_bf16 v[40:43], v[88:91], v[72:75], v[40:43]
	v_mfma_f32_16x16x32_bf16 v[44:47], v[92:95], v[72:75], v[44:47]
	v_mfma_f32_16x16x32_bf16 v[48:51], v[80:83], v[76:79], v[48:51]
	v_mfma_f32_16x16x32_bf16 v[52:55], v[84:87], v[76:79], v[52:55]
	v_mfma_f32_16x16x32_bf16 v[56:59], v[88:91], v[76:79], v[56:59]
	v_mfma_f32_16x16x32_bf16 v[60:63], v[92:95], v[76:79], v[60:63]
	s_waitcnt lgkmcnt(0)
	v_mfma_f32_16x16x32_bf16 v[0:3], v[112:115], v[96:99], v[0:3]
	v_mfma_f32_16x16x32_bf16 v[4:7], v[116:119], v[96:99], v[4:7]
	v_mfma_f32_16x16x32_bf16 v[8:11], v[120:123], v[96:99], v[8:11]
	v_mfma_f32_16x16x32_bf16 v[12:15], v[124:127], v[96:99], v[12:15]
	v_mfma_f32_16x16x32_bf16 v[16:19], v[112:115], v[100:103], v[16:19]
	v_mfma_f32_16x16x32_bf16 v[20:23], v[116:119], v[100:103], v[20:23]
	v_mfma_f32_16x16x32_bf16 v[24:27], v[120:123], v[100:103], v[24:27]
	v_mfma_f32_16x16x32_bf16 v[28:31], v[124:127], v[100:103], v[28:31]
	v_mfma_f32_16x16x32_bf16 v[32:35], v[112:115], v[104:107], v[32:35]
	v_mfma_f32_16x16x32_bf16 v[36:39], v[116:119], v[104:107], v[36:39]
	v_mfma_f32_16x16x32_bf16 v[40:43], v[120:123], v[104:107], v[40:43]
	v_mfma_f32_16x16x32_bf16 v[44:47], v[124:127], v[104:107], v[44:47]
	v_mfma_f32_16x16x32_bf16 v[48:51], v[112:115], v[108:111], v[48:51]
	v_mfma_f32_16x16x32_bf16 v[52:55], v[116:119], v[108:111], v[52:55]
	v_mfma_f32_16x16x32_bf16 v[56:59], v[120:123], v[108:111], v[56:59]
	v_mfma_f32_16x16x32_bf16 v[60:63], v[124:127], v[108:111], v[60:63]
	s_add_i32 s4, s14, 2
	s_cmp_lt_u32 s14, 14
	s_mov_b32 s14, s4
	s_waitcnt vmcnt(0)
	s_barrier
	s_cbranch_scc1 .LBB0_1462
	s_and_saveexec_b64 s[4:5], vcc
	s_cbranch_execz .LBB0_1465
	s_mov_b32 s14, 0x800000
	s_waitcnt vmcnt(15)
	v_mul_f32_e32 v64, 0x4b800000, v170
	v_cmp_gt_f32_e32 vcc, s14, v170
	s_nop 1
	v_cndmask_b32_e32 v64, v170, v64, vcc
	v_rsq_f32_e32 v64, v64
	s_nop 0
	v_mul_f32_e32 v65, 0x45800000, v64
	v_cndmask_b32_e32 v64, v64, v65, vcc
	v_lshl_add_u32 v65, v150, 2, v181
	ds_write_b32 v65, v64
.LBB0_1465:
	s_or_b64 exec, exec, s[4:5]
	s_waitcnt vmcnt(15)
	v_and_b32_e32 v64, 31, v150
	v_lshrrev_b32_e32 v65, 1, v150
	v_and_or_b32 v66, v65, s72, v64
	v_lshlrev_b32_e32 v64, 2, v150
	v_and_b32_e32 v65, 16, v65
	s_movk_i32 s4, 0x100
	v_and_or_b32 v64, v64, s4, v65
	v_mad_u64_u32 v[64:65], s[4:5], v66, s22, v[64:65]
	s_lshl_b32 s4, s13, 6
	s_ashr_i32 s5, s4, 31
	s_lshl_b64 s[4:5], s[4:5], 1
	v_and_b32_e32 v204, 15, v172
	v_lshrrev_b32_e32 v205, 1, v172
	v_and_or_b32 v204, v205, s72, v204
	v_lshlrev_b32_e32 v205, 2, v172
	v_and_b32_e32 v206, 0x30, v172
	v_and_b32_e32 v205, 0x100, v205
	v_or_b32_e32 v205, v205, v206
	v_mad_u32_u24 v64, v204, s22, v205
	ds_write_b128 v64, v[0:3]
	ds_write_b128 v64, v[4:7] offset:64
	ds_write_b128 v64, v[8:11] offset:128
	ds_write_b128 v64, v[12:15] offset:192
	ds_write_b128 v64, v[16:19] offset:8448
	ds_write_b128 v64, v[20:23] offset:8512
	ds_write_b128 v64, v[24:27] offset:8576
	ds_write_b128 v64, v[28:31] offset:8640
	ds_write_b128 v64, v[32:35] offset:16896
	ds_write_b128 v64, v[36:39] offset:16960
	ds_write_b128 v64, v[40:43] offset:17024
	ds_write_b128 v64, v[44:47] offset:17088
	ds_write_b128 v64, v[48:51] offset:25344
	ds_write_b128 v64, v[52:55] offset:25408
	ds_write_b128 v64, v[56:59] offset:25472
	ds_write_b128 v64, v[60:63] offset:25536
	s_add_u32 s4, s68, s4
	v_lshlrev_b32_e32 v0, 3, v150
	s_addc_u32 s5, s69, s5
	v_and_b32_e32 v144, 0x78, v0
	s_add_i32 s11, s11, s10
	v_lshl_add_u64 v[0:1], s[4:5], 0, v[144:145]
	s_sub_i32 s4, s11, s12
	v_ashrrev_i32_e32 v4, 4, v150
	v_lshlrev_b32_e32 v3, 5, v150
	v_and_b32_e32 v5, 7, v150
	s_lshl_b32 s4, s4, 10
	v_mul_lo_u32 v2, v4, s22
	v_and_b32_e32 v3, 0x100, v3
	v_lshlrev_b32_e32 v5, 4, v5
	s_or_b32 s4, s4, s29
	v_add3_u32 v2, v2, v3, v5
	v_lshlrev_b32_e32 v3, 2, v4
	v_add_u32_e32 v4, s4, v4
	s_mov_b32 s10, 8
	s_waitcnt lgkmcnt(0)
	s_barrier
	s_branch .LBB0_1467

; DI int otid() { int t = threadIdx.x; asm volatile("" : "+v"(t)); return t; }
; template <bool SWAP, bool HALF>
; DI void gemm_mainloop(const GemmDesc& d, int m0, int n0, bf16_t* smem, f32x16 (&acc)[2][2], int dry) {
;   const int t = otid(), lane = t & 63, w = t >> 6, wm = w >> 1, wn = w & 1, r = lane & 31, hh = lane >> 5;
;   const int lrow = t >> 3, lkc = t & 7;
;   const bf16_t* ap[4]; const bf16_t* bp[4];
; #pragma unroll
;   for (int i = 0; i < 4; ++i) {
;     int am = m0 + lrow + 32 * i; am = am < M ? am : M - 1;
;     ap[i] = d.A + (size_t)am * d.lda + lkc * 8 + (d.a_grp ? (n0 / d.a_grp) * d.a_grp : 0);
;     bp[i] = d.Bt + (size_t)(n0 + lrow + 32 * i) * d.ldb + lkc * 8;
;   }
; #pragma unroll
;   for (int a = 0; a < 2; ++a)
; #pragma unroll
;     for (int b = 0; b < 2; ++b)
; #pragma unroll
;       for (int i = 0; i < 16; ++i) acc[a][b][i] = 0.f;
;   u32x4 ra0[4], rb0[4], ra1[4], rb1[4];
;   const int nk = d.K >> 6;
;   const int lds_w = lrow * LST + lkc * 8;
;     ...
;   gl(ra0, rb0, 0);
;   gl(ra1, rb1, 1);
;   lw(ra0, rb0, 0);
;   gl(ra0, rb0, 2);
;   __syncthreads();
;   ldf(0, 0, 0);
.LBB0_1527:
	s_lshr_b32 s1, s12, 3
	s_and_b32 s1, s1, 0xffffff8
	v_readlane_b32 s4, v228, 38
	s_sub_i32 s4, s4, s1
	s_min_i32 s4, s4, 8
	s_abs_i32 s5, s4
	v_cvt_f32_u32_e32 v0, s5
	s_sub_i32 s14, 0, s5
	s_lshl_b32 s10, s1, 3
	s_sub_i32 s10, s12, s10
	v_rcp_iflag_f32_e32 v0, v0
	s_abs_i32 s13, s10
	s_xor_b32 s11, s10, s4
	s_ashr_i32 s11, s11, 31
	v_mul_f32_e32 v0, 0x4f7ffffe, v0
	v_cvt_u32_f32_e32 v0, v0
	v_mov_b32_e32 v150, v172
	v_mov_b32_e32 v32, v172
	v_readfirstlane_b32 s15, v0
	s_mul_i32 s14, s14, s15
	s_mul_hi_u32 s14, s15, s14
	s_add_i32 s15, s15, s14
	s_mul_hi_u32 s14, s13, s15
	s_mul_i32 s15, s14, s5
	s_sub_i32 s13, s13, s15
	s_add_i32 s16, s14, 1
	s_sub_i32 s15, s13, s5
	s_cmp_ge_u32 s13, s5
	s_cselect_b32 s14, s16, s14
	s_cselect_b32 s13, s15, s13
	s_add_i32 s15, s14, 1
	s_cmp_ge_u32 s13, s5
	s_cselect_b32 s5, s15, s14
	s_xor_b32 s5, s5, s11
	s_sub_i32 s11, s5, s11
	s_mul_i32 s4, s11, s4
	s_sub_i32 s4, s10, s4
	s_add_i32 s1, s1, s4
	s_lshl_b32 s1, s1, 10
	s_or_b32 s13, s1, s29
	v_lshlrev_b32_e32 v0, 3, v32
	v_ashrrev_i32_e32 v8, 3, v32
	v_and_b32_e32 v33, 56, v0
	v_add_u32_e32 v9, s13, v8
	v_lshlrev_b32_e32 v144, 1, v33
	v_lshl_add_u64 v[4:5], s[68:69], 0, v[144:145]
	v_min_i32_e32 v0, 0x803f, v9
	v_mad_i64_i32 v[152:153], s[4:5], v0, s26, v[4:5]
	s_lshl_b32 s4, s11, 7
	v_min_i32_e32 v11, 0x801f, v9
	v_add_u32_e32 v10, s4, v8
	v_add_u32_e32 v11, 32, v11
	v_lshl_add_u64 v[6:7], s[6:7], 0, v[144:145]
	v_mad_i64_i32 v[156:157], s[10:11], v11, s26, v[4:5]
	v_add_u32_e32 v11, 32, v10
	v_mad_i64_i32 v[158:159], s[10:11], v11, s26, v[6:7]
	v_min_i32_e32 v11, 0x7fff, v9
	v_min_i32_e32 v9, 0x7fdf, v9
	v_add_u32_e32 v11, 64, v11
	v_add_u32_e32 v9, 0x60, v9
	v_mad_i64_i32 v[160:161], s[10:11], v11, s26, v[4:5]
	v_add_u32_e32 v11, 64, v10
	v_mad_i64_i32 v[164:165], s[10:11], v9, s26, v[4:5]
	v_add_u32_e32 v4, 0x60, v10
	s_movk_i32 s5, 0x48
	s_mov_b32 s1, 0
	v_mad_i64_i32 v[154:155], s[10:11], v10, s26, v[6:7]
	v_mad_i64_i32 v[162:163], s[10:11], v11, s26, v[6:7]
	v_mad_i64_i32 v[166:167], s[10:11], v4, s26, v[6:7]
	v_and_b32_e32 v34, 31, v32
	v_mul_lo_u32 v35, v8, s5
	v_add_lshl_u32 v144, v35, v33, 1
	s_waitcnt vmcnt(15)
	s_waitcnt vmcnt(14)
	s_waitcnt vmcnt(13)
	s_waitcnt vmcnt(12)
	s_waitcnt vmcnt(11)
	s_waitcnt vmcnt(10)
	s_waitcnt vmcnt(9)
	s_waitcnt vmcnt(8)
	v_lshrrev_b32_e32 v0, 1, v32
	v_and_or_b32 v1, v0, s72, v34
	v_and_b32_e32 v0, 16, v0
	s_movk_i32 s5, 0x90
	v_mad_u64_u32 v[168:169], s[10:11], v1, s5, v[0:1]
	v_and_b32_e32 v1, 0x5f, v32
	v_mul_u32_u24_e32 v1, 0x48, v1
	v_lshl_add_u32 v169, v1, 1, v0
	v_bfe_u32 v204, v172, 4, 3
	v_lshlrev_b32_e32 v204, 4, v204
	v_xor_b32_e32 v152, v152, v204
	v_xor_b32_e32 v154, v154, v204
	v_xor_b32_e32 v156, v156, v204
	v_xor_b32_e32 v158, v158, v204
	v_xor_b32_e32 v160, v160, v204
	v_xor_b32_e32 v162, v162, v204
	v_xor_b32_e32 v164, v164, v204
	v_xor_b32_e32 v166, v166, v204
	v_lshrrev_b32_e32 v205, 6, v172
	s_nop 1
	v_readfirstlane_b32 s101, v205
	s_lshl_b32 s101, s101, 10
	s_add_u32 m0, s101, 0x0
	s_nop 0
	global_load_lds_dwordx4 v[152:153], off
	s_add_u32 m0, s101, 0x4000
	s_nop 0
	global_load_lds_dwordx4 v[154:155], off
	s_add_u32 m0, s101, 0x1000
	s_nop 0
	global_load_lds_dwordx4 v[156:157], off
	s_add_u32 m0, s101, 0x5000
	s_nop 0
	global_load_lds_dwordx4 v[158:159], off
	s_add_u32 m0, s101, 0x2000
	s_nop 0
	global_load_lds_dwordx4 v[160:161], off
	s_add_u32 m0, s101, 0x6000
	s_nop 0
	global_load_lds_dwordx4 v[162:163], off
	s_add_u32 m0, s101, 0x3000
	s_nop 0
	global_load_lds_dwordx4 v[164:165], off
	s_add_u32 m0, s101, 0x7000
	s_nop 0
	global_load_lds_dwordx4 v[166:167], off
	v_and_b32_e32 v204, 15, v172
	v_bfe_u32 v205, v172, 4, 2
	v_lshrrev_b32_e32 v206, 1, v204
	v_xor_b32_e32 v205, v205, v206
	v_lshlrev_b32_e32 v205, 4, v205
	v_lshl_or_b32 v204, v204, 7, v205
	v_lshrrev_b32_e32 v206, 7, v172
	v_lshl_add_u32 v168, v206, 13, v204
	v_bfe_u32 v206, v172, 6, 1
	v_lshl_add_u32 v169, v206, 13, v204
	v_add_u32_e32 v169, 0x4000, v169
	v_xor_b32_e32 v220, 64, v168
	v_xor_b32_e32 v221, 64, v169
	s_waitcnt vmcnt(0)
	s_waitcnt lgkmcnt(0)
	s_barrier
	v_mov_b32_e32 v0, 0
	v_add_u32_e32 v170, 0x9000, v144
	v_mov_b32_e32 v1, v0
	v_mov_b32_e32 v2, v0
	v_mov_b32_e32 v3, v0
	v_mov_b32_e32 v4, v0
	v_mov_b32_e32 v5, v0
	v_mov_b32_e32 v6, v0
	v_mov_b32_e32 v7, v0
	v_mov_b32_e32 v8, v0
	v_mov_b32_e32 v9, v0
	v_mov_b32_e32 v10, v0
	v_mov_b32_e32 v11, v0
	v_mov_b32_e32 v12, v0
	v_mov_b32_e32 v13, v0
	v_mov_b32_e32 v14, v0
	v_mov_b32_e32 v15, v0
	v_mov_b32_e32 v16, v0
	v_mov_b32_e32 v17, v0
	v_mov_b32_e32 v18, v0
	v_mov_b32_e32 v19, v0
	v_mov_b32_e32 v20, v0
	v_mov_b32_e32 v21, v0
	v_mov_b32_e32 v22, v0
	v_mov_b32_e32 v23, v0
	v_mov_b32_e32 v24, v0
	v_mov_b32_e32 v25, v0
	v_mov_b32_e32 v26, v0
	v_mov_b32_e32 v27, v0
	v_mov_b32_e32 v28, v0
	v_mov_b32_e32 v29, v0
	v_mov_b32_e32 v30, v0
	v_mov_b32_e32 v31, v0
	v_mov_b32_e32 v32, v0
	v_mov_b32_e32 v33, v0
	v_mov_b32_e32 v34, v0
	v_mov_b32_e32 v35, v0
	v_mov_b32_e32 v36, v0
	v_mov_b32_e32 v37, v0
	v_mov_b32_e32 v38, v0
	v_mov_b32_e32 v39, v0
	v_mov_b32_e32 v40, v0
	v_mov_b32_e32 v41, v0
	v_mov_b32_e32 v42, v0
	v_mov_b32_e32 v43, v0
	v_mov_b32_e32 v44, v0
	v_mov_b32_e32 v45, v0
	v_mov_b32_e32 v46, v0
	v_mov_b32_e32 v47, v0
	v_mov_b32_e32 v48, v0
	v_mov_b32_e32 v49, v0
	v_mov_b32_e32 v50, v0
	v_mov_b32_e32 v51, v0
	v_mov_b32_e32 v52, v0
	v_mov_b32_e32 v53, v0
	v_mov_b32_e32 v54, v0
	v_mov_b32_e32 v55, v0
	v_mov_b32_e32 v56, v0
	v_mov_b32_e32 v57, v0
	v_mov_b32_e32 v58, v0
	v_mov_b32_e32 v59, v0
	v_mov_b32_e32 v60, v0
	v_mov_b32_e32 v61, v0
	v_mov_b32_e32 v62, v0
	v_mov_b32_e32 v63, v0
; #define MFMA32(a, b, c) __builtin_amdgcn_mfma_f32_32x32x16_bf16((a), (b), (c), 0, 0, 0)
; #define SB_ __builtin_amdgcn_sched_barrier(0)
; template <bool SWAP, bool HALF>
; DI void gemm_mainloop(const GemmDesc& d, int m0, int n0, bf16_t* smem, f32x16 (&acc)[2][2], int dry) {
;     ...
;   auto ldf = [&](int buf, int kk, int set) {
;     const bf16_t* Ab = smem + buf * 2 * TILE_EL + ((HALF ? 0 : wm * 64) + r) * LST + 8 * hh + kk * 16;
;     const bf16_t* Bb = smem + buf * 2 * TILE_EL + TILE_EL + ((HALF ? w * 32 : wn * 64) + r) * LST + 8 * hh + kk * 16;
; #pragma unroll
;     for (int i = 0; i < 2; ++i) { fa[set][i] = *(const bf16x8*)(Ab + i * 32 * LST); if (!HALF || i == 0) fb[set][i] = *(const bf16x8*)(Bb + i * 32 * LST); }
;   };
;   auto mma = [&](int set) {
; #pragma unroll
;     for (int a = 0; a < 2; ++a)
; #pragma unroll
;       for (int b = 0; b < (HALF ? 1 : 2); ++b) {
;         if (SWAP) acc[a][b] = MFMA32(fb[set][b], fa[set][a], acc[a][b]);
;         else      acc[a][b] = MFMA32(fa[set][a], fb[set][b], acc[a][b]);
;       }
;   };
;     ...
;   auto stage = [&](int cur, u32x4 (&ran)[4], u32x4 (&rbn)[4], int ks) {
;     ldf(cur, 1, 1); SB_;
;     mma(0); SB_;
;     ldf(cur, 2, 0); SB_;
;     lw(ran, rbn, cur ^ 1);
;     gl(ran, rbn, (ks + 3 < nk) ? ks + 3 : nk - 1);
;     SB_;
;     mma(1); SB_;
;     __syncthreads();
;     ldf(cur, 3, 1); SB_;
;     mma(0); SB_;
;     ldf(cur ^ 1, 0, 0);
;     SB_;
;     mma(1); SB_;
;     __syncthreads();
;   };
.LBB0_1528:
	ds_read_b128 v[64:67], v168 offset:0
	ds_read_b128 v[68:71], v168 offset:2048
	ds_read_b128 v[72:75], v168 offset:4096
	ds_read_b128 v[76:79], v168 offset:6144
	ds_read_b128 v[80:83], v169 offset:0
	ds_read_b128 v[84:87], v169 offset:2048
	ds_read_b128 v[88:91], v169 offset:4096
	ds_read_b128 v[92:95], v169 offset:6144
	ds_read_b128 v[96:99], v220 offset:0
	ds_read_b128 v[100:103], v220 offset:2048
	ds_read_b128 v[104:107], v220 offset:4096
	ds_read_b128 v[108:111], v220 offset:6144
	ds_read_b128 v[112:115], v221 offset:0
	ds_read_b128 v[116:119], v221 offset:2048
	ds_read_b128 v[120:123], v221 offset:4096
	ds_read_b128 v[124:127], v221 offset:6144
	s_add_i32 s5, s1, 1
	s_min_u32 s5, s5, 43
	s_lshl_b32 s18, s5, 7
	s_add_u32 m0, s101, 0x8000
	v_lshl_add_u64 v[128:129], v[152:153], 0, s[18:19]
	global_load_lds_dwordx4 v[128:129], off
	s_add_u32 m0, s101, 0xc000
	v_lshl_add_u64 v[128:129], v[154:155], 0, s[18:19]
	global_load_lds_dwordx4 v[128:129], off
	s_add_u32 m0, s101, 0x9000
	v_lshl_add_u64 v[128:129], v[156:157], 0, s[18:19]
	global_load_lds_dwordx4 v[128:129], off
	s_add_u32 m0, s101, 0xd000
	v_lshl_add_u64 v[128:129], v[158:159], 0, s[18:19]
	global_load_lds_dwordx4 v[128:129], off
	s_add_u32 m0, s101, 0xa000
	v_lshl_add_u64 v[128:129], v[160:161], 0, s[18:19]
	global_load_lds_dwordx4 v[128:129], off
	s_add_u32 m0, s101, 0xe000
	v_lshl_add_u64 v[128:129], v[162:163], 0, s[18:19]
	global_load_lds_dwordx4 v[128:129], off
	s_add_u32 m0, s101, 0xb000
	v_lshl_add_u64 v[128:129], v[164:165], 0, s[18:19]
	global_load_lds_dwordx4 v[128:129], off
	s_add_u32 m0, s101, 0xf000
	v_lshl_add_u64 v[128:129], v[166:167], 0, s[18:19]
	global_load_lds_dwordx4 v[128:129], off
	s_waitcnt lgkmcnt(8)
	v_mfma_f32_16x16x32_bf16 v[0:3], v[80:83], v[64:67], v[0:3]
	v_mfma_f32_16x16x32_bf16 v[4:7], v[84:87], v[64:67], v[4:7]
	v_mfma_f32_16x16x32_bf16 v[8:11], v[88:91], v[64:67], v[8:11]
	v_mfma_f32_16x16x32_bf16 v[12:15], v[92:95], v[64:67], v[12:15]
	v_mfma_f32_16x16x32_bf16 v[16:19], v[80:83], v[68:71], v[16:19]
	v_mfma_f32_16x16x32_bf16 v[20:23], v[84:87], v[68:71], v[20:23]
	v_mfma_f32_16x16x32_bf16 v[24:27], v[88:91], v[68:71], v[24:27]
	v_mfma_f32_16x16x32_bf16 v[28:31], v[92:95], v[68:71], v[28:31]
	v_mfma_f32_16x16x32_bf16 v[32:35], v[80:83], v[72:75], v[32:35]
	v_mfma_f32_16x16x32_bf16 v[36:39], v[84:87], v[72:75], v[36:39]
	v_mfma_f32_16x16x32_bf16 v[40:43], v[88:91], v[72:75], v[40:43]
	v_mfma_f32_16x16x32_bf16 v[44:47], v[92:95], v[72:75], v[44:47]
	v_mfma_f32_16x16x32_bf16 v[48:51], v[80:83], v[76:79], v[48:51]
	v_mfma_f32_16x16x32_bf16 v[52:55], v[84:87], v[76:79], v[52:55]
	v_mfma_f32_16x16x32_bf16 v[56:59], v[88:91], v[76:79], v[56:59]
	v_mfma_f32_16x16x32_bf16 v[60:63], v[92:95], v[76:79], v[60:63]
	s_waitcnt lgkmcnt(0)
	v_mfma_f32_16x16x32_bf16 v[0:3], v[112:115], v[96:99], v[0:3]
	v_mfma_f32_16x16x32_bf16 v[4:7], v[116:119], v[96:99], v[4:7]
	v_mfma_f32_16x16x32_bf16 v[8:11], v[120:123], v[96:99], v[8:11]
	v_mfma_f32_16x16x32_bf16 v[12:15], v[124:127], v[96:99], v[12:15]
	v_mfma_f32_16x16x32_bf16 v[16:19], v[112:115], v[100:103], v[16:19]
	v_mfma_f32_16x16x32_bf16 v[20:23], v[116:119], v[100:103], v[20:23]
	v_mfma_f32_16x16x32_bf16 v[24:27], v[120:123], v[100:103], v[24:27]
	v_mfma_f32_16x16x32_bf16 v[28:31], v[124:127], v[100:103], v[28:31]
	v_mfma_f32_16x16x32_bf16 v[32:35], v[112:115], v[104:107], v[32:35]
	v_mfma_f32_16x16x32_bf16 v[36:39], v[116:119], v[104:107], v[36:39]
	v_mfma_f32_16x16x32_bf16 v[40:43], v[120:123], v[104:107], v[40:43]
	v_mfma_f32_16x16x32_bf16 v[44:47], v[124:127], v[104:107], v[44:47]
	v_mfma_f32_16x16x32_bf16 v[48:51], v[112:115], v[108:111], v[48:51]
	v_mfma_f32_16x16x32_bf16 v[52:55], v[116:119], v[108:111], v[52:55]
	v_mfma_f32_16x16x32_bf16 v[56:59], v[120:123], v[108:111], v[56:59]
	v_mfma_f32_16x16x32_bf16 v[60:63], v[124:127], v[108:111], v[60:63]
	s_waitcnt vmcnt(0)
	s_barrier
	ds_read_b128 v[64:67], v168 offset:32768
	ds_read_b128 v[68:71], v168 offset:34816
	ds_read_b128 v[72:75], v168 offset:36864
	ds_read_b128 v[76:79], v168 offset:38912
	ds_read_b128 v[80:83], v169 offset:32768
	ds_read_b128 v[84:87], v169 offset:34816
	ds_read_b128 v[88:91], v169 offset:36864
	ds_read_b128 v[92:95], v169 offset:38912
	ds_read_b128 v[96:99], v220 offset:32768
	ds_read_b128 v[100:103], v220 offset:34816
	ds_read_b128 v[104:107], v220 offset:36864
	ds_read_b128 v[108:111], v220 offset:38912
	ds_read_b128 v[112:115], v221 offset:32768
	ds_read_b128 v[116:119], v221 offset:34816
	ds_read_b128 v[120:123], v221 offset:36864
	ds_read_b128 v[124:127], v221 offset:38912
	s_add_i32 s5, s1, 2
	s_min_u32 s5, s5, 43
	s_lshl_b32 s18, s5, 7
	s_add_u32 m0, s101, 0x0
	v_lshl_add_u64 v[128:129], v[152:153], 0, s[18:19]
	global_load_lds_dwordx4 v[128:129], off
	s_add_u32 m0, s101, 0x4000
	v_lshl_add_u64 v[128:129], v[154:155], 0, s[18:19]
	global_load_lds_dwordx4 v[128:129], off
	s_add_u32 m0, s101, 0x1000
	v_lshl_add_u64 v[128:129], v[156:157], 0, s[18:19]
	global_load_lds_dwordx4 v[128:129], off
	s_add_u32 m0, s101, 0x5000
	v_lshl_add_u64 v[128:129], v[158:159], 0, s[18:19]
	global_load_lds_dwordx4 v[128:129], off
	s_add_u32 m0, s101, 0x2000
	v_lshl_add_u64 v[128:129], v[160:161], 0, s[18:19]
	global_load_lds_dwordx4 v[128:129], off
	s_add_u32 m0, s101, 0x6000
	v_lshl_add_u64 v[128:129], v[162:163], 0, s[18:19]
	global_load_lds_dwordx4 v[128:129], off
	s_add_u32 m0, s101, 0x3000
	v_lshl_add_u64 v[128:129], v[164:165], 0, s[18:19]
	global_load_lds_dwordx4 v[128:129], off
	s_add_u32 m0, s101, 0x7000
	v_lshl_add_u64 v[128:129], v[166:167], 0, s[18:19]
	global_load_lds_dwordx4 v[128:129], off
	s_waitcnt lgkmcnt(8)
; #define MFMA32(a, b, c) __builtin_amdgcn_mfma_f32_32x32x16_bf16((a), (b), (c), 0, 0, 0)
; #define SB_ __builtin_amdgcn_sched_barrier(0)
; template <bool SWAP, bool HALF>
; DI void gemm_mainloop(const GemmDesc& d, int m0, int n0, bf16_t* smem, f32x16 (&acc)[2][2], int dry) {
;     ...
;   auto mma = [&](int set) {
; #pragma unroll
;     for (int a = 0; a < 2; ++a)
; #pragma unroll
;       for (int b = 0; b < (HALF ? 1 : 2); ++b) {
;         if (SWAP) acc[a][b] = MFMA32(fb[set][b], fa[set][a], acc[a][b]);
;         else      acc[a][b] = MFMA32(fa[set][a], fb[set][b], acc[a][b]);
;       }
;   };
;     ...
;   auto stage = [&](int cur, u32x4 (&ran)[4], u32x4 (&rbn)[4], int ks) {
;     ldf(cur, 1, 1); SB_;
;     mma(0); SB_;
;     ldf(cur, 2, 0); SB_;
;     lw(ran, rbn, cur ^ 1);
;     gl(ran, rbn, (ks + 3 < nk) ? ks + 3 : nk - 1);
;     SB_;
;     mma(1); SB_;
;     __syncthreads();
;     ldf(cur, 3, 1); SB_;
;     mma(0); SB_;
;     ldf(cur ^ 1, 0, 0);
;     SB_;
;     mma(1); SB_;
;     __syncthreads();
;   };
	v_mfma_f32_16x16x32_bf16 v[0:3], v[80:83], v[64:67], v[0:3]
	v_mfma_f32_16x16x32_bf16 v[4:7], v[84:87], v[64:67], v[4:7]
	v_mfma_f32_16x16x32_bf16 v[8:11], v[88:91], v[64:67], v[8:11]
	v_mfma_f32_16x16x32_bf16 v[12:15], v[92:95], v[64:67], v[12:15]
	v_mfma_f32_16x16x32_bf16 v[16:19], v[80:83], v[68:71], v[16:19]
	v_mfma_f32_16x16x32_bf16 v[20:23], v[84:87], v[68:71], v[20:23]
	v_mfma_f32_16x16x32_bf16 v[24:27], v[88:91], v[68:71], v[24:27]
	v_mfma_f32_16x16x32_bf16 v[28:31], v[92:95], v[68:71], v[28:31]
	v_mfma_f32_16x16x32_bf16 v[32:35], v[80:83], v[72:75], v[32:35]
	v_mfma_f32_16x16x32_bf16 v[36:39], v[84:87], v[72:75], v[36:39]
	v_mfma_f32_16x16x32_bf16 v[40:43], v[88:91], v[72:75], v[40:43]
	v_mfma_f32_16x16x32_bf16 v[44:47], v[92:95], v[72:75], v[44:47]
	v_mfma_f32_16x16x32_bf16 v[48:51], v[80:83], v[76:79], v[48:51]
	v_mfma_f32_16x16x32_bf16 v[52:55], v[84:87], v[76:79], v[52:55]
	v_mfma_f32_16x16x32_bf16 v[56:59], v[88:91], v[76:79], v[56:59]
	v_mfma_f32_16x16x32_bf16 v[60:63], v[92:95], v[76:79], v[60:63]
	s_waitcnt lgkmcnt(0)
	v_mfma_f32_16x16x32_bf16 v[0:3], v[112:115], v[96:99], v[0:3]
	v_mfma_f32_16x16x32_bf16 v[4:7], v[116:119], v[96:99], v[4:7]
	v_mfma_f32_16x16x32_bf16 v[8:11], v[120:123], v[96:99], v[8:11]
	v_mfma_f32_16x16x32_bf16 v[12:15], v[124:127], v[96:99], v[12:15]
	v_mfma_f32_16x16x32_bf16 v[16:19], v[112:115], v[100:103], v[16:19]
	v_mfma_f32_16x16x32_bf16 v[20:23], v[116:119], v[100:103], v[20:23]
	v_mfma_f32_16x16x32_bf16 v[24:27], v[120:123], v[100:103], v[24:27]
	v_mfma_f32_16x16x32_bf16 v[28:31], v[124:127], v[100:103], v[28:31]
	v_mfma_f32_16x16x32_bf16 v[32:35], v[112:115], v[104:107], v[32:35]
	v_mfma_f32_16x16x32_bf16 v[36:39], v[116:119], v[104:107], v[36:39]
	v_mfma_f32_16x16x32_bf16 v[40:43], v[120:123], v[104:107], v[40:43]
	v_mfma_f32_16x16x32_bf16 v[44:47], v[124:127], v[104:107], v[44:47]
	v_mfma_f32_16x16x32_bf16 v[48:51], v[112:115], v[108:111], v[48:51]
	v_mfma_f32_16x16x32_bf16 v[52:55], v[116:119], v[108:111], v[52:55]
	v_mfma_f32_16x16x32_bf16 v[56:59], v[120:123], v[108:111], v[56:59]
	v_mfma_f32_16x16x32_bf16 v[60:63], v[124:127], v[108:111], v[60:63]
	s_add_i32 s5, s1, 2
	s_cmp_lt_u32 s1, 42
	s_mov_b32 s1, s5
	s_waitcnt vmcnt(0)
	s_barrier
	s_cbranch_scc1 .LBB0_1528
; DI float ssq_f(u64 v) { return (float)v * (1.f / 1048576.f); }
; DI void gemm_tile(const GemmDesc& d, int m0, int n0, bf16_t* smem, int dry) {
;     ...
;   u32x2 hpre[16];
;   if (d.epi == EPI_RESID) {
; #pragma unroll
;     for (int pass = 0; pass < 16; ++pass) {
;       int m = m0 + pass * 8 + (t >> 5); m = m < M ? m : M - 1;
;       hpre[pass] = *(const u32x2*)(d.hb + (size_t)m * D + d.c_off + n0 + (t & 31) * 4);
;     }
;   } else if (t < 128) {
;     rs_s[t] = rsqrtf(ssq_f(myss) * d.inv_dim + EPS);
;   }
;   if (half) {
; #pragma unroll
;     for (int a = 0; a < 2; ++a)
; #pragma unroll
;       for (int g = 0; g < 4; ++g) {
;         f32x4 o;
; #pragma unroll
;         for (int j = 0; j < 4; ++j) o[j] = acc[a][0][4 * g + j];
;         *(f32x4*)(Ct + (a * 32 + r) * CS + w * 32 + 8 * g + 4 * hh) = o;
;       }
;   } else {
; #pragma unroll
;     for (int a = 0; a < 2; ++a)
; #pragma unroll
;       for (int b = 0; b < 2; ++b)
; #pragma unroll
;         for (int g = 0; g < 4; ++g) {
;           f32x4 o;
; #pragma unroll
;           for (int j = 0; j < 4; ++j) o[j] = acc[a][b][4 * g + j];
;           *(f32x4*)(Ct + (wm * 64 + a * 32 + r) * CS + wn * 64 + b * 32 + 8 * g + 4 * hh) = o;
;         }
;   }
;   __syncthreads();
;   if (d.epi == EPI_RESID) {
; #pragma unroll
;     for (int pass = 0; pass < 16; ++pass) {
;       const int row = pass * 8 + (t >> 5), c4 = t & 31, m = m0 + row;
;       float part = 0.f;
;       if (m < M) {
;         const f32x4 v = *(const f32x4*)(Ct + row * CS + c4 * 4);
;         const int n = d.c_off + n0 + c4 * 4;
;         f32x4 hv;
;         hv[0] = __uint_as_float(hpre[pass][0] << 16); hv[1] = __uint_as_float(hpre[pass][0] & 0xffff0000u);
;         hv[2] = __uint_as_float(hpre[pass][1] << 16); hv[3] = __uint_as_float(hpre[pass][1] & 0xffff0000u);
; #pragma unroll
;         for (int j = 0; j < 4; ++j) { hv[j] += v[j]; part += hv[j] * hv[j]; }
;         u32x2 o; o[0] = pk_bf16(hv[0], hv[1]); o[1] = pk_bf16(hv[2], hv[3]);
;         *(u32x2*)(d.hb + (size_t)m * D + n) = o;
	s_waitcnt vmcnt(7)
	v_ashrrev_i32_e32 v98, 5, v150
	v_add_u32_e32 v92, s13, v98
	s_ashr_i32 s5, s4, 31
	s_lshl_b64 s[10:11], s[4:5], 1
	v_add_u32_e32 v70, 16, v92
	v_add_u32_e32 v72, 24, v92
	s_add_u32 s10, s56, s10
	v_lshlrev_b32_e32 v64, 3, v150
	v_min_i32_e32 v66, 0x803f, v92
	v_add_u32_e32 v68, 8, v92
	v_min_i32_e32 v70, 0x803f, v70
	v_min_i32_e32 v72, 0x803f, v72
	s_addc_u32 s11, s57, s11
	v_and_b32_e32 v144, 0xf8, v64
	v_ashrrev_i32_e32 v67, 31, v66
	v_min_i32_e32 v68, 0x803f, v68
	v_ashrrev_i32_e32 v71, 31, v70
	v_ashrrev_i32_e32 v73, 31, v72
	v_lshl_add_u64 v[64:65], s[10:11], 0, v[144:145]
	v_lshlrev_b64 v[66:67], 11, v[66:67]
	v_ashrrev_i32_e32 v69, 31, v68
	v_lshlrev_b64 v[70:71], 11, v[70:71]
	v_lshlrev_b64 v[72:73], 11, v[72:73]
	v_lshl_add_u64 v[66:67], v[64:65], 0, v[66:67]
	v_lshlrev_b64 v[68:69], 11, v[68:69]
	v_lshl_add_u64 v[70:71], v[64:65], 0, v[70:71]
	v_lshl_add_u64 v[72:73], v[64:65], 0, v[72:73]
	v_lshl_add_u64 v[68:69], v[64:65], 0, v[68:69]
	global_load_dwordx2 v[96:97], v[66:67], off
	global_load_dwordx2 v[94:95], v[68:69], off
	global_load_dwordx2 v[90:91], v[70:71], off
	global_load_dwordx2 v[88:89], v[72:73], off
	v_add_u32_e32 v66, 32, v92
	v_add_u32_e32 v70, 48, v92
	v_add_u32_e32 v72, 56, v92
	v_min_i32_e32 v66, 0x803f, v66
	v_add_u32_e32 v68, 40, v92
	v_min_i32_e32 v70, 0x803f, v70
	v_min_i32_e32 v72, 0x803f, v72
	v_ashrrev_i32_e32 v67, 31, v66
	v_min_i32_e32 v68, 0x803f, v68
	v_ashrrev_i32_e32 v71, 31, v70
	v_ashrrev_i32_e32 v73, 31, v72
	v_lshlrev_b64 v[66:67], 11, v[66:67]
	v_ashrrev_i32_e32 v69, 31, v68
	v_lshlrev_b64 v[70:71], 11, v[70:71]
	v_lshlrev_b64 v[72:73], 11, v[72:73]
	v_lshl_add_u64 v[66:67], v[64:65], 0, v[66:67]
	v_lshlrev_b64 v[68:69], 11, v[68:69]
	v_lshl_add_u64 v[70:71], v[64:65], 0, v[70:71]
	v_lshl_add_u64 v[72:73], v[64:65], 0, v[72:73]
	v_lshl_add_u64 v[68:69], v[64:65], 0, v[68:69]
	global_load_dwordx2 v[86:87], v[66:67], off
	global_load_dwordx2 v[84:85], v[68:69], off
	global_load_dwordx2 v[82:83], v[70:71], off
	global_load_dwordx2 v[80:81], v[72:73], off
	v_add_u32_e32 v66, 64, v92
	v_add_u32_e32 v70, 0x50, v92
	v_add_u32_e32 v72, 0x58, v92
	v_min_i32_e32 v66, 0x803f, v66
	v_add_u32_e32 v68, 0x48, v92
	v_min_i32_e32 v70, 0x803f, v70
	v_min_i32_e32 v72, 0x803f, v72
	v_ashrrev_i32_e32 v67, 31, v66
	v_min_i32_e32 v68, 0x803f, v68
	v_ashrrev_i32_e32 v71, 31, v70
	v_ashrrev_i32_e32 v73, 31, v72
	v_lshlrev_b64 v[66:67], 11, v[66:67]
	v_ashrrev_i32_e32 v69, 31, v68
	v_lshlrev_b64 v[70:71], 11, v[70:71]
	v_lshlrev_b64 v[72:73], 11, v[72:73]
	v_lshl_add_u64 v[66:67], v[64:65], 0, v[66:67]
	v_lshlrev_b64 v[68:69], 11, v[68:69]
	v_lshl_add_u64 v[70:71], v[64:65], 0, v[70:71]
	v_lshl_add_u64 v[72:73], v[64:65], 0, v[72:73]
	v_lshl_add_u64 v[68:69], v[64:65], 0, v[68:69]
	global_load_dwordx2 v[78:79], v[66:67], off
	global_load_dwordx2 v[76:77], v[68:69], off
	global_load_dwordx2 v[74:75], v[70:71], off
	s_nop 0
	global_load_dwordx2 v[72:73], v[72:73], off
	v_add_u32_e32 v70, 0x70, v92
	v_min_i32_e32 v70, 0x803f, v70
	v_ashrrev_i32_e32 v71, 31, v70
	v_lshlrev_b64 v[70:71], 11, v[70:71]
	v_add_u32_e32 v66, 0x60, v92
	v_add_u32_e32 v68, 0x68, v92
	s_waitcnt vmcnt(18)
	v_lshl_add_u64 v[100:101], v[64:65], 0, v[70:71]
	v_add_u32_e32 v70, 0x78, v92
	v_min_i32_e32 v66, 0x803f, v66
	v_min_i32_e32 v68, 0x803f, v68
	v_min_i32_e32 v70, 0x803f, v70
	v_ashrrev_i32_e32 v67, 31, v66
	v_ashrrev_i32_e32 v69, 31, v68
	v_ashrrev_i32_e32 v71, 31, v70
	v_lshlrev_b64 v[66:67], 11, v[66:67]
	v_lshlrev_b64 v[68:69], 11, v[68:69]
	v_lshlrev_b64 v[70:71], 11, v[70:71]
	v_lshl_add_u64 v[66:67], v[64:65], 0, v[66:67]
	v_lshl_add_u64 v[68:69], v[64:65], 0, v[68:69]
	v_lshl_add_u64 v[64:65], v[64:65], 0, v[70:71]
	global_load_dwordx2 v[70:71], v[66:67], off
	s_nop 0
	global_load_dwordx2 v[68:69], v[68:69], off
	s_nop 0
	global_load_dwordx2 v[66:67], v[100:101], off
	s_nop 0
	global_load_dwordx2 v[64:65], v[64:65], off
	v_and_b32_e32 v99, 31, v150
	v_lshrrev_b32_e32 v100, 1, v150
	v_lshlrev_b32_e32 v93, 2, v150
	v_and_or_b32 v101, v100, s72, v99
	v_and_b32_e32 v100, 16, v100
	s_movk_i32 s1, 0x100
	v_and_or_b32 v100, v93, s1, v100
	v_mad_u64_u32 v[100:101], s[10:11], v101, s22, v[100:101]
	v_and_b32_e32 v204, 15, v172
	v_lshrrev_b32_e32 v205, 1, v172
	v_and_or_b32 v204, v205, s72, v204
	v_lshlrev_b32_e32 v205, 2, v172
	v_and_b32_e32 v206, 0x30, v172
	v_and_b32_e32 v205, 0x100, v205
	v_or_b32_e32 v205, v205, v206
	v_mad_u32_u24 v100, v204, s22, v205
	ds_write_b128 v100, v[0:3]
	ds_write_b128 v100, v[4:7] offset:64
	ds_write_b128 v100, v[8:11] offset:128
	ds_write_b128 v100, v[12:15] offset:192
	ds_write_b128 v100, v[16:19] offset:8448
	ds_write_b128 v100, v[20:23] offset:8512
	ds_write_b128 v100, v[24:27] offset:8576
	ds_write_b128 v100, v[28:31] offset:8640
	ds_write_b128 v100, v[32:35] offset:16896
	ds_write_b128 v100, v[36:39] offset:16960
	ds_write_b128 v100, v[40:43] offset:17024
	ds_write_b128 v100, v[44:47] offset:17088
	ds_write_b128 v100, v[48:51] offset:25344
	ds_write_b128 v100, v[52:55] offset:25408
	ds_write_b128 v100, v[56:59] offset:25472
	ds_write_b128 v100, v[60:63] offset:25536
	v_lshl_or_b32 v0, v99, 2, s4
	v_lshlrev_b32_e32 v2, 4, v99
	v_cmp_gt_i32_e64 s[4:5], s23, v92
	v_mov_b32_e32 v4, 0
	v_ashrrev_i32_e32 v93, 31, v92
	v_ashrrev_i32_e32 v1, 31, v0
	s_waitcnt lgkmcnt(0)
	s_barrier
	s_and_saveexec_b64 s[10:11], s[4:5]
	s_cbranch_execz .LBB0_1531
	v_mad_u64_u32 v[4:5], s[14:15], v98, s22, v[2:3]
	ds_read_b128 v[4:7], v4
	s_waitcnt vmcnt(15)
	v_lshlrev_b32_e32 v8, 16, v96
	v_and_b32_e32 v9, 0xffff0000, v96
	v_and_b32_e32 v11, 0xffff0000, v97
	v_lshlrev_b32_e32 v10, 16, v97
	s_waitcnt lgkmcnt(0)
	v_pk_add_f32 v[8:9], v[4:5], v[8:9]
	v_pk_add_f32 v[6:7], v[6:7], v[10:11]
	v_pk_mul_f32 v[4:5], v[8:9], v[8:9]
	v_pk_mul_f32 v[10:11], v[6:7], v[6:7]
	v_add_f32_e32 v3, v4, v5
	v_cvt_pk_bf16_f32 v8, v8, v9
	v_cvt_pk_bf16_f32 v9, v6, v7
	v_lshlrev_b64 v[6:7], 11, v[92:93]
	v_add_f32_e32 v3, v10, v3
	v_lshl_add_u64 v[6:7], s[56:57], 0, v[6:7]
	v_add_f32_e32 v4, v11, v3
	v_lshl_add_u64 v[6:7], v[0:1], 1, v[6:7]
	global_store_dwordx2 v[6:7], v[8:9], off

; __global__ void __launch_bounds__(NTHREADS, 2) fwd_kernel(Params p, int ph_begin, int ph_end) {
;   __shared__ __attribute__((aligned(16))) unsigned char smem_raw[SMEM_BYTES];
	.amdhsa_kernel _Z10fwd_kernel6Paramsii
		.amdhsa_group_segment_fixed_size 73744
		.amdhsa_private_segment_fixed_size 0
		.amdhsa_kernarg_size 2824
		.amdhsa_user_sgpr_count 2
		.amdhsa_user_sgpr_dispatch_ptr 0
		.amdhsa_user_sgpr_queue_ptr 0
		.amdhsa_user_sgpr_kernarg_segment_ptr 1
		.amdhsa_user_sgpr_dispatch_id 0
		.amdhsa_user_sgpr_kernarg_preload_length 0
		.amdhsa_user_sgpr_kernarg_preload_offset 0
		.amdhsa_user_sgpr_private_segment_size 0
		.amdhsa_uses_dynamic_stack 0
		.amdhsa_enable_private_segment 0
		.amdhsa_system_sgpr_workgroup_id_x 1
		.amdhsa_system_sgpr_workgroup_id_y 0
		.amdhsa_system_sgpr_workgroup_id_z 0
		.amdhsa_system_sgpr_workgroup_info 0
		.amdhsa_system_vgpr_workitem_id 2
		.amdhsa_next_free_vgpr 232
		.amdhsa_next_free_sgpr 102
		.amdhsa_accum_offset 232
		.amdhsa_reserve_vcc 1
		.amdhsa_float_round_mode_32 0
		.amdhsa_float_round_mode_16_64 0
		.amdhsa_float_denorm_mode_32 3
		.amdhsa_float_denorm_mode_16_64 3
		.amdhsa_dx10_clamp 1
		.amdhsa_ieee_mode 1
		.amdhsa_fp16_overflow 0
		.amdhsa_tg_split 0
		.amdhsa_exception_fp_ieee_invalid_op 0
		.amdhsa_exception_fp_denorm_src 0
		.amdhsa_exception_fp_ieee_div_zero 0
		.amdhsa_exception_fp_ieee_overflow 0
		.amdhsa_exception_fp_ieee_underflow 0
		.amdhsa_exception_fp_ieee_inexact 0
		.amdhsa_exception_int_div_zero 0
	.end_amdhsa_kernel

; __global__ void __launch_bounds__(NTHREADS, 2) fwd_kernel(Params p, int ph_begin, int ph_end) {
;   __shared__ __attribute__((aligned(16))) unsigned char smem_raw[SMEM_BYTES];
amdhsa.kernels:
  - .agpr_count:     0
    .args:
      - .offset:         0
        .size:           2560
        .value_kind:     by_value
      - .offset:         2560
        .size:           4
        .value_kind:     by_value
      - .offset:         2564
        .size:           4
        .value_kind:     by_value
      - .offset:         2568
        .size:           4
        .value_kind:     hidden_block_count_x
      - .offset:         2572
        .size:           4
        .value_kind:     hidden_block_count_y
      - .offset:         2576
        .size:           4
        .value_kind:     hidden_block_count_z
      - .offset:         2580
        .size:           2
        .value_kind:     hidden_group_size_x
      - .offset:         2582
        .size:           2
        .value_kind:     hidden_group_size_y
      - .offset:         2584
        .size:           2
        .value_kind:     hidden_group_size_z
      - .offset:         2586
        .size:           2
        .value_kind:     hidden_remainder_x
      - .offset:         2588
        .size:           2
        .value_kind:     hidden_remainder_y
      - .offset:         2590
        .size:           2
        .value_kind:     hidden_remainder_z
      - .offset:         2608
        .size:           8
        .value_kind:     hidden_global_offset_x
      - .offset:         2616
        .size:           8
        .value_kind:     hidden_global_offset_y
      - .offset:         2624
        .size:           8
        .value_kind:     hidden_global_offset_z
      - .offset:         2632
        .size:           2
        .value_kind:     hidden_grid_dims
      - .offset:         2656
        .size:           8
        .value_kind:     hidden_multigrid_sync_arg
    .group_segment_fixed_size: 73744
    .kernarg_segment_align: 8
    .kernarg_segment_size: 2824
    .language:       OpenCL C
    .language_version:
      - 2
      - 0
    .max_flat_workgroup_size: 256
    .name:           _Z10fwd_kernel6Paramsii
    .private_segment_fixed_size: 0
    .sgpr_count:     108
    .sgpr_spill_count: 163
    .symbol:         _Z10fwd_kernel6Paramsii.kd
    .uniform_work_group_size: 1
    .uses_dynamic_stack: false
    .vgpr_count:     232
    .vgpr_spill_count: 0
    .wavefront_size: 64
